# first K-iteration of every GEMM main loop peeled: first-write MFMAs use srcC=0, per-unit accumulator zeroing removed
# speedup vs baseline: 1.0273x; 1.0058x over previous
; #define PG8_STAGE(bufoff, gbase, voff) do { _Pragma("unroll") for (int _i = 0; _i < 2; ++_i) \
;         __builtin_amdgcn_global_load_lds((const unsigned*)((const char*)(gbase) + (voff)[_i]), (LAS unsigned*)(lds + (bufoff) + ldsw + _i * 8192), 16, 0, 0); } while (0)
; #define PG8_LDA(dst, b, h) do { _Pragma("unroll") for (int m = 0; m < 4; ++m) _Pragma("unroll") for (int k = 0; k < 2; ++k) dst[m][k] = *(const LAS bf16x8*)(lds + PG8_SA(b, h) + aoff + m * 2048 + k * 1024); } while (0)
; #define PG8_LDB(dst, b, h) do { _Pragma("unroll") for (int n = 0; n < 2; ++n) _Pragma("unroll") for (int k = 0; k < 2; ++k) dst[n][k] = *(const LAS bf16x8*)(lds + PG8_SB(b, h) + boff + n * 2048 + k * 1024); } while (0)
; #define PG8_WAIT_V(n) asm volatile("s_waitcnt vmcnt(" #n ")" ::: "memory")
; #define PG8_WAIT_L(n) asm volatile("s_waitcnt lgkmcnt(" #n ")" ::: "memory")
; #define PG8_BAR __builtin_amdgcn_s_barrier()
; #define PG8_SCHED __builtin_amdgcn_sched_barrier(0)
;     ...
;         for (int t = 0; t < nt; t += 2) {
;             const bool last = (t == nt - 2);
;             const char* a1 = cA + (size_t)(t + 1) * kstep;
;             const char* a2 = last ? nA : cA + (size_t)(t + 2) * kstep; const char* b2 = last ? nB : cB + (size_t)(t + 2) * kstep;
;             const char* a3 = a2 + kstep; const char* b3 = b2 + kstep;
;             PG8_LDB(B0, 0, 0); PG8_LDB(B1, 0, 1); PG8_SCHED; PG8_LDA(At, 0, 0); PG8_STAGE(PG8_SA(1, 1), a1 + hstep, voffA);
;             PG8_WAIT_V(8); PG8_WAIT_L(0); PG8_BAR; PG8_MMA(0, 0, At, B0); PG8_MMA(0, 1, At, B1); PG8_BAR; PG8_SCHED;
;             PG8_LDA(At, 0, 1); PG8_STAGE(PG8_SB(0, 0), b2, voffB); PG8_STAGE(PG8_SB(0, 1), b2 + hstep, voffB); PG8_STAGE(PG8_SA(0, 0), a2, voffA);
;             PG8_WAIT_V(8); PG8_WAIT_L(0); PG8_BAR; PG8_MMA(1, 0, At, B0); PG8_MMA(1, 1, At, B1); PG8_BAR; PG8_SCHED;
;     ...
; #pragma unroll
;         for (int a = 0; a < 2; ++a)
; #pragma unroll
;             for (int b = 0; b < 2; ++b)
; #pragma unroll
;                 for (int m = 0; m < 4; ++m)
; #pragma unroll
;                     for (int n = 0; n < 2; ++n) acc[a][b][m][n] = (f32x4){0.f, 0.f, 0.f, 0.f};
.LBB0_1083:
	s_ashr_i32 s21, s20, 31
	s_lshl_b64 s[24:25], s[20:21], 19
	s_add_u32 s24, s23, s24
	s_addc_u32 s25, s34, s25
	s_and_b64 s[26:27], s[4:5], exec
	s_cselect_b32 s7, s25, s29
	s_cselect_b32 s9, s24, s28
	s_ashr_i32 s19, s18, 31
	s_lshl_b64 s[26:27], s[18:19], 19
	s_add_u32 s26, s35, s26
	s_addc_u32 s27, s38, s27
	s_and_b64 s[36:37], s[4:5], exec
	s_cselect_b32 s19, s27, s31
	s_cselect_b32 s21, s26, s30
	s_add_u32 s28, s28, 0x40080
	s_addc_u32 s29, s29, 0
	s_add_u32 s58, s30, 0x100
	s_addc_u32 s59, s31, 0
	s_mov_b32 s60, -2
	s_waitcnt lgkmcnt(0)
	ds_read_b128 v[128:131], v166
	ds_read_b128 v[132:135], v166 offset:1024
	ds_read_b128 v[158:161], v166 offset:2048
	ds_read_b128 v[172:175], v166 offset:3072
	ds_read_b128 v[176:179], v167
	ds_read_b128 v[180:183], v167 offset:1024
	ds_read_b128 v[184:187], v167 offset:2048
	ds_read_b128 v[188:191], v167 offset:3072
	s_add_u32 s30, s28, 0xfffc0080
	s_addc_u32 s31, s29, -1
	s_cmp_eq_u32 s60, 12
	s_cselect_b32 s37, s7, s31
	s_cselect_b32 s36, s9, s30
	s_cselect_b32 s31, s19, s59
	s_cselect_b32 s30, s21, s58
	v_lshl_add_u64 v[162:163], s[28:29], 0, v[150:151]
	s_add_i32 m0, s42, 0xc000
	ds_read_b128 v[192:195], v168
	ds_read_b128 v[196:199], v168 offset:1024
	ds_read_b128 v[200:203], v168 offset:2048
	ds_read_b128 v[204:207], v168 offset:3072
	ds_read_b128 v[208:211], v168 offset:4096
	ds_read_b128 v[212:215], v168 offset:5120
	ds_read_b128 v[216:219], v168 offset:6144
	ds_read_b128 v[220:223], v168 offset:7168
	global_load_lds_dwordx4 v[162:163], off
	v_lshl_add_u64 v[162:163], s[28:29], 0, v[152:153]
	s_add_i32 m0, s42, 0xe000
	s_nop 0
	global_load_lds_dwordx4 v[162:163], off
	s_waitcnt vmcnt(8)
	s_waitcnt lgkmcnt(0)
	s_barrier
	s_setprio 1
	s_waitcnt lgkmcnt(0)
	v_mfma_i32_16x16x64_i8 v[124:127], v[128:131], v[192:195], 0
	v_mfma_i32_16x16x64_i8 v[120:123], v[158:161], v[192:195], 0
	v_mfma_i32_16x16x64_i8 v[108:111], v[128:131], v[200:203], 0
	v_mfma_i32_16x16x64_i8 v[104:107], v[158:161], v[200:203], 0
	v_mfma_i32_16x16x64_i8 v[92:95], v[128:131], v[208:211], 0
	v_mfma_i32_16x16x64_i8 v[88:91], v[158:161], v[208:211], 0
	v_mfma_i32_16x16x64_i8 v[76:79], v[128:131], v[216:219], 0
	v_mfma_i32_16x16x64_i8 v[72:75], v[158:161], v[216:219], 0
	v_mfma_i32_16x16x64_i8 v[124:127], v[132:135], v[196:199], v[124:127]
	v_mfma_i32_16x16x64_i8 v[120:123], v[172:175], v[196:199], v[120:123]
	v_mfma_i32_16x16x64_i8 v[108:111], v[132:135], v[204:207], v[108:111]
	v_mfma_i32_16x16x64_i8 v[104:107], v[172:175], v[204:207], v[104:107]
	v_mfma_i32_16x16x64_i8 v[92:95], v[132:135], v[212:215], v[92:95]
	v_mfma_i32_16x16x64_i8 v[88:91], v[172:175], v[212:215], v[88:91]
	v_mfma_i32_16x16x64_i8 v[76:79], v[132:135], v[220:223], v[76:79]
	v_mfma_i32_16x16x64_i8 v[72:75], v[172:175], v[220:223], v[72:75]
	s_setprio 0
	s_setprio 1
	v_mfma_i32_16x16x64_i8 v[116:119], v[176:179], v[192:195], 0
	v_mfma_i32_16x16x64_i8 v[112:115], v[184:187], v[192:195], 0
	v_mfma_i32_16x16x64_i8 v[100:103], v[176:179], v[200:203], 0
	v_mfma_i32_16x16x64_i8 v[96:99], v[184:187], v[200:203], 0
	v_mfma_i32_16x16x64_i8 v[84:87], v[176:179], v[208:211], 0
	v_mfma_i32_16x16x64_i8 v[80:83], v[184:187], v[208:211], 0
	v_mfma_i32_16x16x64_i8 v[68:71], v[176:179], v[216:219], 0
	v_mfma_i32_16x16x64_i8 v[64:67], v[184:187], v[216:219], 0
	v_mfma_i32_16x16x64_i8 v[116:119], v[180:183], v[196:199], v[116:119]
	v_mfma_i32_16x16x64_i8 v[112:115], v[188:191], v[196:199], v[112:115]
	v_mfma_i32_16x16x64_i8 v[100:103], v[180:183], v[204:207], v[100:103]
	v_mfma_i32_16x16x64_i8 v[96:99], v[188:191], v[204:207], v[96:99]
	v_mfma_i32_16x16x64_i8 v[84:87], v[180:183], v[212:215], v[84:87]
	v_mfma_i32_16x16x64_i8 v[80:83], v[188:191], v[212:215], v[80:83]
	v_mfma_i32_16x16x64_i8 v[68:71], v[180:183], v[220:223], v[68:71]
	v_mfma_i32_16x16x64_i8 v[64:67], v[188:191], v[220:223], v[64:67]
	s_setprio 0
	s_barrier
	s_add_i32 s61, s54, s39
	v_lshl_add_u64 v[162:163], s[30:31], 0, v[138:139]
	s_mov_b32 m0, s61
	ds_read_b128 v[192:195], v168 offset:16384
	ds_read_b128 v[196:199], v168 offset:17408
	ds_read_b128 v[200:203], v168 offset:18432
	ds_read_b128 v[204:207], v168 offset:19456
	ds_read_b128 v[208:211], v168 offset:20480
	ds_read_b128 v[212:215], v168 offset:21504
	ds_read_b128 v[216:219], v168 offset:22528
	ds_read_b128 v[220:223], v168 offset:23552
	global_load_lds_dwordx4 v[162:163], off
	s_add_i32 m0, s61, 0x2000
	s_add_u32 s62, s30, 0x40000
	v_lshl_add_u64 v[224:225], s[30:31], 0, v[142:143]
	s_addc_u32 s63, s31, 0
	s_add_i32 s61, s55, s39
	global_load_lds_dwordx4 v[224:225], off
	v_lshl_add_u64 v[226:227], s[62:63], 0, v[138:139]
	s_mov_b32 m0, s61
	v_lshl_add_u64 v[228:229], s[36:37], 0, v[140:141]
	global_load_lds_dwordx4 v[226:227], off
	v_lshl_add_u64 v[226:227], s[62:63], 0, v[142:143]
	s_add_i32 m0, s61, 0x2000
	s_nop 0
	global_load_lds_dwordx4 v[226:227], off
	v_lshl_add_u64 v[226:227], s[36:37], 0, v[136:137]
	s_mov_b32 m0, s42
	s_nop 0
	global_load_lds_dwordx4 v[226:227], off
	s_mov_b32 m0, s43
	s_nop 0
	global_load_lds_dwordx4 v[228:229], off
	s_waitcnt vmcnt(8)
	s_waitcnt lgkmcnt(0)
	s_barrier
; #define PG8_STAGE(bufoff, gbase, voff) do { _Pragma("unroll") for (int _i = 0; _i < 2; ++_i) \
;         __builtin_amdgcn_global_load_lds((const unsigned*)((const char*)(gbase) + (voff)[_i]), (LAS unsigned*)(lds + (bufoff) + ldsw + _i * 8192), 16, 0, 0); } while (0)
; #define PG8_LDA(dst, b, h) do { _Pragma("unroll") for (int m = 0; m < 4; ++m) _Pragma("unroll") for (int k = 0; k < 2; ++k) dst[m][k] = *(const LAS bf16x8*)(lds + PG8_SA(b, h) + aoff + m * 2048 + k * 1024); } while (0)
; #define PG8_LDB(dst, b, h) do { _Pragma("unroll") for (int n = 0; n < 2; ++n) _Pragma("unroll") for (int k = 0; k < 2; ++k) dst[n][k] = *(const LAS bf16x8*)(lds + PG8_SB(b, h) + boff + n * 2048 + k * 1024); } while (0)
; #define PG8_WAIT_V(n) asm volatile("s_waitcnt vmcnt(" #n ")" ::: "memory")
; #define PG8_WAIT_L(n) asm volatile("s_waitcnt lgkmcnt(" #n ")" ::: "memory")
; #define PG8_BAR __builtin_amdgcn_s_barrier()
; #define PG8_SCHED __builtin_amdgcn_sched_barrier(0)
;     ...
;             PG8_WAIT_V(8); PG8_WAIT_L(0); PG8_BAR; PG8_MMA(1, 0, At, B0); PG8_MMA(1, 1, At, B1); PG8_BAR; PG8_SCHED;
;             PG8_LDB(B0, 1, 0); PG8_LDB(B1, 1, 1); PG8_SCHED; PG8_LDA(At, 1, 0); PG8_STAGE(PG8_SA(0, 1), a2 + hstep, voffA);
;             PG8_WAIT_V(8); PG8_WAIT_L(0); PG8_BAR; PG8_MMA(0, 0, At, B0); PG8_MMA(0, 1, At, B1); PG8_BAR; PG8_SCHED;
;             PG8_LDA(At, 1, 1); PG8_STAGE(PG8_SB(1, 0), b3, voffB); PG8_STAGE(PG8_SB(1, 1), b3 + hstep, voffB); PG8_STAGE(PG8_SA(1, 0), a3, voffA);
;             PG8_WAIT_V(8); PG8_WAIT_L(0); PG8_BAR; PG8_MMA(1, 0, At, B0); PG8_MMA(1, 1, At, B1); PG8_BAR; PG8_SCHED;
	s_setprio 1
	s_waitcnt lgkmcnt(0)
	v_mfma_i32_16x16x64_i8 v[60:63], v[128:131], v[192:195], 0
	v_mfma_i32_16x16x64_i8 v[56:59], v[158:161], v[192:195], 0
	v_mfma_i32_16x16x64_i8 v[44:47], v[128:131], v[200:203], 0
	v_mfma_i32_16x16x64_i8 v[40:43], v[158:161], v[200:203], 0
	v_mfma_i32_16x16x64_i8 v[28:31], v[128:131], v[208:211], 0
	v_mfma_i32_16x16x64_i8 v[24:27], v[158:161], v[208:211], 0
	v_mfma_i32_16x16x64_i8 v[12:15], v[128:131], v[216:219], 0
	v_mfma_i32_16x16x64_i8 v[8:11], v[158:161], v[216:219], 0
	v_mfma_i32_16x16x64_i8 v[60:63], v[132:135], v[196:199], v[60:63]
	v_mfma_i32_16x16x64_i8 v[56:59], v[172:175], v[196:199], v[56:59]
	v_mfma_i32_16x16x64_i8 v[44:47], v[132:135], v[204:207], v[44:47]
	v_mfma_i32_16x16x64_i8 v[40:43], v[172:175], v[204:207], v[40:43]
	v_mfma_i32_16x16x64_i8 v[28:31], v[132:135], v[212:215], v[28:31]
	v_mfma_i32_16x16x64_i8 v[24:27], v[172:175], v[212:215], v[24:27]
	v_mfma_i32_16x16x64_i8 v[12:15], v[132:135], v[220:223], v[12:15]
	v_mfma_i32_16x16x64_i8 v[8:11], v[172:175], v[220:223], v[8:11]
	s_setprio 0
	s_setprio 1
	v_mfma_i32_16x16x64_i8 v[52:55], v[176:179], v[192:195], 0
	v_mfma_i32_16x16x64_i8 v[48:51], v[184:187], v[192:195], 0
	v_mfma_i32_16x16x64_i8 v[36:39], v[176:179], v[200:203], 0
	v_mfma_i32_16x16x64_i8 v[32:35], v[184:187], v[200:203], 0
	v_mfma_i32_16x16x64_i8 v[20:23], v[176:179], v[208:211], 0
	v_mfma_i32_16x16x64_i8 v[16:19], v[184:187], v[208:211], 0
	v_mfma_i32_16x16x64_i8 v[4:7], v[176:179], v[216:219], 0
	v_mfma_i32_16x16x64_i8 v[0:3], v[184:187], v[216:219], 0
	v_mfma_i32_16x16x64_i8 v[52:55], v[180:183], v[196:199], v[52:55]
	v_mfma_i32_16x16x64_i8 v[48:51], v[188:191], v[196:199], v[48:51]
	v_mfma_i32_16x16x64_i8 v[36:39], v[180:183], v[204:207], v[36:39]
	v_mfma_i32_16x16x64_i8 v[32:35], v[188:191], v[204:207], v[32:35]
	v_mfma_i32_16x16x64_i8 v[20:23], v[180:183], v[212:215], v[20:23]
	v_mfma_i32_16x16x64_i8 v[16:19], v[188:191], v[212:215], v[16:19]
	v_mfma_i32_16x16x64_i8 v[4:7], v[180:183], v[220:223], v[4:7]
	v_mfma_i32_16x16x64_i8 v[0:3], v[188:191], v[220:223], v[0:3]
	s_setprio 0
	s_barrier
	s_add_i32 s61, 0, 0x18000
	s_add_i32 s62, 0, 0x1c000
	v_add_u32_e32 v172, s61, v165
	v_add_u32_e32 v188, s62, v165
	ds_read_b128 v[128:131], v172
	ds_read_b128 v[132:135], v172 offset:1024
	ds_read_b128 v[158:161], v172 offset:2048
	ds_read_b128 v[172:175], v172 offset:3072
	ds_read_b128 v[176:179], v188
	ds_read_b128 v[180:183], v188 offset:1024
	ds_read_b128 v[184:187], v188 offset:2048
	ds_read_b128 v[188:191], v188 offset:3072
	s_add_u32 s36, s36, 0x40000
	s_addc_u32 s37, s37, 0
	s_mov_b32 m0, s44
	v_lshl_add_u64 v[230:231], s[36:37], 0, v[136:137]
	ds_read_b128 v[192:195], v168 offset:32768
	ds_read_b128 v[196:199], v168 offset:33792
	ds_read_b128 v[200:203], v168 offset:34816
	ds_read_b128 v[204:207], v168 offset:35840
	ds_read_b128 v[208:211], v168 offset:36864
	ds_read_b128 v[212:215], v168 offset:37888
	ds_read_b128 v[216:219], v168 offset:38912
	ds_read_b128 v[220:223], v168 offset:39936
	global_load_lds_dwordx4 v[230:231], off
	v_lshl_add_u64 v[230:231], s[36:37], 0, v[140:141]
	s_mov_b32 m0, s45
	s_nop 0
	global_load_lds_dwordx4 v[230:231], off
	s_waitcnt vmcnt(8)
	s_waitcnt lgkmcnt(0)
	s_barrier
	s_setprio 1
	s_waitcnt lgkmcnt(0)
	v_mfma_i32_16x16x64_i8 v[124:127], v[128:131], v[192:195], v[124:127]
	v_mfma_i32_16x16x64_i8 v[120:123], v[158:161], v[192:195], v[120:123]
	v_mfma_i32_16x16x64_i8 v[108:111], v[128:131], v[200:203], v[108:111]
	v_mfma_i32_16x16x64_i8 v[104:107], v[158:161], v[200:203], v[104:107]
	v_mfma_i32_16x16x64_i8 v[92:95], v[128:131], v[208:211], v[92:95]
	v_mfma_i32_16x16x64_i8 v[88:91], v[158:161], v[208:211], v[88:91]
	v_mfma_i32_16x16x64_i8 v[76:79], v[128:131], v[216:219], v[76:79]
	v_mfma_i32_16x16x64_i8 v[72:75], v[158:161], v[216:219], v[72:75]
	v_mfma_i32_16x16x64_i8 v[124:127], v[132:135], v[196:199], v[124:127]
	v_mfma_i32_16x16x64_i8 v[120:123], v[172:175], v[196:199], v[120:123]
	v_mfma_i32_16x16x64_i8 v[108:111], v[132:135], v[204:207], v[108:111]
	v_mfma_i32_16x16x64_i8 v[104:107], v[172:175], v[204:207], v[104:107]
	v_mfma_i32_16x16x64_i8 v[92:95], v[132:135], v[212:215], v[92:95]
	v_mfma_i32_16x16x64_i8 v[88:91], v[172:175], v[212:215], v[88:91]
	v_mfma_i32_16x16x64_i8 v[76:79], v[132:135], v[220:223], v[76:79]
	v_mfma_i32_16x16x64_i8 v[72:75], v[172:175], v[220:223], v[72:75]
	s_setprio 0
	s_setprio 1
	v_mfma_i32_16x16x64_i8 v[116:119], v[176:179], v[192:195], v[116:119]
	v_mfma_i32_16x16x64_i8 v[112:115], v[184:187], v[192:195], v[112:115]
	v_mfma_i32_16x16x64_i8 v[100:103], v[176:179], v[200:203], v[100:103]
	v_mfma_i32_16x16x64_i8 v[96:99], v[184:187], v[200:203], v[96:99]
	v_mfma_i32_16x16x64_i8 v[84:87], v[176:179], v[208:211], v[84:87]
	v_mfma_i32_16x16x64_i8 v[80:83], v[184:187], v[208:211], v[80:83]
	v_mfma_i32_16x16x64_i8 v[68:71], v[176:179], v[216:219], v[68:71]
	v_mfma_i32_16x16x64_i8 v[64:67], v[184:187], v[216:219], v[64:67]
	v_mfma_i32_16x16x64_i8 v[116:119], v[180:183], v[196:199], v[116:119]
	v_mfma_i32_16x16x64_i8 v[112:115], v[188:191], v[196:199], v[112:115]
	v_mfma_i32_16x16x64_i8 v[100:103], v[180:183], v[204:207], v[100:103]
	v_mfma_i32_16x16x64_i8 v[96:99], v[188:191], v[204:207], v[96:99]
	v_mfma_i32_16x16x64_i8 v[84:87], v[180:183], v[212:215], v[84:87]
	v_mfma_i32_16x16x64_i8 v[80:83], v[188:191], v[212:215], v[80:83]
	v_mfma_i32_16x16x64_i8 v[68:71], v[180:183], v[220:223], v[68:71]
	v_mfma_i32_16x16x64_i8 v[64:67], v[188:191], v[220:223], v[64:67]
	s_setprio 0
	s_barrier
; #define PG8_STAGE(bufoff, gbase, voff) do { _Pragma("unroll") for (int _i = 0; _i < 2; ++_i) \
;         __builtin_amdgcn_global_load_lds((const unsigned*)((const char*)(gbase) + (voff)[_i]), (LAS unsigned*)(lds + (bufoff) + ldsw + _i * 8192), 16, 0, 0); } while (0)
; #define PG8_LDA(dst, b, h) do { _Pragma("unroll") for (int m = 0; m < 4; ++m) _Pragma("unroll") for (int k = 0; k < 2; ++k) dst[m][k] = *(const LAS bf16x8*)(lds + PG8_SA(b, h) + aoff + m * 2048 + k * 1024); } while (0)
; #define PG8_WAIT_V(n) asm volatile("s_waitcnt vmcnt(" #n ")" ::: "memory")
; #define PG8_WAIT_L(n) asm volatile("s_waitcnt lgkmcnt(" #n ")" ::: "memory")
; #define PG8_BAR __builtin_amdgcn_s_barrier()
; #define PG8_SCHED __builtin_amdgcn_sched_barrier(0)
;     ...
;             PG8_LDA(At, 1, 1); PG8_STAGE(PG8_SB(1, 0), b3, voffB); PG8_STAGE(PG8_SB(1, 1), b3 + hstep, voffB); PG8_STAGE(PG8_SA(1, 0), a3, voffA);
;             PG8_WAIT_V(8); PG8_WAIT_L(0); PG8_BAR; PG8_MMA(1, 0, At, B0); PG8_MMA(1, 1, At, B1); PG8_BAR; PG8_SCHED;
;         }
	s_add_i32 s36, s61, s39
	v_lshl_add_u64 v[162:163], v[162:163], 0, s[12:13]
	s_mov_b32 m0, s36
	ds_read_b128 v[192:195], v168 offset:49152
	ds_read_b128 v[196:199], v168 offset:50176
	ds_read_b128 v[200:203], v168 offset:51200
	ds_read_b128 v[204:207], v168 offset:52224
	ds_read_b128 v[208:211], v168 offset:53248
	ds_read_b128 v[212:215], v168 offset:54272
	ds_read_b128 v[216:219], v168 offset:55296
	ds_read_b128 v[220:223], v168 offset:56320
	global_load_lds_dwordx4 v[162:163], off
	s_add_i32 m0, s36, 0x2000
	s_add_u32 s30, s30, 0x40080
	v_lshl_add_u64 v[162:163], v[224:225], 0, s[12:13]
	s_addc_u32 s31, s31, 0
	s_add_i32 s36, s62, s39
	global_load_lds_dwordx4 v[162:163], off
	v_lshl_add_u64 v[162:163], s[30:31], 0, v[138:139]
	s_mov_b32 m0, s36
	s_nop 0
	global_load_lds_dwordx4 v[162:163], off
	v_lshl_add_u64 v[162:163], s[30:31], 0, v[142:143]
	s_add_i32 m0, s36, 0x2000
	s_nop 0
	global_load_lds_dwordx4 v[162:163], off
	v_lshl_add_u64 v[162:163], v[226:227], 0, s[12:13]
	s_mov_b32 m0, s47
	s_nop 0
	global_load_lds_dwordx4 v[162:163], off
	v_lshl_add_u64 v[162:163], v[228:229], 0, s[12:13]
	s_mov_b32 m0, s48
	s_nop 0
	global_load_lds_dwordx4 v[162:163], off
	s_waitcnt vmcnt(8)
	s_waitcnt lgkmcnt(0)
	s_barrier
	s_setprio 1
	s_waitcnt lgkmcnt(0)
	v_mfma_i32_16x16x64_i8 v[60:63], v[128:131], v[192:195], v[60:63]
	v_mfma_i32_16x16x64_i8 v[56:59], v[158:161], v[192:195], v[56:59]
	v_mfma_i32_16x16x64_i8 v[44:47], v[128:131], v[200:203], v[44:47]
	v_mfma_i32_16x16x64_i8 v[40:43], v[158:161], v[200:203], v[40:43]
	v_mfma_i32_16x16x64_i8 v[28:31], v[128:131], v[208:211], v[28:31]
	v_mfma_i32_16x16x64_i8 v[24:27], v[158:161], v[208:211], v[24:27]
	v_mfma_i32_16x16x64_i8 v[12:15], v[128:131], v[216:219], v[12:15]
	v_mfma_i32_16x16x64_i8 v[8:11], v[158:161], v[216:219], v[8:11]
	v_mfma_i32_16x16x64_i8 v[60:63], v[132:135], v[196:199], v[60:63]
	v_mfma_i32_16x16x64_i8 v[56:59], v[172:175], v[196:199], v[56:59]
	v_mfma_i32_16x16x64_i8 v[44:47], v[132:135], v[204:207], v[44:47]
	v_mfma_i32_16x16x64_i8 v[40:43], v[172:175], v[204:207], v[40:43]
	v_mfma_i32_16x16x64_i8 v[28:31], v[132:135], v[212:215], v[28:31]
	v_mfma_i32_16x16x64_i8 v[24:27], v[172:175], v[212:215], v[24:27]
	v_mfma_i32_16x16x64_i8 v[12:15], v[132:135], v[220:223], v[12:15]
	v_mfma_i32_16x16x64_i8 v[8:11], v[172:175], v[220:223], v[8:11]
	s_setprio 0
	s_setprio 1
	v_mfma_i32_16x16x64_i8 v[52:55], v[176:179], v[192:195], v[52:55]
	v_mfma_i32_16x16x64_i8 v[48:51], v[184:187], v[192:195], v[48:51]
	v_mfma_i32_16x16x64_i8 v[36:39], v[176:179], v[200:203], v[36:39]
	v_mfma_i32_16x16x64_i8 v[32:35], v[184:187], v[200:203], v[32:35]
	v_mfma_i32_16x16x64_i8 v[20:23], v[176:179], v[208:211], v[20:23]
	v_mfma_i32_16x16x64_i8 v[16:19], v[184:187], v[208:211], v[16:19]
	v_mfma_i32_16x16x64_i8 v[4:7], v[176:179], v[216:219], v[4:7]
	v_mfma_i32_16x16x64_i8 v[0:3], v[184:187], v[216:219], v[0:3]
	v_mfma_i32_16x16x64_i8 v[52:55], v[180:183], v[196:199], v[52:55]
	v_mfma_i32_16x16x64_i8 v[48:51], v[188:191], v[196:199], v[48:51]
	v_mfma_i32_16x16x64_i8 v[36:39], v[180:183], v[204:207], v[36:39]
	v_mfma_i32_16x16x64_i8 v[32:35], v[188:191], v[204:207], v[32:35]
	v_mfma_i32_16x16x64_i8 v[20:23], v[180:183], v[212:215], v[20:23]
	v_mfma_i32_16x16x64_i8 v[16:19], v[188:191], v[212:215], v[16:19]
	v_mfma_i32_16x16x64_i8 v[4:7], v[180:183], v[220:223], v[4:7]
	v_mfma_i32_16x16x64_i8 v[0:3], v[188:191], v[220:223], v[0:3]
	s_setprio 0
	s_barrier
	s_add_i32 s60, s60, 2
	s_add_u32 s28, s28, 0x100
	s_addc_u32 s29, s29, 0
	s_add_u32 s58, s58, 0x100
	s_addc_u32 s59, s59, 0
	s_cmp_gt_u32 s60, 13
	s_cbranch_scc0 .LBB0_1084

; #define PG8_STAGE(bufoff, gbase, voff) do { _Pragma("unroll") for (int _i = 0; _i < 2; ++_i) \
;         __builtin_amdgcn_global_load_lds((const unsigned*)((const char*)(gbase) + (voff)[_i]), (LAS unsigned*)(lds + (bufoff) + ldsw + _i * 8192), 16, 0, 0); } while (0)
; #define PG8_LDA(dst, b, h) do { _Pragma("unroll") for (int m = 0; m < 4; ++m) _Pragma("unroll") for (int k = 0; k < 2; ++k) dst[m][k] = *(const LAS bf16x8*)(lds + PG8_SA(b, h) + aoff + m * 2048 + k * 1024); } while (0)
; #define PG8_LDB(dst, b, h) do { _Pragma("unroll") for (int n = 0; n < 2; ++n) _Pragma("unroll") for (int k = 0; k < 2; ++k) dst[n][k] = *(const LAS bf16x8*)(lds + PG8_SB(b, h) + boff + n * 2048 + k * 1024); } while (0)
; #define PG8_WAIT_V(n) asm volatile("s_waitcnt vmcnt(" #n ")" ::: "memory")
; #define PG8_WAIT_L(n) asm volatile("s_waitcnt lgkmcnt(" #n ")" ::: "memory")
; #define PG8_BAR __builtin_amdgcn_s_barrier()
; #define PG8_SCHED __builtin_amdgcn_sched_barrier(0)
;     ...
;         for (int t = 0; t < nt; t += 2) {
;             const bool last = (t == nt - 2);
;             const char* a1 = cA + (size_t)(t + 1) * kstep;
;             const char* a2 = last ? nA : cA + (size_t)(t + 2) * kstep; const char* b2 = last ? nB : cB + (size_t)(t + 2) * kstep;
;             const char* a3 = a2 + kstep; const char* b3 = b2 + kstep;
;             PG8_LDB(B0, 0, 0); PG8_LDB(B1, 0, 1); PG8_SCHED; PG8_LDA(At, 0, 0); PG8_STAGE(PG8_SA(1, 1), a1 + hstep, voffA);
;             PG8_WAIT_V(8); PG8_WAIT_L(0); PG8_BAR; PG8_MMA(0, 0, At, B0); PG8_MMA(0, 1, At, B1); PG8_BAR; PG8_SCHED;
;             PG8_LDA(At, 0, 1); PG8_STAGE(PG8_SB(0, 0), b2, voffB); PG8_STAGE(PG8_SB(0, 1), b2 + hstep, voffB); PG8_STAGE(PG8_SA(0, 0), a2, voffA);
;             PG8_WAIT_V(8); PG8_WAIT_L(0); PG8_BAR; PG8_MMA(1, 0, At, B0); PG8_MMA(1, 1, At, B1); PG8_BAR; PG8_SCHED;
;     ...
; #pragma unroll
;         for (int a = 0; a < 2; ++a)
; #pragma unroll
;             for (int b = 0; b < 2; ++b)
; #pragma unroll
;                 for (int m = 0; m < 4; ++m)
; #pragma unroll
;                     for (int n = 0; n < 2; ++n) acc[a][b][m][n] = (f32x4){0.f, 0.f, 0.f, 0.f};
.LBB0_3685:
	s_ashr_i32 s31, s30, 31
	s_lshl_b64 s[36:37], s[30:31], 19
	s_add_u32 s36, s21, s36
	s_addc_u32 s37, s23, s37
	s_and_b64 s[38:39], s[4:5], exec
	s_cselect_b32 s31, s37, s45
	s_cselect_b32 s41, s36, s44
	s_ashr_i32 s29, s28, 31
	s_lshl_b64 s[38:39], s[28:29], 19
	s_add_u32 s38, s25, s38
	s_addc_u32 s39, s27, s39
	s_and_b64 s[48:49], s[4:5], exec
	s_cselect_b32 s29, s39, s47
	s_cselect_b32 s66, s38, s46
	s_add_u32 s44, s44, 0x40080
	s_addc_u32 s45, s45, 0
	s_add_u32 s67, s46, 0x100
	s_addc_u32 s68, s47, 0
	s_mov_b32 s69, -2
	ds_read_b128 v[24:27], v187
	ds_read_b128 v[28:31], v187 offset:1024
	ds_read_b128 v[16:19], v187 offset:2048
	ds_read_b128 v[20:23], v187 offset:3072
	ds_read_b128 v[8:11], v188
	ds_read_b128 v[12:15], v188 offset:1024
	s_waitcnt lgkmcnt(0)
	ds_read_b128 v[0:3], v188 offset:2048
	ds_read_b128 v[4:7], v188 offset:3072
	s_add_u32 s46, s44, 0xfffc0080
	s_addc_u32 s47, s45, -1
	s_cmp_eq_u32 s69, 12
	s_cselect_b32 s49, s31, s47
	s_cselect_b32 s48, s41, s46
	s_cselect_b32 s47, s29, s68
	s_cselect_b32 s46, s66, s67
	v_lshl_add_u64 v[218:219], s[44:45], 0, v[168:169]
	s_add_i32 m0, s35, 0xc000
	ds_read_b128 v[176:179], v189
	ds_read_b128 v[180:183], v189 offset:1024
	ds_read_b128 v[194:197], v189 offset:2048
	ds_read_b128 v[198:201], v189 offset:3072
	ds_read_b128 v[202:205], v189 offset:4096
	ds_read_b128 v[206:209], v189 offset:5120
	ds_read_b128 v[210:213], v189 offset:6144
	ds_read_b128 v[214:217], v189 offset:7168
	global_load_lds_dwordx4 v[218:219], off
	v_lshl_add_u64 v[218:219], s[44:45], 0, v[170:171]
	s_add_i32 m0, s35, 0xe000
	s_nop 0
	global_load_lds_dwordx4 v[218:219], off
	s_waitcnt vmcnt(8)
	s_waitcnt lgkmcnt(0)
	s_barrier
	s_setprio 1
	s_waitcnt lgkmcnt(0)
	v_mfma_scale_f32_16x16x128_f8f6f4 v[156:159], v[24:31], v[176:183], 0, v190, v190 op_sel_hi:[0,0,0]
	v_mfma_scale_f32_16x16x128_f8f6f4 v[152:155], v[16:23], v[176:183], 0, v190, v190 op_sel_hi:[0,0,0]
	v_mfma_scale_f32_16x16x128_f8f6f4 v[140:143], v[24:31], v[194:201], 0, v190, v190 op_sel_hi:[0,0,0]
	v_mfma_scale_f32_16x16x128_f8f6f4 v[136:139], v[16:23], v[194:201], 0, v190, v190 op_sel_hi:[0,0,0]
	v_mfma_scale_f32_16x16x128_f8f6f4 v[124:127], v[24:31], v[202:209], 0, v190, v190 op_sel_hi:[0,0,0]
	v_mfma_scale_f32_16x16x128_f8f6f4 v[120:123], v[16:23], v[202:209], 0, v190, v190 op_sel_hi:[0,0,0]
	v_mfma_scale_f32_16x16x128_f8f6f4 v[108:111], v[24:31], v[210:217], 0, v190, v190 op_sel_hi:[0,0,0]
	v_mfma_scale_f32_16x16x128_f8f6f4 v[104:107], v[16:23], v[210:217], 0, v190, v190 op_sel_hi:[0,0,0]
	s_setprio 0
	s_setprio 1
	v_mfma_scale_f32_16x16x128_f8f6f4 v[148:151], v[8:15], v[176:183], 0, v190, v190 op_sel_hi:[0,0,0]
	v_mfma_scale_f32_16x16x128_f8f6f4 v[144:147], v[0:7], v[176:183], 0, v190, v190 op_sel_hi:[0,0,0]
	v_mfma_scale_f32_16x16x128_f8f6f4 v[132:135], v[8:15], v[194:201], 0, v190, v190 op_sel_hi:[0,0,0]
	v_mfma_scale_f32_16x16x128_f8f6f4 v[128:131], v[0:7], v[194:201], 0, v190, v190 op_sel_hi:[0,0,0]
	v_mfma_scale_f32_16x16x128_f8f6f4 v[116:119], v[8:15], v[202:209], 0, v190, v190 op_sel_hi:[0,0,0]
	v_mfma_scale_f32_16x16x128_f8f6f4 v[112:115], v[0:7], v[202:209], 0, v190, v190 op_sel_hi:[0,0,0]
	v_mfma_scale_f32_16x16x128_f8f6f4 v[100:103], v[8:15], v[210:217], 0, v190, v190 op_sel_hi:[0,0,0]
	v_mfma_scale_f32_16x16x128_f8f6f4 v[96:99], v[0:7], v[210:217], 0, v190, v190 op_sel_hi:[0,0,0]
	s_setprio 0
	s_barrier
	s_add_i32 s70, s61, s34
	v_lshl_add_u64 v[176:177], s[46:47], 0, v[162:163]
	s_mov_b32 m0, s70
	ds_read_b128 v[194:197], v189 offset:16384
	ds_read_b128 v[198:201], v189 offset:17408
	ds_read_b128 v[202:205], v189 offset:18432
	ds_read_b128 v[206:209], v189 offset:19456
	ds_read_b128 v[210:213], v189 offset:20480
	ds_read_b128 v[214:217], v189 offset:21504
	ds_read_b128 v[218:221], v189 offset:22528
	ds_read_b128 v[222:225], v189 offset:23552
	global_load_lds_dwordx4 v[176:177], off
	s_add_i32 m0, s70, 0x2000
	s_add_u32 s70, s46, 0x40000
	v_lshl_add_u64 v[178:179], s[46:47], 0, v[166:167]
	s_addc_u32 s71, s47, 0
	s_add_i32 s72, s62, s34
	global_load_lds_dwordx4 v[178:179], off
	v_lshl_add_u64 v[180:181], s[70:71], 0, v[162:163]
	s_mov_b32 m0, s72
	v_lshl_add_u64 v[182:183], s[48:49], 0, v[164:165]
	global_load_lds_dwordx4 v[180:181], off
	v_lshl_add_u64 v[180:181], s[70:71], 0, v[166:167]
	s_add_i32 m0, s72, 0x2000
	s_nop 0
	global_load_lds_dwordx4 v[180:181], off
	v_lshl_add_u64 v[180:181], s[48:49], 0, v[160:161]
	s_mov_b32 m0, s35
	s_nop 0
	global_load_lds_dwordx4 v[180:181], off
	s_mov_b32 m0, s43
	s_nop 0
	global_load_lds_dwordx4 v[182:183], off
	s_waitcnt vmcnt(8)
	s_waitcnt lgkmcnt(0)
	s_barrier
	s_setprio 1
	s_waitcnt lgkmcnt(0)
	v_mfma_scale_f32_16x16x128_f8f6f4 v[92:95], v[24:31], v[194:201], 0, v190, v190 op_sel_hi:[0,0,0]
	v_mfma_scale_f32_16x16x128_f8f6f4 v[88:91], v[16:23], v[194:201], 0, v190, v190 op_sel_hi:[0,0,0]
	v_mfma_scale_f32_16x16x128_f8f6f4 v[76:79], v[24:31], v[202:209], 0, v190, v190 op_sel_hi:[0,0,0]
	v_mfma_scale_f32_16x16x128_f8f6f4 v[72:75], v[16:23], v[202:209], 0, v190, v190 op_sel_hi:[0,0,0]
	v_mfma_scale_f32_16x16x128_f8f6f4 v[60:63], v[24:31], v[210:217], 0, v190, v190 op_sel_hi:[0,0,0]
	v_mfma_scale_f32_16x16x128_f8f6f4 v[56:59], v[16:23], v[210:217], 0, v190, v190 op_sel_hi:[0,0,0]
	v_mfma_scale_f32_16x16x128_f8f6f4 v[44:47], v[24:31], v[218:225], 0, v190, v190 op_sel_hi:[0,0,0]
	v_mfma_scale_f32_16x16x128_f8f6f4 v[40:43], v[16:23], v[218:225], 0, v190, v190 op_sel_hi:[0,0,0]
	s_setprio 0
	s_setprio 1
	v_mfma_scale_f32_16x16x128_f8f6f4 v[84:87], v[8:15], v[194:201], 0, v190, v190 op_sel_hi:[0,0,0]
	v_mfma_scale_f32_16x16x128_f8f6f4 v[80:83], v[0:7], v[194:201], 0, v190, v190 op_sel_hi:[0,0,0]
	v_mfma_scale_f32_16x16x128_f8f6f4 v[68:71], v[8:15], v[202:209], 0, v190, v190 op_sel_hi:[0,0,0]
	v_mfma_scale_f32_16x16x128_f8f6f4 v[64:67], v[0:7], v[202:209], 0, v190, v190 op_sel_hi:[0,0,0]
	v_mfma_scale_f32_16x16x128_f8f6f4 v[52:55], v[8:15], v[210:217], 0, v190, v190 op_sel_hi:[0,0,0]
	v_mfma_scale_f32_16x16x128_f8f6f4 v[48:51], v[0:7], v[210:217], 0, v190, v190 op_sel_hi:[0,0,0]
	v_mfma_scale_f32_16x16x128_f8f6f4 v[36:39], v[8:15], v[218:225], 0, v190, v190 op_sel_hi:[0,0,0]
	v_mfma_scale_f32_16x16x128_f8f6f4 v[32:35], v[0:7], v[218:225], 0, v190, v190 op_sel_hi:[0,0,0]
	s_setprio 0
	s_barrier
; #define PG8_STAGE(bufoff, gbase, voff) do { _Pragma("unroll") for (int _i = 0; _i < 2; ++_i) \
;         __builtin_amdgcn_global_load_lds((const unsigned*)((const char*)(gbase) + (voff)[_i]), (LAS unsigned*)(lds + (bufoff) + ldsw + _i * 8192), 16, 0, 0); } while (0)
; #define PG8_LDA(dst, b, h) do { _Pragma("unroll") for (int m = 0; m < 4; ++m) _Pragma("unroll") for (int k = 0; k < 2; ++k) dst[m][k] = *(const LAS bf16x8*)(lds + PG8_SA(b, h) + aoff + m * 2048 + k * 1024); } while (0)
; #define PG8_LDB(dst, b, h) do { _Pragma("unroll") for (int n = 0; n < 2; ++n) _Pragma("unroll") for (int k = 0; k < 2; ++k) dst[n][k] = *(const LAS bf16x8*)(lds + PG8_SB(b, h) + boff + n * 2048 + k * 1024); } while (0)
; #define PG8_WAIT_V(n) asm volatile("s_waitcnt vmcnt(" #n ")" ::: "memory")
; #define PG8_WAIT_L(n) asm volatile("s_waitcnt lgkmcnt(" #n ")" ::: "memory")
; #define PG8_BAR __builtin_amdgcn_s_barrier()
; #define PG8_SCHED __builtin_amdgcn_sched_barrier(0)
;     ...
;             PG8_LDB(B0, 1, 0); PG8_LDB(B1, 1, 1); PG8_SCHED; PG8_LDA(At, 1, 0); PG8_STAGE(PG8_SA(0, 1), a2 + hstep, voffA);
;             PG8_WAIT_V(8); PG8_WAIT_L(0); PG8_BAR; PG8_MMA(0, 0, At, B0); PG8_MMA(0, 1, At, B1); PG8_BAR; PG8_SCHED;
;             PG8_LDA(At, 1, 1); PG8_STAGE(PG8_SB(1, 0), b3, voffB); PG8_STAGE(PG8_SB(1, 1), b3 + hstep, voffB); PG8_STAGE(PG8_SA(1, 0), a3, voffA);
;             PG8_WAIT_V(8); PG8_WAIT_L(0); PG8_BAR; PG8_MMA(1, 0, At, B0); PG8_MMA(1, 1, At, B1); PG8_BAR; PG8_SCHED;
;         }
	s_add_i32 s70, 0, 0x18000
	s_add_i32 s71, 0, 0x1c000
	v_add_u32_e32 v12, s70, v185
	v_add_u32_e32 v28, s71, v185
	ds_read_b128 v[0:3], v12
	ds_read_b128 v[4:7], v12 offset:1024
	ds_read_b128 v[8:11], v12 offset:2048
	ds_read_b128 v[12:15], v12 offset:3072
	ds_read_b128 v[16:19], v28
	ds_read_b128 v[20:23], v28 offset:1024
	ds_read_b128 v[24:27], v28 offset:2048
	ds_read_b128 v[28:31], v28 offset:3072
	s_add_u32 s48, s48, 0x40000
	s_addc_u32 s49, s49, 0
	s_mov_b32 m0, s50
	v_lshl_add_u64 v[226:227], s[48:49], 0, v[160:161]
	ds_read_b128 v[194:197], v189 offset:32768
	ds_read_b128 v[198:201], v189 offset:33792
	ds_read_b128 v[202:205], v189 offset:34816
	ds_read_b128 v[206:209], v189 offset:35840
	ds_read_b128 v[210:213], v189 offset:36864
	ds_read_b128 v[214:217], v189 offset:37888
	ds_read_b128 v[218:221], v189 offset:38912
	ds_read_b128 v[222:225], v189 offset:39936
	global_load_lds_dwordx4 v[226:227], off
	v_lshl_add_u64 v[226:227], s[48:49], 0, v[164:165]
	s_mov_b32 m0, s51
	s_nop 0
	global_load_lds_dwordx4 v[226:227], off
	s_waitcnt vmcnt(8)
	s_waitcnt lgkmcnt(0)
	s_barrier
	s_setprio 1
	s_waitcnt lgkmcnt(0)
	v_mfma_scale_f32_16x16x128_f8f6f4 v[156:159], v[0:7], v[194:201], v[156:159], v190, v190 op_sel_hi:[0,0,0]
	v_mfma_scale_f32_16x16x128_f8f6f4 v[152:155], v[8:15], v[194:201], v[152:155], v190, v190 op_sel_hi:[0,0,0]
	v_mfma_scale_f32_16x16x128_f8f6f4 v[140:143], v[0:7], v[202:209], v[140:143], v190, v190 op_sel_hi:[0,0,0]
	v_mfma_scale_f32_16x16x128_f8f6f4 v[136:139], v[8:15], v[202:209], v[136:139], v190, v190 op_sel_hi:[0,0,0]
	v_mfma_scale_f32_16x16x128_f8f6f4 v[124:127], v[0:7], v[210:217], v[124:127], v190, v190 op_sel_hi:[0,0,0]
	v_mfma_scale_f32_16x16x128_f8f6f4 v[120:123], v[8:15], v[210:217], v[120:123], v190, v190 op_sel_hi:[0,0,0]
	v_mfma_scale_f32_16x16x128_f8f6f4 v[108:111], v[0:7], v[218:225], v[108:111], v190, v190 op_sel_hi:[0,0,0]
	v_mfma_scale_f32_16x16x128_f8f6f4 v[104:107], v[8:15], v[218:225], v[104:107], v190, v190 op_sel_hi:[0,0,0]
	s_setprio 0
	s_setprio 1
	v_mfma_scale_f32_16x16x128_f8f6f4 v[148:151], v[16:23], v[194:201], v[148:151], v190, v190 op_sel_hi:[0,0,0]
	v_mfma_scale_f32_16x16x128_f8f6f4 v[144:147], v[24:31], v[194:201], v[144:147], v190, v190 op_sel_hi:[0,0,0]
	v_mfma_scale_f32_16x16x128_f8f6f4 v[132:135], v[16:23], v[202:209], v[132:135], v190, v190 op_sel_hi:[0,0,0]
	v_mfma_scale_f32_16x16x128_f8f6f4 v[128:131], v[24:31], v[202:209], v[128:131], v190, v190 op_sel_hi:[0,0,0]
	v_mfma_scale_f32_16x16x128_f8f6f4 v[116:119], v[16:23], v[210:217], v[116:119], v190, v190 op_sel_hi:[0,0,0]
	v_mfma_scale_f32_16x16x128_f8f6f4 v[112:115], v[24:31], v[210:217], v[112:115], v190, v190 op_sel_hi:[0,0,0]
	v_mfma_scale_f32_16x16x128_f8f6f4 v[100:103], v[16:23], v[218:225], v[100:103], v190, v190 op_sel_hi:[0,0,0]
	v_mfma_scale_f32_16x16x128_f8f6f4 v[96:99], v[24:31], v[218:225], v[96:99], v190, v190 op_sel_hi:[0,0,0]
	s_setprio 0
	s_barrier
	s_add_i32 s48, s70, s34
	v_lshl_add_u64 v[176:177], v[176:177], 0, s[16:17]
	s_mov_b32 m0, s48
	ds_read_b128 v[194:197], v189 offset:49152
	ds_read_b128 v[198:201], v189 offset:50176
	ds_read_b128 v[202:205], v189 offset:51200
	ds_read_b128 v[206:209], v189 offset:52224
	ds_read_b128 v[210:213], v189 offset:53248
	ds_read_b128 v[214:217], v189 offset:54272
	ds_read_b128 v[218:221], v189 offset:55296
	ds_read_b128 v[222:225], v189 offset:56320
	global_load_lds_dwordx4 v[176:177], off
	s_add_i32 m0, s48, 0x2000
	s_add_u32 s46, s46, 0x40080
	v_lshl_add_u64 v[176:177], v[178:179], 0, s[16:17]
	s_addc_u32 s47, s47, 0
	s_add_i32 s48, s71, s34
	global_load_lds_dwordx4 v[176:177], off
	v_lshl_add_u64 v[176:177], s[46:47], 0, v[162:163]
	s_mov_b32 m0, s48
	s_nop 0
	global_load_lds_dwordx4 v[176:177], off
	v_lshl_add_u64 v[176:177], s[46:47], 0, v[166:167]
	s_add_i32 m0, s48, 0x2000
	s_nop 0
	global_load_lds_dwordx4 v[176:177], off
	v_lshl_add_u64 v[176:177], v[180:181], 0, s[16:17]
	s_mov_b32 m0, s55
	s_nop 0
	global_load_lds_dwordx4 v[176:177], off
	v_lshl_add_u64 v[176:177], v[182:183], 0, s[16:17]
	s_mov_b32 m0, s58
	s_nop 0
	global_load_lds_dwordx4 v[176:177], off
	s_waitcnt vmcnt(8)
	s_waitcnt lgkmcnt(0)
	s_barrier
	s_setprio 1
	s_waitcnt lgkmcnt(0)
	v_mfma_scale_f32_16x16x128_f8f6f4 v[92:95], v[0:7], v[194:201], v[92:95], v190, v190 op_sel_hi:[0,0,0]
	v_mfma_scale_f32_16x16x128_f8f6f4 v[88:91], v[8:15], v[194:201], v[88:91], v190, v190 op_sel_hi:[0,0,0]
	v_mfma_scale_f32_16x16x128_f8f6f4 v[76:79], v[0:7], v[202:209], v[76:79], v190, v190 op_sel_hi:[0,0,0]
	v_mfma_scale_f32_16x16x128_f8f6f4 v[72:75], v[8:15], v[202:209], v[72:75], v190, v190 op_sel_hi:[0,0,0]
	v_mfma_scale_f32_16x16x128_f8f6f4 v[60:63], v[0:7], v[210:217], v[60:63], v190, v190 op_sel_hi:[0,0,0]
	v_mfma_scale_f32_16x16x128_f8f6f4 v[56:59], v[8:15], v[210:217], v[56:59], v190, v190 op_sel_hi:[0,0,0]
	v_mfma_scale_f32_16x16x128_f8f6f4 v[44:47], v[0:7], v[218:225], v[44:47], v190, v190 op_sel_hi:[0,0,0]
	v_mfma_scale_f32_16x16x128_f8f6f4 v[40:43], v[8:15], v[218:225], v[40:43], v190, v190 op_sel_hi:[0,0,0]
	s_setprio 0
	s_setprio 1
	v_mfma_scale_f32_16x16x128_f8f6f4 v[84:87], v[16:23], v[194:201], v[84:87], v190, v190 op_sel_hi:[0,0,0]
	v_mfma_scale_f32_16x16x128_f8f6f4 v[80:83], v[24:31], v[194:201], v[80:83], v190, v190 op_sel_hi:[0,0,0]
	v_mfma_scale_f32_16x16x128_f8f6f4 v[68:71], v[16:23], v[202:209], v[68:71], v190, v190 op_sel_hi:[0,0,0]
	v_mfma_scale_f32_16x16x128_f8f6f4 v[64:67], v[24:31], v[202:209], v[64:67], v190, v190 op_sel_hi:[0,0,0]
	v_mfma_scale_f32_16x16x128_f8f6f4 v[52:55], v[16:23], v[210:217], v[52:55], v190, v190 op_sel_hi:[0,0,0]
	v_mfma_scale_f32_16x16x128_f8f6f4 v[48:51], v[24:31], v[210:217], v[48:51], v190, v190 op_sel_hi:[0,0,0]
	v_mfma_scale_f32_16x16x128_f8f6f4 v[36:39], v[16:23], v[218:225], v[36:39], v190, v190 op_sel_hi:[0,0,0]
	v_mfma_scale_f32_16x16x128_f8f6f4 v[32:35], v[24:31], v[218:225], v[32:35], v190, v190 op_sel_hi:[0,0,0]
	s_setprio 0
	s_barrier
	s_add_i32 s69, s69, 2
	s_add_u32 s44, s44, 0x100
	s_addc_u32 s45, s45, 0
	s_add_u32 s67, s67, 0x100
	s_addc_u32 s68, s68, 0
	s_cmp_gt_u32 s69, 13
	s_cbranch_scc0 .LBB0_3686

; #define PG8_STAGE(bufoff, gbase, voff) do { _Pragma("unroll") for (int _i = 0; _i < 2; ++_i) \
;         __builtin_amdgcn_global_load_lds((const unsigned*)((const char*)(gbase) + (voff)[_i]), (LAS unsigned*)(lds + (bufoff) + ldsw + _i * 8192), 16, 0, 0); } while (0)
; #define PG8_LDA(dst, b, h) do { _Pragma("unroll") for (int m = 0; m < 4; ++m) _Pragma("unroll") for (int k = 0; k < 2; ++k) dst[m][k] = *(const LAS bf16x8*)(lds + PG8_SA(b, h) + aoff + m * 2048 + k * 1024); } while (0)
; #define PG8_LDB(dst, b, h) do { _Pragma("unroll") for (int n = 0; n < 2; ++n) _Pragma("unroll") for (int k = 0; k < 2; ++k) dst[n][k] = *(const LAS bf16x8*)(lds + PG8_SB(b, h) + boff + n * 2048 + k * 1024); } while (0)
; #define PG8_WAIT_V(n) asm volatile("s_waitcnt vmcnt(" #n ")" ::: "memory")
; #define PG8_WAIT_L(n) asm volatile("s_waitcnt lgkmcnt(" #n ")" ::: "memory")
; #define PG8_BAR __builtin_amdgcn_s_barrier()
; #define PG8_SCHED __builtin_amdgcn_sched_barrier(0)
;     ...
;         const char* nA = has_next ? (const char*)g.A + (size_t)nxt.pm * tstep + (size_t)nxt.kt0 * kstep : cA; const char* nB = has_next ? (const char*)g.Bt + (size_t)nxt.e * g.estride + (size_t)nxt.pn * tstep + (size_t)nxt.kt0 * kstep : cB;
;         const int nt = cur.nkt;
;         for (int t = 0; t < nt; t += 2) {
;             const bool last = (t == nt - 2);
;             const char* a1 = cA + (size_t)(t + 1) * kstep;
;             const char* a2 = last ? nA : cA + (size_t)(t + 2) * kstep; const char* b2 = last ? nB : cB + (size_t)(t + 2) * kstep;
;             const char* a3 = a2 + kstep; const char* b3 = b2 + kstep;
;             PG8_LDB(B0, 0, 0); PG8_LDB(B1, 0, 1); PG8_SCHED; PG8_LDA(At, 0, 0); PG8_STAGE(PG8_SA(1, 1), a1 + hstep, voffA);
;             PG8_WAIT_V(8); PG8_WAIT_L(0); PG8_BAR; PG8_MMA(0, 0, At, B0); PG8_MMA(0, 1, At, B1); PG8_BAR; PG8_SCHED;
;             PG8_LDA(At, 0, 1); PG8_STAGE(PG8_SB(0, 0), b2, voffB); PG8_STAGE(PG8_SB(0, 1), b2 + hstep, voffB); PG8_STAGE(PG8_SA(0, 0), a2, voffA);
;             PG8_WAIT_V(8); PG8_WAIT_L(0); PG8_BAR; PG8_MMA(1, 0, At, B0); PG8_MMA(1, 1, At, B1); PG8_BAR; PG8_SCHED;
.LBB0_3775:
	s_ashr_i32 s31, s30, 31
	s_lshl_b64 s[36:37], s[30:31], 19
	s_add_u32 s36, s21, s36
	s_addc_u32 s37, s23, s37
	s_and_b64 s[38:39], s[2:3], exec
	s_cselect_b32 s31, s37, s41
	s_cselect_b32 s64, s36, s40
	s_ashr_i32 s29, s28, 31
	s_lshl_b64 s[38:39], s[28:29], 19
	s_add_u32 s38, s25, s38
	s_addc_u32 s39, s27, s39
	s_and_b64 s[44:45], s[2:3], exec
	s_cselect_b32 s29, s39, s43
	s_cselect_b32 s65, s38, s42
	s_add_u32 s40, s40, 0x40080
	s_addc_u32 s41, s41, 0
	s_add_u32 s66, s42, 0x100
	s_addc_u32 s67, s43, 0
	s_mov_b32 s68, -2
	ds_read_b128 v[84:87], v169
	ds_read_b128 v[88:91], v169 offset:1024
	ds_read_b128 v[96:99], v169 offset:2048
	ds_read_b128 v[100:103], v169 offset:3072
	ds_read_b128 v[160:163], v170
	ds_read_b128 v[174:177], v170 offset:1024
	ds_read_b128 v[178:181], v170 offset:2048
	ds_read_b128 v[182:185], v170 offset:3072
	s_add_u32 s42, s40, 0xfffc0080
	s_addc_u32 s43, s41, -1
	s_cmp_eq_u32 s68, 12
	s_cselect_b32 s45, s31, s43
	s_cselect_b32 s44, s64, s42
	s_cselect_b32 s43, s29, s67
	s_cselect_b32 s42, s65, s66
	v_lshl_add_u64 v[164:165], s[40:41], 0, v[152:153]
	s_add_i32 m0, s47, 0xc000
	ds_read_b128 v[186:189], v171
	ds_read_b128 v[190:193], v171 offset:1024
	ds_read_b128 v[194:197], v171 offset:2048
	ds_read_b128 v[198:201], v171 offset:3072
	ds_read_b128 v[202:205], v171 offset:4096
	ds_read_b128 v[206:209], v171 offset:5120
	ds_read_b128 v[210:213], v171 offset:6144
	ds_read_b128 v[214:217], v171 offset:7168
	global_load_lds_dwordx4 v[164:165], off
	v_lshl_add_u64 v[164:165], s[40:41], 0, v[154:155]
	s_add_i32 m0, s47, 0xe000
	s_nop 0
	global_load_lds_dwordx4 v[164:165], off
	s_waitcnt vmcnt(8)
	s_waitcnt lgkmcnt(0)
	s_barrier
	s_setprio 1
	s_waitcnt lgkmcnt(0)
	v_mfma_i32_16x16x64_i8 v[140:143], v[84:87], v[186:189], 0
	v_mfma_i32_16x16x64_i8 v[136:139], v[96:99], v[186:189], 0
	v_mfma_i32_16x16x64_i8 v[124:127], v[84:87], v[194:197], 0
	v_mfma_i32_16x16x64_i8 v[120:123], v[96:99], v[194:197], 0
	v_mfma_i32_16x16x64_i8 v[108:111], v[84:87], v[202:205], 0
	v_mfma_i32_16x16x64_i8 v[104:107], v[96:99], v[202:205], 0
	v_mfma_i32_16x16x64_i8 v[76:79], v[84:87], v[210:213], 0
	v_mfma_i32_16x16x64_i8 v[72:75], v[96:99], v[210:213], 0
	v_mfma_i32_16x16x64_i8 v[140:143], v[88:91], v[190:193], v[140:143]
	v_mfma_i32_16x16x64_i8 v[136:139], v[100:103], v[190:193], v[136:139]
	v_mfma_i32_16x16x64_i8 v[124:127], v[88:91], v[198:201], v[124:127]
	v_mfma_i32_16x16x64_i8 v[120:123], v[100:103], v[198:201], v[120:123]
	v_mfma_i32_16x16x64_i8 v[108:111], v[88:91], v[206:209], v[108:111]
	v_mfma_i32_16x16x64_i8 v[104:107], v[100:103], v[206:209], v[104:107]
	v_mfma_i32_16x16x64_i8 v[76:79], v[88:91], v[214:217], v[76:79]
	v_mfma_i32_16x16x64_i8 v[72:75], v[100:103], v[214:217], v[72:75]
	s_setprio 0
	s_setprio 1
	v_mfma_i32_16x16x64_i8 v[132:135], v[160:163], v[186:189], 0
	v_mfma_i32_16x16x64_i8 v[128:131], v[178:181], v[186:189], 0
	v_mfma_i32_16x16x64_i8 v[116:119], v[160:163], v[194:197], 0
	v_mfma_i32_16x16x64_i8 v[112:115], v[178:181], v[194:197], 0
	v_mfma_i32_16x16x64_i8 v[92:95], v[160:163], v[202:205], 0
	v_mfma_i32_16x16x64_i8 v[80:83], v[178:181], v[202:205], 0
	v_mfma_i32_16x16x64_i8 v[68:71], v[160:163], v[210:213], 0
	v_mfma_i32_16x16x64_i8 v[64:67], v[178:181], v[210:213], 0
	v_mfma_i32_16x16x64_i8 v[132:135], v[174:177], v[190:193], v[132:135]
	v_mfma_i32_16x16x64_i8 v[128:131], v[182:185], v[190:193], v[128:131]
	v_mfma_i32_16x16x64_i8 v[116:119], v[174:177], v[198:201], v[116:119]
	v_mfma_i32_16x16x64_i8 v[112:115], v[182:185], v[198:201], v[112:115]
	v_mfma_i32_16x16x64_i8 v[92:95], v[174:177], v[206:209], v[92:95]
	v_mfma_i32_16x16x64_i8 v[80:83], v[182:185], v[206:209], v[80:83]
	v_mfma_i32_16x16x64_i8 v[68:71], v[174:177], v[214:217], v[68:71]
	v_mfma_i32_16x16x64_i8 v[64:67], v[182:185], v[214:217], v[64:67]
	s_setprio 0
	s_barrier
	s_add_i32 s69, s59, s34
	v_lshl_add_u64 v[164:165], s[42:43], 0, v[148:149]
	s_mov_b32 m0, s69
	ds_read_b128 v[186:189], v171 offset:16384
	ds_read_b128 v[190:193], v171 offset:17408
	ds_read_b128 v[194:197], v171 offset:18432
	ds_read_b128 v[198:201], v171 offset:19456
	ds_read_b128 v[202:205], v171 offset:20480
	ds_read_b128 v[206:209], v171 offset:21504
	ds_read_b128 v[210:213], v171 offset:22528
	ds_read_b128 v[214:217], v171 offset:23552
	global_load_lds_dwordx4 v[164:165], off
	s_add_i32 m0, s69, 0x2000
	s_add_u32 s70, s42, 0x40000
	v_lshl_add_u64 v[218:219], s[42:43], 0, v[144:145]
	s_addc_u32 s71, s43, 0
	s_add_i32 s69, s60, s34
	global_load_lds_dwordx4 v[218:219], off
	v_lshl_add_u64 v[220:221], s[70:71], 0, v[148:149]
	s_mov_b32 m0, s69
	v_lshl_add_u64 v[222:223], s[44:45], 0, v[146:147]
	global_load_lds_dwordx4 v[220:221], off
	v_lshl_add_u64 v[220:221], s[70:71], 0, v[144:145]
	s_add_i32 m0, s69, 0x2000
	s_nop 0
	global_load_lds_dwordx4 v[220:221], off
	v_lshl_add_u64 v[220:221], s[44:45], 0, v[150:151]
	s_mov_b32 m0, s47
	s_nop 0
	global_load_lds_dwordx4 v[220:221], off
	s_mov_b32 m0, s48
	s_nop 0
	global_load_lds_dwordx4 v[222:223], off
	s_waitcnt vmcnt(8)
	s_waitcnt lgkmcnt(0)
	s_barrier
; #define PG8_STAGE(bufoff, gbase, voff) do { _Pragma("unroll") for (int _i = 0; _i < 2; ++_i) \
;         __builtin_amdgcn_global_load_lds((const unsigned*)((const char*)(gbase) + (voff)[_i]), (LAS unsigned*)(lds + (bufoff) + ldsw + _i * 8192), 16, 0, 0); } while (0)
; #define PG8_LDA(dst, b, h) do { _Pragma("unroll") for (int m = 0; m < 4; ++m) _Pragma("unroll") for (int k = 0; k < 2; ++k) dst[m][k] = *(const LAS bf16x8*)(lds + PG8_SA(b, h) + aoff + m * 2048 + k * 1024); } while (0)
; #define PG8_LDB(dst, b, h) do { _Pragma("unroll") for (int n = 0; n < 2; ++n) _Pragma("unroll") for (int k = 0; k < 2; ++k) dst[n][k] = *(const LAS bf16x8*)(lds + PG8_SB(b, h) + boff + n * 2048 + k * 1024); } while (0)
; #define PG8_WAIT_V(n) asm volatile("s_waitcnt vmcnt(" #n ")" ::: "memory")
; #define PG8_WAIT_L(n) asm volatile("s_waitcnt lgkmcnt(" #n ")" ::: "memory")
; #define PG8_BAR __builtin_amdgcn_s_barrier()
; #define PG8_SCHED __builtin_amdgcn_sched_barrier(0)
;     ...
;             PG8_WAIT_V(8); PG8_WAIT_L(0); PG8_BAR; PG8_MMA(1, 0, At, B0); PG8_MMA(1, 1, At, B1); PG8_BAR; PG8_SCHED;
;             PG8_LDB(B0, 1, 0); PG8_LDB(B1, 1, 1); PG8_SCHED; PG8_LDA(At, 1, 0); PG8_STAGE(PG8_SA(0, 1), a2 + hstep, voffA);
;             PG8_WAIT_V(8); PG8_WAIT_L(0); PG8_BAR; PG8_MMA(0, 0, At, B0); PG8_MMA(0, 1, At, B1); PG8_BAR; PG8_SCHED;
	s_setprio 1
	s_waitcnt lgkmcnt(0)
	v_mfma_i32_16x16x64_i8 v[60:63], v[84:87], v[186:189], 0
	v_mfma_i32_16x16x64_i8 v[56:59], v[96:99], v[186:189], 0
	v_mfma_i32_16x16x64_i8 v[44:47], v[84:87], v[194:197], 0
	v_mfma_i32_16x16x64_i8 v[40:43], v[96:99], v[194:197], 0
	v_mfma_i32_16x16x64_i8 v[28:31], v[84:87], v[202:205], 0
	v_mfma_i32_16x16x64_i8 v[24:27], v[96:99], v[202:205], 0
	v_mfma_i32_16x16x64_i8 v[12:15], v[84:87], v[210:213], 0
	v_mfma_i32_16x16x64_i8 v[8:11], v[96:99], v[210:213], 0
	v_mfma_i32_16x16x64_i8 v[60:63], v[88:91], v[190:193], v[60:63]
	v_mfma_i32_16x16x64_i8 v[56:59], v[100:103], v[190:193], v[56:59]
	v_mfma_i32_16x16x64_i8 v[44:47], v[88:91], v[198:201], v[44:47]
	v_mfma_i32_16x16x64_i8 v[40:43], v[100:103], v[198:201], v[40:43]
	v_mfma_i32_16x16x64_i8 v[28:31], v[88:91], v[206:209], v[28:31]
	v_mfma_i32_16x16x64_i8 v[24:27], v[100:103], v[206:209], v[24:27]
	v_mfma_i32_16x16x64_i8 v[12:15], v[88:91], v[214:217], v[12:15]
	v_mfma_i32_16x16x64_i8 v[8:11], v[100:103], v[214:217], v[8:11]
	s_setprio 0
	s_setprio 1
	v_mfma_i32_16x16x64_i8 v[52:55], v[160:163], v[186:189], 0
	v_mfma_i32_16x16x64_i8 v[48:51], v[178:181], v[186:189], 0
	v_mfma_i32_16x16x64_i8 v[36:39], v[160:163], v[194:197], 0
	v_mfma_i32_16x16x64_i8 v[32:35], v[178:181], v[194:197], 0
	v_mfma_i32_16x16x64_i8 v[20:23], v[160:163], v[202:205], 0
	v_mfma_i32_16x16x64_i8 v[16:19], v[178:181], v[202:205], 0
	v_mfma_i32_16x16x64_i8 v[4:7], v[160:163], v[210:213], 0
	v_mfma_i32_16x16x64_i8 v[0:3], v[178:181], v[210:213], 0
	v_mfma_i32_16x16x64_i8 v[52:55], v[174:177], v[190:193], v[52:55]
	v_mfma_i32_16x16x64_i8 v[48:51], v[182:185], v[190:193], v[48:51]
	v_mfma_i32_16x16x64_i8 v[36:39], v[174:177], v[198:201], v[36:39]
	v_mfma_i32_16x16x64_i8 v[32:35], v[182:185], v[198:201], v[32:35]
	v_mfma_i32_16x16x64_i8 v[20:23], v[174:177], v[206:209], v[20:23]
	v_mfma_i32_16x16x64_i8 v[16:19], v[182:185], v[206:209], v[16:19]
	v_mfma_i32_16x16x64_i8 v[4:7], v[174:177], v[214:217], v[4:7]
	v_mfma_i32_16x16x64_i8 v[0:3], v[182:185], v[214:217], v[0:3]
	s_setprio 0
	s_barrier
	s_add_i32 s69, 0, 0x18000
	s_add_i32 s70, 0, 0x1c000
	v_add_u32_e32 v100, s69, v167
	v_add_u32_e32 v182, s70, v167
	ds_read_b128 v[84:87], v100
	ds_read_b128 v[88:91], v100 offset:1024
	ds_read_b128 v[96:99], v100 offset:2048
	ds_read_b128 v[100:103], v100 offset:3072
	ds_read_b128 v[160:163], v182
	ds_read_b128 v[174:177], v182 offset:1024
	ds_read_b128 v[178:181], v182 offset:2048
	ds_read_b128 v[182:185], v182 offset:3072
	s_add_u32 s44, s44, 0x40000
	s_addc_u32 s45, s45, 0
	s_mov_b32 m0, s49
	v_lshl_add_u64 v[224:225], s[44:45], 0, v[150:151]
	ds_read_b128 v[186:189], v171 offset:32768
	ds_read_b128 v[190:193], v171 offset:33792
	ds_read_b128 v[194:197], v171 offset:34816
	ds_read_b128 v[198:201], v171 offset:35840
	ds_read_b128 v[202:205], v171 offset:36864
	ds_read_b128 v[206:209], v171 offset:37888
	ds_read_b128 v[210:213], v171 offset:38912
	ds_read_b128 v[214:217], v171 offset:39936
	global_load_lds_dwordx4 v[224:225], off
	v_lshl_add_u64 v[224:225], s[44:45], 0, v[146:147]
	s_mov_b32 m0, s50
	s_nop 0
	global_load_lds_dwordx4 v[224:225], off
	s_waitcnt vmcnt(8)
	s_waitcnt lgkmcnt(0)
	s_barrier
	s_setprio 1
	s_waitcnt lgkmcnt(0)
	v_mfma_i32_16x16x64_i8 v[140:143], v[84:87], v[186:189], v[140:143]
	v_mfma_i32_16x16x64_i8 v[136:139], v[96:99], v[186:189], v[136:139]
	v_mfma_i32_16x16x64_i8 v[124:127], v[84:87], v[194:197], v[124:127]
	v_mfma_i32_16x16x64_i8 v[120:123], v[96:99], v[194:197], v[120:123]
	v_mfma_i32_16x16x64_i8 v[108:111], v[84:87], v[202:205], v[108:111]
	v_mfma_i32_16x16x64_i8 v[104:107], v[96:99], v[202:205], v[104:107]
	v_mfma_i32_16x16x64_i8 v[76:79], v[84:87], v[210:213], v[76:79]
	v_mfma_i32_16x16x64_i8 v[72:75], v[96:99], v[210:213], v[72:75]
	v_mfma_i32_16x16x64_i8 v[140:143], v[88:91], v[190:193], v[140:143]
	v_mfma_i32_16x16x64_i8 v[136:139], v[100:103], v[190:193], v[136:139]
	v_mfma_i32_16x16x64_i8 v[124:127], v[88:91], v[198:201], v[124:127]
	v_mfma_i32_16x16x64_i8 v[120:123], v[100:103], v[198:201], v[120:123]
	v_mfma_i32_16x16x64_i8 v[108:111], v[88:91], v[206:209], v[108:111]
	v_mfma_i32_16x16x64_i8 v[104:107], v[100:103], v[206:209], v[104:107]
	v_mfma_i32_16x16x64_i8 v[76:79], v[88:91], v[214:217], v[76:79]
	v_mfma_i32_16x16x64_i8 v[72:75], v[100:103], v[214:217], v[72:75]
	s_setprio 0
	s_setprio 1
	v_mfma_i32_16x16x64_i8 v[132:135], v[160:163], v[186:189], v[132:135]
	v_mfma_i32_16x16x64_i8 v[128:131], v[178:181], v[186:189], v[128:131]
	v_mfma_i32_16x16x64_i8 v[116:119], v[160:163], v[194:197], v[116:119]
	v_mfma_i32_16x16x64_i8 v[112:115], v[178:181], v[194:197], v[112:115]
	v_mfma_i32_16x16x64_i8 v[92:95], v[160:163], v[202:205], v[92:95]
	v_mfma_i32_16x16x64_i8 v[80:83], v[178:181], v[202:205], v[80:83]
	v_mfma_i32_16x16x64_i8 v[68:71], v[160:163], v[210:213], v[68:71]
	v_mfma_i32_16x16x64_i8 v[64:67], v[178:181], v[210:213], v[64:67]
	v_mfma_i32_16x16x64_i8 v[132:135], v[174:177], v[190:193], v[132:135]
	v_mfma_i32_16x16x64_i8 v[128:131], v[182:185], v[190:193], v[128:131]
	v_mfma_i32_16x16x64_i8 v[116:119], v[174:177], v[198:201], v[116:119]
	v_mfma_i32_16x16x64_i8 v[112:115], v[182:185], v[198:201], v[112:115]
	v_mfma_i32_16x16x64_i8 v[92:95], v[174:177], v[206:209], v[92:95]
	v_mfma_i32_16x16x64_i8 v[80:83], v[182:185], v[206:209], v[80:83]
	v_mfma_i32_16x16x64_i8 v[68:71], v[174:177], v[214:217], v[68:71]
	v_mfma_i32_16x16x64_i8 v[64:67], v[182:185], v[214:217], v[64:67]
	s_setprio 0
	s_barrier
; #define PG8_STAGE(bufoff, gbase, voff) do { _Pragma("unroll") for (int _i = 0; _i < 2; ++_i) \
;         __builtin_amdgcn_global_load_lds((const unsigned*)((const char*)(gbase) + (voff)[_i]), (LAS unsigned*)(lds + (bufoff) + ldsw + _i * 8192), 16, 0, 0); } while (0)
; #define PG8_LDA(dst, b, h) do { _Pragma("unroll") for (int m = 0; m < 4; ++m) _Pragma("unroll") for (int k = 0; k < 2; ++k) dst[m][k] = *(const LAS bf16x8*)(lds + PG8_SA(b, h) + aoff + m * 2048 + k * 1024); } while (0)
; #define PG8_WAIT_V(n) asm volatile("s_waitcnt vmcnt(" #n ")" ::: "memory")
; #define PG8_WAIT_L(n) asm volatile("s_waitcnt lgkmcnt(" #n ")" ::: "memory")
; #define PG8_BAR __builtin_amdgcn_s_barrier()
; #define PG8_SCHED __builtin_amdgcn_sched_barrier(0)
;     ...
;             PG8_LDA(At, 1, 1); PG8_STAGE(PG8_SB(1, 0), b3, voffB); PG8_STAGE(PG8_SB(1, 1), b3 + hstep, voffB); PG8_STAGE(PG8_SA(1, 0), a3, voffA);
;             PG8_WAIT_V(8); PG8_WAIT_L(0); PG8_BAR; PG8_MMA(1, 0, At, B0); PG8_MMA(1, 1, At, B1); PG8_BAR; PG8_SCHED;
;         }
	s_add_i32 s44, s69, s34
	v_lshl_add_u64 v[164:165], v[164:165], 0, s[16:17]
	s_mov_b32 m0, s44
	ds_read_b128 v[186:189], v171 offset:49152
	ds_read_b128 v[190:193], v171 offset:50176
	ds_read_b128 v[194:197], v171 offset:51200
	ds_read_b128 v[198:201], v171 offset:52224
	ds_read_b128 v[202:205], v171 offset:53248
	ds_read_b128 v[206:209], v171 offset:54272
	ds_read_b128 v[210:213], v171 offset:55296
	ds_read_b128 v[214:217], v171 offset:56320
	global_load_lds_dwordx4 v[164:165], off
	s_add_i32 m0, s44, 0x2000
	s_add_u32 s42, s42, 0x40080
	v_lshl_add_u64 v[164:165], v[218:219], 0, s[16:17]
	s_addc_u32 s43, s43, 0
	s_add_i32 s44, s70, s34
	global_load_lds_dwordx4 v[164:165], off
	v_lshl_add_u64 v[164:165], s[42:43], 0, v[148:149]
	s_mov_b32 m0, s44
	s_nop 0
	global_load_lds_dwordx4 v[164:165], off
	v_lshl_add_u64 v[164:165], s[42:43], 0, v[144:145]
	s_add_i32 m0, s44, 0x2000
	s_nop 0
	global_load_lds_dwordx4 v[164:165], off
	v_lshl_add_u64 v[164:165], v[220:221], 0, s[16:17]
	s_mov_b32 m0, s54
	s_nop 0
	global_load_lds_dwordx4 v[164:165], off
	v_lshl_add_u64 v[164:165], v[222:223], 0, s[16:17]
	s_mov_b32 m0, s55
	s_nop 0
	global_load_lds_dwordx4 v[164:165], off
	s_waitcnt vmcnt(8)
	s_waitcnt lgkmcnt(0)
	s_barrier
	s_setprio 1
	s_waitcnt lgkmcnt(0)
	v_mfma_i32_16x16x64_i8 v[60:63], v[84:87], v[186:189], v[60:63]
	v_mfma_i32_16x16x64_i8 v[56:59], v[96:99], v[186:189], v[56:59]
	v_mfma_i32_16x16x64_i8 v[44:47], v[84:87], v[194:197], v[44:47]
	v_mfma_i32_16x16x64_i8 v[40:43], v[96:99], v[194:197], v[40:43]
	v_mfma_i32_16x16x64_i8 v[28:31], v[84:87], v[202:205], v[28:31]
	v_mfma_i32_16x16x64_i8 v[24:27], v[96:99], v[202:205], v[24:27]
	v_mfma_i32_16x16x64_i8 v[12:15], v[84:87], v[210:213], v[12:15]
	v_mfma_i32_16x16x64_i8 v[8:11], v[96:99], v[210:213], v[8:11]
	v_mfma_i32_16x16x64_i8 v[60:63], v[88:91], v[190:193], v[60:63]
	v_mfma_i32_16x16x64_i8 v[56:59], v[100:103], v[190:193], v[56:59]
	v_mfma_i32_16x16x64_i8 v[44:47], v[88:91], v[198:201], v[44:47]
	v_mfma_i32_16x16x64_i8 v[40:43], v[100:103], v[198:201], v[40:43]
	v_mfma_i32_16x16x64_i8 v[28:31], v[88:91], v[206:209], v[28:31]
	v_mfma_i32_16x16x64_i8 v[24:27], v[100:103], v[206:209], v[24:27]
	v_mfma_i32_16x16x64_i8 v[12:15], v[88:91], v[214:217], v[12:15]
	v_mfma_i32_16x16x64_i8 v[8:11], v[100:103], v[214:217], v[8:11]
	s_setprio 0
	s_setprio 1
	v_mfma_i32_16x16x64_i8 v[52:55], v[160:163], v[186:189], v[52:55]
	v_mfma_i32_16x16x64_i8 v[48:51], v[178:181], v[186:189], v[48:51]
	v_mfma_i32_16x16x64_i8 v[36:39], v[160:163], v[194:197], v[36:39]
	v_mfma_i32_16x16x64_i8 v[32:35], v[178:181], v[194:197], v[32:35]
	v_mfma_i32_16x16x64_i8 v[20:23], v[160:163], v[202:205], v[20:23]
	v_mfma_i32_16x16x64_i8 v[16:19], v[178:181], v[202:205], v[16:19]
	v_mfma_i32_16x16x64_i8 v[4:7], v[160:163], v[210:213], v[4:7]
	v_mfma_i32_16x16x64_i8 v[0:3], v[178:181], v[210:213], v[0:3]
	v_mfma_i32_16x16x64_i8 v[52:55], v[174:177], v[190:193], v[52:55]
	v_mfma_i32_16x16x64_i8 v[48:51], v[182:185], v[190:193], v[48:51]
	v_mfma_i32_16x16x64_i8 v[36:39], v[174:177], v[198:201], v[36:39]
	v_mfma_i32_16x16x64_i8 v[32:35], v[182:185], v[198:201], v[32:35]
	v_mfma_i32_16x16x64_i8 v[20:23], v[174:177], v[206:209], v[20:23]
	v_mfma_i32_16x16x64_i8 v[16:19], v[182:185], v[206:209], v[16:19]
	v_mfma_i32_16x16x64_i8 v[4:7], v[174:177], v[214:217], v[4:7]
	v_mfma_i32_16x16x64_i8 v[0:3], v[182:185], v[214:217], v[0:3]
	s_setprio 0
	s_barrier
	s_add_i32 s68, s68, 2
	s_add_u32 s40, s40, 0x100
	s_addc_u32 s41, s41, 0
	s_add_u32 s66, s66, 0x100
	s_addc_u32 s67, s67, 0
	s_cmp_gt_u32 s68, 13
	s_cbranch_scc0 .LBB0_3776

; #define PG8_STAGE(bufoff, gbase, voff) do { _Pragma("unroll") for (int _i = 0; _i < 2; ++_i) \
;         __builtin_amdgcn_global_load_lds((const unsigned*)((const char*)(gbase) + (voff)[_i]), (LAS unsigned*)(lds + (bufoff) + ldsw + _i * 8192), 16, 0, 0); } while (0)
; #define PG8_LDA(dst, b, h) do { _Pragma("unroll") for (int m = 0; m < 4; ++m) _Pragma("unroll") for (int k = 0; k < 2; ++k) dst[m][k] = *(const LAS bf16x8*)(lds + PG8_SA(b, h) + aoff + m * 2048 + k * 1024); } while (0)
; #define PG8_LDB(dst, b, h) do { _Pragma("unroll") for (int n = 0; n < 2; ++n) _Pragma("unroll") for (int k = 0; k < 2; ++k) dst[n][k] = *(const LAS bf16x8*)(lds + PG8_SB(b, h) + boff + n * 2048 + k * 1024); } while (0)
; #define PG8_WAIT_V(n) asm volatile("s_waitcnt vmcnt(" #n ")" ::: "memory")
; #define PG8_WAIT_L(n) asm volatile("s_waitcnt lgkmcnt(" #n ")" ::: "memory")
; #define PG8_BAR __builtin_amdgcn_s_barrier()
; #define PG8_SCHED __builtin_amdgcn_sched_barrier(0)
;     ...
;             PG8_LDB(B0, 0, 0); PG8_LDB(B1, 0, 1); PG8_SCHED; PG8_LDA(At, 0, 0); PG8_STAGE(PG8_SA(1, 1), a1 + hstep, voffA);
;             PG8_WAIT_V(8); PG8_WAIT_L(0); PG8_BAR; PG8_MMA(0, 0, At, B0); PG8_MMA(0, 1, At, B1); PG8_BAR; PG8_SCHED;
;             PG8_LDA(At, 0, 1); PG8_STAGE(PG8_SB(0, 0), b2, voffB); PG8_STAGE(PG8_SB(0, 1), b2 + hstep, voffB); PG8_STAGE(PG8_SA(0, 0), a2, voffA);
;             PG8_WAIT_V(8); PG8_WAIT_L(0); PG8_BAR; PG8_MMA(1, 0, At, B0); PG8_MMA(1, 1, At, B1); PG8_BAR; PG8_SCHED;
.LBB0_3857:
	s_add_u32 s71, s46, 0x100
	s_addc_u32 s72, s47, 0
	s_mov_b32 s73, -2
	ds_read_b128 v[24:27], v189
	ds_read_b128 v[28:31], v189 offset:1024
	ds_read_b128 v[16:19], v189 offset:2048
	ds_read_b128 v[20:23], v189 offset:3072
	ds_read_b128 v[8:11], v190
	ds_read_b128 v[12:15], v190 offset:1024
	s_waitcnt lgkmcnt(0)
	ds_read_b128 v[0:3], v190 offset:2048
	ds_read_b128 v[4:7], v190 offset:3072
	s_add_u32 s6, s44, 0x100
	s_addc_u32 s7, s45, 0
	s_cmp_eq_u32 s73, 40
	s_cselect_b32 s49, s41, s7
	s_cselect_b32 s48, s40, s6
	s_cselect_b32 s47, s43, s72
	s_cselect_b32 s46, s42, s71
	v_lshl_add_u64 v[184:185], s[44:45], 0, v[168:169]
	s_add_i32 m0, s37, 0xc000
	ds_read_b128 v[176:179], v191
	ds_read_b128 v[180:183], v191 offset:1024
	ds_read_b128 v[196:199], v191 offset:2048
	ds_read_b128 v[200:203], v191 offset:3072
	ds_read_b128 v[204:207], v191 offset:4096
	ds_read_b128 v[208:211], v191 offset:5120
	ds_read_b128 v[212:215], v191 offset:6144
	ds_read_b128 v[216:219], v191 offset:7168
	global_load_lds_dwordx4 v[184:185], off
	v_lshl_add_u64 v[184:185], s[44:45], 0, v[170:171]
	s_add_i32 m0, s37, 0xe000
	s_nop 0
	global_load_lds_dwordx4 v[184:185], off
	s_waitcnt vmcnt(8)
	s_waitcnt lgkmcnt(0)
	s_barrier
	s_setprio 1
	s_waitcnt lgkmcnt(0)
	v_mfma_scale_f32_16x16x128_f8f6f4 v[156:159], v[24:31], v[176:183], 0, v192, v192 op_sel_hi:[0,0,0]
	v_mfma_scale_f32_16x16x128_f8f6f4 v[152:155], v[16:23], v[176:183], 0, v192, v192 op_sel_hi:[0,0,0]
	v_mfma_scale_f32_16x16x128_f8f6f4 v[140:143], v[24:31], v[196:203], 0, v192, v192 op_sel_hi:[0,0,0]
	v_mfma_scale_f32_16x16x128_f8f6f4 v[136:139], v[16:23], v[196:203], 0, v192, v192 op_sel_hi:[0,0,0]
	v_mfma_scale_f32_16x16x128_f8f6f4 v[124:127], v[24:31], v[204:211], 0, v192, v192 op_sel_hi:[0,0,0]
	v_mfma_scale_f32_16x16x128_f8f6f4 v[120:123], v[16:23], v[204:211], 0, v192, v192 op_sel_hi:[0,0,0]
	v_mfma_scale_f32_16x16x128_f8f6f4 v[108:111], v[24:31], v[212:219], 0, v192, v192 op_sel_hi:[0,0,0]
	v_mfma_scale_f32_16x16x128_f8f6f4 v[104:107], v[16:23], v[212:219], 0, v192, v192 op_sel_hi:[0,0,0]
	s_setprio 0
	s_setprio 1
	v_mfma_scale_f32_16x16x128_f8f6f4 v[148:151], v[8:15], v[176:183], 0, v192, v192 op_sel_hi:[0,0,0]
	v_mfma_scale_f32_16x16x128_f8f6f4 v[144:147], v[0:7], v[176:183], 0, v192, v192 op_sel_hi:[0,0,0]
	v_mfma_scale_f32_16x16x128_f8f6f4 v[132:135], v[8:15], v[196:203], 0, v192, v192 op_sel_hi:[0,0,0]
	v_mfma_scale_f32_16x16x128_f8f6f4 v[128:131], v[0:7], v[196:203], 0, v192, v192 op_sel_hi:[0,0,0]
	v_mfma_scale_f32_16x16x128_f8f6f4 v[116:119], v[8:15], v[204:211], 0, v192, v192 op_sel_hi:[0,0,0]
	v_mfma_scale_f32_16x16x128_f8f6f4 v[112:115], v[0:7], v[204:211], 0, v192, v192 op_sel_hi:[0,0,0]
	v_mfma_scale_f32_16x16x128_f8f6f4 v[100:103], v[8:15], v[212:219], 0, v192, v192 op_sel_hi:[0,0,0]
	v_mfma_scale_f32_16x16x128_f8f6f4 v[96:99], v[0:7], v[212:219], 0, v192, v192 op_sel_hi:[0,0,0]
	s_setprio 0
	s_barrier
	s_add_i32 s44, s61, s35
	v_lshl_add_u64 v[176:177], s[46:47], 0, v[162:163]
	s_mov_b32 m0, s44
	ds_read_b128 v[196:199], v191 offset:16384
	ds_read_b128 v[200:203], v191 offset:17408
	ds_read_b128 v[204:207], v191 offset:18432
	ds_read_b128 v[208:211], v191 offset:19456
	ds_read_b128 v[212:215], v191 offset:20480
	ds_read_b128 v[216:219], v191 offset:21504
	ds_read_b128 v[220:223], v191 offset:22528
	ds_read_b128 v[224:227], v191 offset:23552
	global_load_lds_dwordx4 v[176:177], off
	s_add_i32 m0, s44, 0x2000
	s_add_u32 s44, s46, 0xb0000
	v_lshl_add_u64 v[178:179], s[46:47], 0, v[166:167]
	s_addc_u32 s45, s47, 0
	s_add_i32 s74, s62, s35
	global_load_lds_dwordx4 v[178:179], off
	v_lshl_add_u64 v[180:181], s[44:45], 0, v[162:163]
	s_mov_b32 m0, s74
	v_lshl_add_u64 v[182:183], s[48:49], 0, v[164:165]
	global_load_lds_dwordx4 v[180:181], off
	v_lshl_add_u64 v[180:181], s[44:45], 0, v[166:167]
	s_add_i32 m0, s74, 0x2000
	s_nop 0
	global_load_lds_dwordx4 v[180:181], off
	v_lshl_add_u64 v[180:181], s[48:49], 0, v[160:161]
	s_mov_b32 m0, s37
	s_nop 0
	global_load_lds_dwordx4 v[180:181], off
	s_mov_b32 m0, s39
	s_nop 0
	global_load_lds_dwordx4 v[182:183], off
	s_waitcnt vmcnt(8)
	s_waitcnt lgkmcnt(0)
	s_barrier
	s_setprio 1
	s_waitcnt lgkmcnt(0)
	v_mfma_scale_f32_16x16x128_f8f6f4 v[92:95], v[24:31], v[196:203], 0, v192, v192 op_sel_hi:[0,0,0]
	v_mfma_scale_f32_16x16x128_f8f6f4 v[88:91], v[16:23], v[196:203], 0, v192, v192 op_sel_hi:[0,0,0]
	v_mfma_scale_f32_16x16x128_f8f6f4 v[76:79], v[24:31], v[204:211], 0, v192, v192 op_sel_hi:[0,0,0]
	v_mfma_scale_f32_16x16x128_f8f6f4 v[72:75], v[16:23], v[204:211], 0, v192, v192 op_sel_hi:[0,0,0]
	v_mfma_scale_f32_16x16x128_f8f6f4 v[60:63], v[24:31], v[212:219], 0, v192, v192 op_sel_hi:[0,0,0]
	v_mfma_scale_f32_16x16x128_f8f6f4 v[56:59], v[16:23], v[212:219], 0, v192, v192 op_sel_hi:[0,0,0]
	v_mfma_scale_f32_16x16x128_f8f6f4 v[44:47], v[24:31], v[220:227], 0, v192, v192 op_sel_hi:[0,0,0]
	v_mfma_scale_f32_16x16x128_f8f6f4 v[40:43], v[16:23], v[220:227], 0, v192, v192 op_sel_hi:[0,0,0]
	s_setprio 0
	s_setprio 1
	v_mfma_scale_f32_16x16x128_f8f6f4 v[84:87], v[8:15], v[196:203], 0, v192, v192 op_sel_hi:[0,0,0]
	v_mfma_scale_f32_16x16x128_f8f6f4 v[80:83], v[0:7], v[196:203], 0, v192, v192 op_sel_hi:[0,0,0]
	v_mfma_scale_f32_16x16x128_f8f6f4 v[68:71], v[8:15], v[204:211], 0, v192, v192 op_sel_hi:[0,0,0]
	v_mfma_scale_f32_16x16x128_f8f6f4 v[64:67], v[0:7], v[204:211], 0, v192, v192 op_sel_hi:[0,0,0]
	v_mfma_scale_f32_16x16x128_f8f6f4 v[52:55], v[8:15], v[212:219], 0, v192, v192 op_sel_hi:[0,0,0]
	v_mfma_scale_f32_16x16x128_f8f6f4 v[48:51], v[0:7], v[212:219], 0, v192, v192 op_sel_hi:[0,0,0]
	v_mfma_scale_f32_16x16x128_f8f6f4 v[36:39], v[8:15], v[220:227], 0, v192, v192 op_sel_hi:[0,0,0]
	v_mfma_scale_f32_16x16x128_f8f6f4 v[32:35], v[0:7], v[220:227], 0, v192, v192 op_sel_hi:[0,0,0]
	s_setprio 0
	s_barrier
; #define PG8_STAGE(bufoff, gbase, voff) do { _Pragma("unroll") for (int _i = 0; _i < 2; ++_i) \
;         __builtin_amdgcn_global_load_lds((const unsigned*)((const char*)(gbase) + (voff)[_i]), (LAS unsigned*)(lds + (bufoff) + ldsw + _i * 8192), 16, 0, 0); } while (0)
; #define PG8_LDA(dst, b, h) do { _Pragma("unroll") for (int m = 0; m < 4; ++m) _Pragma("unroll") for (int k = 0; k < 2; ++k) dst[m][k] = *(const LAS bf16x8*)(lds + PG8_SA(b, h) + aoff + m * 2048 + k * 1024); } while (0)
; #define PG8_LDB(dst, b, h) do { _Pragma("unroll") for (int n = 0; n < 2; ++n) _Pragma("unroll") for (int k = 0; k < 2; ++k) dst[n][k] = *(const LAS bf16x8*)(lds + PG8_SB(b, h) + boff + n * 2048 + k * 1024); } while (0)
; #define PG8_WAIT_V(n) asm volatile("s_waitcnt vmcnt(" #n ")" ::: "memory")
; #define PG8_WAIT_L(n) asm volatile("s_waitcnt lgkmcnt(" #n ")" ::: "memory")
; #define PG8_BAR __builtin_amdgcn_s_barrier()
; #define PG8_SCHED __builtin_amdgcn_sched_barrier(0)
;     ...
;             PG8_LDB(B0, 1, 0); PG8_LDB(B1, 1, 1); PG8_SCHED; PG8_LDA(At, 1, 0); PG8_STAGE(PG8_SA(0, 1), a2 + hstep, voffA);
;             PG8_WAIT_V(8); PG8_WAIT_L(0); PG8_BAR; PG8_MMA(0, 0, At, B0); PG8_MMA(0, 1, At, B1); PG8_BAR; PG8_SCHED;
;             PG8_LDA(At, 1, 1); PG8_STAGE(PG8_SB(1, 0), b3, voffB); PG8_STAGE(PG8_SB(1, 1), b3 + hstep, voffB); PG8_STAGE(PG8_SA(1, 0), a3, voffA);
;             PG8_WAIT_V(8); PG8_WAIT_L(0); PG8_BAR; PG8_MMA(1, 0, At, B0); PG8_MMA(1, 1, At, B1); PG8_BAR; PG8_SCHED;
;         }
	s_add_i32 s74, 0, 0x18000
	s_add_i32 s75, 0, 0x1c000
	v_add_u32_e32 v12, s74, v187
	v_add_u32_e32 v28, s75, v187
	ds_read_b128 v[0:3], v12
	ds_read_b128 v[4:7], v12 offset:1024
	ds_read_b128 v[8:11], v12 offset:2048
	ds_read_b128 v[12:15], v12 offset:3072
	ds_read_b128 v[16:19], v28
	ds_read_b128 v[20:23], v28 offset:1024
	ds_read_b128 v[24:27], v28 offset:2048
	ds_read_b128 v[28:31], v28 offset:3072
	s_add_u32 s44, s48, 0xb0000
	s_addc_u32 s45, s49, 0
	s_mov_b32 m0, s50
	v_lshl_add_u64 v[184:185], s[44:45], 0, v[160:161]
	ds_read_b128 v[196:199], v191 offset:32768
	ds_read_b128 v[200:203], v191 offset:33792
	ds_read_b128 v[204:207], v191 offset:34816
	ds_read_b128 v[208:211], v191 offset:35840
	ds_read_b128 v[212:215], v191 offset:36864
	ds_read_b128 v[216:219], v191 offset:37888
	ds_read_b128 v[220:223], v191 offset:38912
	ds_read_b128 v[224:227], v191 offset:39936
	global_load_lds_dwordx4 v[184:185], off
	v_lshl_add_u64 v[184:185], s[44:45], 0, v[164:165]
	s_mov_b32 m0, s51
	s_nop 0
	global_load_lds_dwordx4 v[184:185], off
	s_waitcnt vmcnt(8)
	s_waitcnt lgkmcnt(0)
	s_barrier
	s_setprio 1
	s_waitcnt lgkmcnt(0)
	v_mfma_scale_f32_16x16x128_f8f6f4 v[156:159], v[0:7], v[196:203], v[156:159], v192, v192 op_sel_hi:[0,0,0]
	v_mfma_scale_f32_16x16x128_f8f6f4 v[152:155], v[8:15], v[196:203], v[152:155], v192, v192 op_sel_hi:[0,0,0]
	v_mfma_scale_f32_16x16x128_f8f6f4 v[140:143], v[0:7], v[204:211], v[140:143], v192, v192 op_sel_hi:[0,0,0]
	v_mfma_scale_f32_16x16x128_f8f6f4 v[136:139], v[8:15], v[204:211], v[136:139], v192, v192 op_sel_hi:[0,0,0]
	v_mfma_scale_f32_16x16x128_f8f6f4 v[124:127], v[0:7], v[212:219], v[124:127], v192, v192 op_sel_hi:[0,0,0]
	v_mfma_scale_f32_16x16x128_f8f6f4 v[120:123], v[8:15], v[212:219], v[120:123], v192, v192 op_sel_hi:[0,0,0]
	v_mfma_scale_f32_16x16x128_f8f6f4 v[108:111], v[0:7], v[220:227], v[108:111], v192, v192 op_sel_hi:[0,0,0]
	v_mfma_scale_f32_16x16x128_f8f6f4 v[104:107], v[8:15], v[220:227], v[104:107], v192, v192 op_sel_hi:[0,0,0]
	s_setprio 0
	s_setprio 1
	v_mfma_scale_f32_16x16x128_f8f6f4 v[148:151], v[16:23], v[196:203], v[148:151], v192, v192 op_sel_hi:[0,0,0]
	v_mfma_scale_f32_16x16x128_f8f6f4 v[144:147], v[24:31], v[196:203], v[144:147], v192, v192 op_sel_hi:[0,0,0]
	v_mfma_scale_f32_16x16x128_f8f6f4 v[132:135], v[16:23], v[204:211], v[132:135], v192, v192 op_sel_hi:[0,0,0]
	v_mfma_scale_f32_16x16x128_f8f6f4 v[128:131], v[24:31], v[204:211], v[128:131], v192, v192 op_sel_hi:[0,0,0]
	v_mfma_scale_f32_16x16x128_f8f6f4 v[116:119], v[16:23], v[212:219], v[116:119], v192, v192 op_sel_hi:[0,0,0]
	v_mfma_scale_f32_16x16x128_f8f6f4 v[112:115], v[24:31], v[212:219], v[112:115], v192, v192 op_sel_hi:[0,0,0]
	v_mfma_scale_f32_16x16x128_f8f6f4 v[100:103], v[16:23], v[220:227], v[100:103], v192, v192 op_sel_hi:[0,0,0]
	v_mfma_scale_f32_16x16x128_f8f6f4 v[96:99], v[24:31], v[220:227], v[96:99], v192, v192 op_sel_hi:[0,0,0]
	s_setprio 0
	s_barrier
	s_add_i32 s44, s74, s35
	v_lshl_add_u64 v[176:177], v[176:177], 0, s[24:25]
	s_mov_b32 m0, s44
	ds_read_b128 v[196:199], v191 offset:49152
	ds_read_b128 v[200:203], v191 offset:50176
	ds_read_b128 v[204:207], v191 offset:51200
	ds_read_b128 v[208:211], v191 offset:52224
	ds_read_b128 v[212:215], v191 offset:53248
	ds_read_b128 v[216:219], v191 offset:54272
	ds_read_b128 v[220:223], v191 offset:55296
	ds_read_b128 v[224:227], v191 offset:56320
	global_load_lds_dwordx4 v[176:177], off
	s_add_i32 m0, s44, 0x2000
	s_add_u32 s44, s46, 0xb0080
	v_lshl_add_u64 v[176:177], v[178:179], 0, s[24:25]
	s_addc_u32 s45, s47, 0
	s_add_i32 s46, s75, s35
	global_load_lds_dwordx4 v[176:177], off
	v_lshl_add_u64 v[176:177], s[44:45], 0, v[162:163]
	s_mov_b32 m0, s46
	s_nop 0
	global_load_lds_dwordx4 v[176:177], off
	v_lshl_add_u64 v[176:177], s[44:45], 0, v[166:167]
	s_add_i32 m0, s46, 0x2000
	s_nop 0
	global_load_lds_dwordx4 v[176:177], off
	v_lshl_add_u64 v[176:177], v[180:181], 0, s[24:25]
	s_mov_b32 m0, s55
	s_nop 0
	global_load_lds_dwordx4 v[176:177], off
	v_lshl_add_u64 v[176:177], v[182:183], 0, s[24:25]
	s_mov_b32 m0, s58
	s_nop 0
	global_load_lds_dwordx4 v[176:177], off
	s_waitcnt vmcnt(8)
	s_waitcnt lgkmcnt(0)
	s_barrier
	s_setprio 1
	s_waitcnt lgkmcnt(0)
	v_mfma_scale_f32_16x16x128_f8f6f4 v[92:95], v[0:7], v[196:203], v[92:95], v192, v192 op_sel_hi:[0,0,0]
	v_mfma_scale_f32_16x16x128_f8f6f4 v[88:91], v[8:15], v[196:203], v[88:91], v192, v192 op_sel_hi:[0,0,0]
	v_mfma_scale_f32_16x16x128_f8f6f4 v[76:79], v[0:7], v[204:211], v[76:79], v192, v192 op_sel_hi:[0,0,0]
	v_mfma_scale_f32_16x16x128_f8f6f4 v[72:75], v[8:15], v[204:211], v[72:75], v192, v192 op_sel_hi:[0,0,0]
	v_mfma_scale_f32_16x16x128_f8f6f4 v[60:63], v[0:7], v[212:219], v[60:63], v192, v192 op_sel_hi:[0,0,0]
	v_mfma_scale_f32_16x16x128_f8f6f4 v[56:59], v[8:15], v[212:219], v[56:59], v192, v192 op_sel_hi:[0,0,0]
	v_mfma_scale_f32_16x16x128_f8f6f4 v[44:47], v[0:7], v[220:227], v[44:47], v192, v192 op_sel_hi:[0,0,0]
	v_mfma_scale_f32_16x16x128_f8f6f4 v[40:43], v[8:15], v[220:227], v[40:43], v192, v192 op_sel_hi:[0,0,0]
	s_setprio 0
	s_setprio 1
	v_mfma_scale_f32_16x16x128_f8f6f4 v[84:87], v[16:23], v[196:203], v[84:87], v192, v192 op_sel_hi:[0,0,0]
	v_mfma_scale_f32_16x16x128_f8f6f4 v[80:83], v[24:31], v[196:203], v[80:83], v192, v192 op_sel_hi:[0,0,0]
	v_mfma_scale_f32_16x16x128_f8f6f4 v[68:71], v[16:23], v[204:211], v[68:71], v192, v192 op_sel_hi:[0,0,0]
	v_mfma_scale_f32_16x16x128_f8f6f4 v[64:67], v[24:31], v[204:211], v[64:67], v192, v192 op_sel_hi:[0,0,0]
	v_mfma_scale_f32_16x16x128_f8f6f4 v[52:55], v[16:23], v[212:219], v[52:55], v192, v192 op_sel_hi:[0,0,0]
	v_mfma_scale_f32_16x16x128_f8f6f4 v[48:51], v[24:31], v[212:219], v[48:51], v192, v192 op_sel_hi:[0,0,0]
	v_mfma_scale_f32_16x16x128_f8f6f4 v[36:39], v[16:23], v[220:227], v[36:39], v192, v192 op_sel_hi:[0,0,0]
	v_mfma_scale_f32_16x16x128_f8f6f4 v[32:35], v[24:31], v[220:227], v[32:35], v192, v192 op_sel_hi:[0,0,0]
	s_setprio 0
	s_barrier
	s_add_i32 s73, s73, 2
	s_add_u32 s71, s71, 0x100
	s_addc_u32 s72, s72, 0
	s_cmp_gt_u32 s73, 41
	s_mov_b64 s[44:45], s[6:7]
	s_cbranch_scc0 .LBB0_3858

; #define PG8_STAGE(bufoff, gbase, voff) do { _Pragma("unroll") for (int _i = 0; _i < 2; ++_i) \
;         __builtin_amdgcn_global_load_lds((const unsigned*)((const char*)(gbase) + (voff)[_i]), (LAS unsigned*)(lds + (bufoff) + ldsw + _i * 8192), 16, 0, 0); } while (0)
; #define PG8_LDA(dst, b, h) do { _Pragma("unroll") for (int m = 0; m < 4; ++m) _Pragma("unroll") for (int k = 0; k < 2; ++k) dst[m][k] = *(const LAS bf16x8*)(lds + PG8_SA(b, h) + aoff + m * 2048 + k * 1024); } while (0)
; #define PG8_LDB(dst, b, h) do { _Pragma("unroll") for (int n = 0; n < 2; ++n) _Pragma("unroll") for (int k = 0; k < 2; ++k) dst[n][k] = *(const LAS bf16x8*)(lds + PG8_SB(b, h) + boff + n * 2048 + k * 1024); } while (0)
; #define PG8_WAIT_V(n) asm volatile("s_waitcnt vmcnt(" #n ")" ::: "memory")
; #define PG8_WAIT_L(n) asm volatile("s_waitcnt lgkmcnt(" #n ")" ::: "memory")
; #define PG8_BAR __builtin_amdgcn_s_barrier()
; #define PG8_SCHED __builtin_amdgcn_sched_barrier(0)
;     ...
;         const char* nA = has_next ? (const char*)g.A + (size_t)nxt.pm * tstep + (size_t)nxt.kt0 * kstep : cA; const char* nB = has_next ? (const char*)g.Bt + (size_t)nxt.e * g.estride + (size_t)nxt.pn * tstep + (size_t)nxt.kt0 * kstep : cB;
;         const int nt = cur.nkt;
;         for (int t = 0; t < nt; t += 2) {
;             const bool last = (t == nt - 2);
;             const char* a1 = cA + (size_t)(t + 1) * kstep;
;             const char* a2 = last ? nA : cA + (size_t)(t + 2) * kstep; const char* b2 = last ? nB : cB + (size_t)(t + 2) * kstep;
;             const char* a3 = a2 + kstep; const char* b3 = b2 + kstep;
;             PG8_LDB(B0, 0, 0); PG8_LDB(B1, 0, 1); PG8_SCHED; PG8_LDA(At, 0, 0); PG8_STAGE(PG8_SA(1, 1), a1 + hstep, voffA);
;             PG8_WAIT_V(8); PG8_WAIT_L(0); PG8_BAR; PG8_MMA(0, 0, At, B0); PG8_MMA(0, 1, At, B1); PG8_BAR; PG8_SCHED;
;             PG8_LDA(At, 0, 1); PG8_STAGE(PG8_SB(0, 0), b2, voffB); PG8_STAGE(PG8_SB(0, 1), b2 + hstep, voffB); PG8_STAGE(PG8_SA(0, 0), a2, voffA);
;             PG8_WAIT_V(8); PG8_WAIT_L(0); PG8_BAR; PG8_MMA(1, 0, At, B0); PG8_MMA(1, 1, At, B1); PG8_BAR; PG8_SCHED;
.LBB0_3954:
	s_ashr_i32 s39, s38, 31
	s_lshl_b64 s[40:41], s[38:39], 19
	s_add_u32 s40, s23, s40
	s_addc_u32 s41, s27, s41
	s_and_b64 s[42:43], s[4:5], exec
	s_cselect_b32 s7, s41, s47
	s_cselect_b32 s39, s40, s46
	s_ashr_i32 s37, s36, 31
	s_lshl_b64 s[42:43], s[36:37], 19
	s_add_u32 s42, s29, s42
	s_addc_u32 s43, s31, s43
	s_and_b64 s[50:51], s[4:5], exec
	s_cselect_b32 s37, s43, s49
	s_cselect_b32 s45, s42, s48
	s_add_u32 s46, s46, 0x40080
	s_addc_u32 s47, s47, 0
	s_add_u32 s73, s48, 0x100
	s_addc_u32 s74, s49, 0
	s_mov_b32 s75, -2
	s_waitcnt lgkmcnt(0)
	ds_read_b128 v[152:155], v183
	ds_read_b128 v[156:159], v183 offset:1024
	ds_read_b128 v[160:163], v183 offset:2048
	ds_read_b128 v[164:167], v183 offset:3072
	ds_read_b128 v[168:171], v184
	ds_read_b128 v[172:175], v184 offset:1024
	ds_read_b128 v[176:179], v184 offset:2048
	ds_read_b128 v[190:193], v184 offset:3072
	s_add_u32 s48, s46, 0xfffc0080
	s_addc_u32 s49, s47, -1
	s_cmp_eq_u32 s75, 12
	s_cselect_b32 s51, s7, s49
	s_cselect_b32 s50, s39, s48
	s_cselect_b32 s49, s37, s74
	s_cselect_b32 s48, s45, s73
	v_lshl_add_u64 v[226:227], s[46:47], 0, v[144:145]
	s_add_i32 m0, s35, 0xc000
	ds_read_b128 v[194:197], v185
	ds_read_b128 v[198:201], v185 offset:1024
	ds_read_b128 v[202:205], v185 offset:2048
	ds_read_b128 v[206:209], v185 offset:3072
	ds_read_b128 v[210:213], v185 offset:4096
	ds_read_b128 v[214:217], v185 offset:5120
	ds_read_b128 v[218:221], v185 offset:6144
	ds_read_b128 v[222:225], v185 offset:7168
	global_load_lds_dwordx4 v[226:227], off
	v_lshl_add_u64 v[226:227], s[46:47], 0, v[146:147]
	s_add_i32 m0, s35, 0xe000
	s_nop 0
	global_load_lds_dwordx4 v[226:227], off
	s_waitcnt vmcnt(8)
	s_waitcnt lgkmcnt(0)
	s_barrier
	s_setprio 1
	s_waitcnt lgkmcnt(0)
	v_mfma_i32_16x16x64_i8 v[124:127], v[152:155], v[194:197], 0
	v_mfma_i32_16x16x64_i8 v[120:123], v[160:163], v[194:197], 0
	v_mfma_i32_16x16x64_i8 v[116:119], v[152:155], v[202:205], 0
	v_mfma_i32_16x16x64_i8 v[112:115], v[160:163], v[202:205], 0
	v_mfma_i32_16x16x64_i8 v[108:111], v[152:155], v[210:213], 0
	v_mfma_i32_16x16x64_i8 v[104:107], v[160:163], v[210:213], 0
	v_mfma_i32_16x16x64_i8 v[100:103], v[152:155], v[218:221], 0
	v_mfma_i32_16x16x64_i8 v[96:99], v[160:163], v[218:221], 0
	v_mfma_i32_16x16x64_i8 v[124:127], v[156:159], v[198:201], v[124:127]
	v_mfma_i32_16x16x64_i8 v[120:123], v[164:167], v[198:201], v[120:123]
	v_mfma_i32_16x16x64_i8 v[116:119], v[156:159], v[206:209], v[116:119]
	v_mfma_i32_16x16x64_i8 v[112:115], v[164:167], v[206:209], v[112:115]
	v_mfma_i32_16x16x64_i8 v[108:111], v[156:159], v[214:217], v[108:111]
	v_mfma_i32_16x16x64_i8 v[104:107], v[164:167], v[214:217], v[104:107]
	v_mfma_i32_16x16x64_i8 v[100:103], v[156:159], v[222:225], v[100:103]
	v_mfma_i32_16x16x64_i8 v[96:99], v[164:167], v[222:225], v[96:99]
	s_setprio 0
	s_setprio 1
	v_mfma_i32_16x16x64_i8 v[60:63], v[168:171], v[194:197], 0
	v_mfma_i32_16x16x64_i8 v[56:59], v[176:179], v[194:197], 0
	v_mfma_i32_16x16x64_i8 v[52:55], v[168:171], v[202:205], 0
	v_mfma_i32_16x16x64_i8 v[48:51], v[176:179], v[202:205], 0
	v_mfma_i32_16x16x64_i8 v[44:47], v[168:171], v[210:213], 0
	v_mfma_i32_16x16x64_i8 v[40:43], v[176:179], v[210:213], 0
	v_mfma_i32_16x16x64_i8 v[36:39], v[168:171], v[218:221], 0
	v_mfma_i32_16x16x64_i8 v[32:35], v[176:179], v[218:221], 0
	v_mfma_i32_16x16x64_i8 v[60:63], v[172:175], v[198:201], v[60:63]
	v_mfma_i32_16x16x64_i8 v[56:59], v[190:193], v[198:201], v[56:59]
	v_mfma_i32_16x16x64_i8 v[52:55], v[172:175], v[206:209], v[52:55]
	v_mfma_i32_16x16x64_i8 v[48:51], v[190:193], v[206:209], v[48:51]
	v_mfma_i32_16x16x64_i8 v[44:47], v[172:175], v[214:217], v[44:47]
	v_mfma_i32_16x16x64_i8 v[40:43], v[190:193], v[214:217], v[40:43]
	v_mfma_i32_16x16x64_i8 v[36:39], v[172:175], v[222:225], v[36:39]
	v_mfma_i32_16x16x64_i8 v[32:35], v[190:193], v[222:225], v[32:35]
	s_setprio 0
	s_barrier
	s_add_i32 s76, s65, s34
	v_lshl_add_u64 v[226:227], s[48:49], 0, v[130:131]
	s_mov_b32 m0, s76
	ds_read_b128 v[194:197], v185 offset:16384
	ds_read_b128 v[198:201], v185 offset:17408
	ds_read_b128 v[202:205], v185 offset:18432
	ds_read_b128 v[206:209], v185 offset:19456
	ds_read_b128 v[210:213], v185 offset:20480
	ds_read_b128 v[214:217], v185 offset:21504
	ds_read_b128 v[218:221], v185 offset:22528
	ds_read_b128 v[222:225], v185 offset:23552
	global_load_lds_dwordx4 v[226:227], off
	s_add_i32 m0, s76, 0x2000
	s_add_u32 s76, s48, 0x40000
	v_lshl_add_u64 v[228:229], s[48:49], 0, v[134:135]
	s_addc_u32 s77, s49, 0
	s_add_i32 s78, s66, s34
	global_load_lds_dwordx4 v[228:229], off
	v_lshl_add_u64 v[230:231], s[76:77], 0, v[130:131]
	s_mov_b32 m0, s78
	v_lshl_add_u64 v[232:233], s[50:51], 0, v[132:133]
	global_load_lds_dwordx4 v[230:231], off
	v_lshl_add_u64 v[230:231], s[76:77], 0, v[134:135]
	s_add_i32 m0, s78, 0x2000
	s_nop 0
	global_load_lds_dwordx4 v[230:231], off
	v_lshl_add_u64 v[230:231], s[50:51], 0, v[128:129]
	s_mov_b32 m0, s35
	s_nop 0
	global_load_lds_dwordx4 v[230:231], off
	s_mov_b32 m0, s54
	s_nop 0
	global_load_lds_dwordx4 v[232:233], off
	s_waitcnt vmcnt(8)
	s_waitcnt lgkmcnt(0)
	s_barrier
; #define PG8_STAGE(bufoff, gbase, voff) do { _Pragma("unroll") for (int _i = 0; _i < 2; ++_i) \
;         __builtin_amdgcn_global_load_lds((const unsigned*)((const char*)(gbase) + (voff)[_i]), (LAS unsigned*)(lds + (bufoff) + ldsw + _i * 8192), 16, 0, 0); } while (0)
; #define PG8_LDA(dst, b, h) do { _Pragma("unroll") for (int m = 0; m < 4; ++m) _Pragma("unroll") for (int k = 0; k < 2; ++k) dst[m][k] = *(const LAS bf16x8*)(lds + PG8_SA(b, h) + aoff + m * 2048 + k * 1024); } while (0)
; #define PG8_LDB(dst, b, h) do { _Pragma("unroll") for (int n = 0; n < 2; ++n) _Pragma("unroll") for (int k = 0; k < 2; ++k) dst[n][k] = *(const LAS bf16x8*)(lds + PG8_SB(b, h) + boff + n * 2048 + k * 1024); } while (0)
; #define PG8_WAIT_V(n) asm volatile("s_waitcnt vmcnt(" #n ")" ::: "memory")
; #define PG8_WAIT_L(n) asm volatile("s_waitcnt lgkmcnt(" #n ")" ::: "memory")
; #define PG8_BAR __builtin_amdgcn_s_barrier()
; #define PG8_SCHED __builtin_amdgcn_sched_barrier(0)
;     ...
;             PG8_WAIT_V(8); PG8_WAIT_L(0); PG8_BAR; PG8_MMA(1, 0, At, B0); PG8_MMA(1, 1, At, B1); PG8_BAR; PG8_SCHED;
;             PG8_LDB(B0, 1, 0); PG8_LDB(B1, 1, 1); PG8_SCHED; PG8_LDA(At, 1, 0); PG8_STAGE(PG8_SA(0, 1), a2 + hstep, voffA);
;             PG8_WAIT_V(8); PG8_WAIT_L(0); PG8_BAR; PG8_MMA(0, 0, At, B0); PG8_MMA(0, 1, At, B1); PG8_BAR; PG8_SCHED;
	s_setprio 1
	s_waitcnt lgkmcnt(0)
	v_mfma_i32_16x16x64_i8 v[92:95], v[152:155], v[194:197], 0
	v_mfma_i32_16x16x64_i8 v[88:91], v[160:163], v[194:197], 0
	v_mfma_i32_16x16x64_i8 v[84:87], v[152:155], v[202:205], 0
	v_mfma_i32_16x16x64_i8 v[80:83], v[160:163], v[202:205], 0
	v_mfma_i32_16x16x64_i8 v[76:79], v[152:155], v[210:213], 0
	v_mfma_i32_16x16x64_i8 v[72:75], v[160:163], v[210:213], 0
	v_mfma_i32_16x16x64_i8 v[68:71], v[152:155], v[218:221], 0
	v_mfma_i32_16x16x64_i8 v[64:67], v[160:163], v[218:221], 0
	v_mfma_i32_16x16x64_i8 v[92:95], v[156:159], v[198:201], v[92:95]
	v_mfma_i32_16x16x64_i8 v[88:91], v[164:167], v[198:201], v[88:91]
	v_mfma_i32_16x16x64_i8 v[84:87], v[156:159], v[206:209], v[84:87]
	v_mfma_i32_16x16x64_i8 v[80:83], v[164:167], v[206:209], v[80:83]
	v_mfma_i32_16x16x64_i8 v[76:79], v[156:159], v[214:217], v[76:79]
	v_mfma_i32_16x16x64_i8 v[72:75], v[164:167], v[214:217], v[72:75]
	v_mfma_i32_16x16x64_i8 v[68:71], v[156:159], v[222:225], v[68:71]
	v_mfma_i32_16x16x64_i8 v[64:67], v[164:167], v[222:225], v[64:67]
	s_setprio 0
	s_setprio 1
	v_mfma_i32_16x16x64_i8 v[28:31], v[168:171], v[194:197], 0
	v_mfma_i32_16x16x64_i8 v[24:27], v[176:179], v[194:197], 0
	v_mfma_i32_16x16x64_i8 v[20:23], v[168:171], v[202:205], 0
	v_mfma_i32_16x16x64_i8 v[16:19], v[176:179], v[202:205], 0
	v_mfma_i32_16x16x64_i8 v[12:15], v[168:171], v[210:213], 0
	v_mfma_i32_16x16x64_i8 v[8:11], v[176:179], v[210:213], 0
	v_mfma_i32_16x16x64_i8 v[4:7], v[168:171], v[218:221], 0
	v_mfma_i32_16x16x64_i8 v[0:3], v[176:179], v[218:221], 0
	v_mfma_i32_16x16x64_i8 v[28:31], v[172:175], v[198:201], v[28:31]
	v_mfma_i32_16x16x64_i8 v[24:27], v[190:193], v[198:201], v[24:27]
	v_mfma_i32_16x16x64_i8 v[20:23], v[172:175], v[206:209], v[20:23]
	v_mfma_i32_16x16x64_i8 v[16:19], v[190:193], v[206:209], v[16:19]
	v_mfma_i32_16x16x64_i8 v[12:15], v[172:175], v[214:217], v[12:15]
	v_mfma_i32_16x16x64_i8 v[8:11], v[190:193], v[214:217], v[8:11]
	v_mfma_i32_16x16x64_i8 v[4:7], v[172:175], v[222:225], v[4:7]
	v_mfma_i32_16x16x64_i8 v[0:3], v[190:193], v[222:225], v[0:3]
	s_setprio 0
	s_barrier
	s_add_i32 s76, 0, 0x18000
	v_add_u32_e32 v136, s76, v181
	s_add_i32 s77, 0, 0x1c000
	ds_read_b128 v[152:155], v136
	ds_read_b128 v[156:159], v136 offset:1024
	ds_read_b128 v[160:163], v136 offset:2048
	ds_read_b128 v[164:167], v136 offset:3072
	v_add_u32_e32 v136, s77, v181
	ds_read_b128 v[168:171], v136
	ds_read_b128 v[172:175], v136 offset:1024
	ds_read_b128 v[176:179], v136 offset:2048
	ds_read_b128 v[190:193], v136 offset:3072
	s_add_u32 s50, s50, 0x40000
	s_addc_u32 s51, s51, 0
	s_mov_b32 m0, s55
	v_lshl_add_u64 v[234:235], s[50:51], 0, v[128:129]
	ds_read_b128 v[194:197], v185 offset:32768
	ds_read_b128 v[198:201], v185 offset:33792
	ds_read_b128 v[202:205], v185 offset:34816
	ds_read_b128 v[206:209], v185 offset:35840
	ds_read_b128 v[210:213], v185 offset:36864
	ds_read_b128 v[214:217], v185 offset:37888
	ds_read_b128 v[218:221], v185 offset:38912
	ds_read_b128 v[222:225], v185 offset:39936
	global_load_lds_dwordx4 v[234:235], off
	v_lshl_add_u64 v[234:235], s[50:51], 0, v[132:133]
	s_mov_b32 m0, s58
	s_nop 0
	global_load_lds_dwordx4 v[234:235], off
	s_waitcnt vmcnt(8)
	s_waitcnt lgkmcnt(0)
	s_barrier
	s_setprio 1
	s_waitcnt lgkmcnt(0)
	v_mfma_i32_16x16x64_i8 v[124:127], v[152:155], v[194:197], v[124:127]
	v_mfma_i32_16x16x64_i8 v[120:123], v[160:163], v[194:197], v[120:123]
	v_mfma_i32_16x16x64_i8 v[116:119], v[152:155], v[202:205], v[116:119]
	v_mfma_i32_16x16x64_i8 v[112:115], v[160:163], v[202:205], v[112:115]
	v_mfma_i32_16x16x64_i8 v[108:111], v[152:155], v[210:213], v[108:111]
	v_mfma_i32_16x16x64_i8 v[104:107], v[160:163], v[210:213], v[104:107]
	v_mfma_i32_16x16x64_i8 v[100:103], v[152:155], v[218:221], v[100:103]
	v_mfma_i32_16x16x64_i8 v[96:99], v[160:163], v[218:221], v[96:99]
	v_mfma_i32_16x16x64_i8 v[124:127], v[156:159], v[198:201], v[124:127]
	v_mfma_i32_16x16x64_i8 v[120:123], v[164:167], v[198:201], v[120:123]
	v_mfma_i32_16x16x64_i8 v[116:119], v[156:159], v[206:209], v[116:119]
	v_mfma_i32_16x16x64_i8 v[112:115], v[164:167], v[206:209], v[112:115]
	v_mfma_i32_16x16x64_i8 v[108:111], v[156:159], v[214:217], v[108:111]
	v_mfma_i32_16x16x64_i8 v[104:107], v[164:167], v[214:217], v[104:107]
	v_mfma_i32_16x16x64_i8 v[100:103], v[156:159], v[222:225], v[100:103]
	v_mfma_i32_16x16x64_i8 v[96:99], v[164:167], v[222:225], v[96:99]
	s_setprio 0
	s_setprio 1
	v_mfma_i32_16x16x64_i8 v[60:63], v[168:171], v[194:197], v[60:63]
	v_mfma_i32_16x16x64_i8 v[56:59], v[176:179], v[194:197], v[56:59]
	v_mfma_i32_16x16x64_i8 v[52:55], v[168:171], v[202:205], v[52:55]
	v_mfma_i32_16x16x64_i8 v[48:51], v[176:179], v[202:205], v[48:51]
	v_mfma_i32_16x16x64_i8 v[44:47], v[168:171], v[210:213], v[44:47]
	v_mfma_i32_16x16x64_i8 v[40:43], v[176:179], v[210:213], v[40:43]
	v_mfma_i32_16x16x64_i8 v[36:39], v[168:171], v[218:221], v[36:39]
	v_mfma_i32_16x16x64_i8 v[32:35], v[176:179], v[218:221], v[32:35]
	v_mfma_i32_16x16x64_i8 v[60:63], v[172:175], v[198:201], v[60:63]
	v_mfma_i32_16x16x64_i8 v[56:59], v[190:193], v[198:201], v[56:59]
	v_mfma_i32_16x16x64_i8 v[52:55], v[172:175], v[206:209], v[52:55]
	v_mfma_i32_16x16x64_i8 v[48:51], v[190:193], v[206:209], v[48:51]
	v_mfma_i32_16x16x64_i8 v[44:47], v[172:175], v[214:217], v[44:47]
	v_mfma_i32_16x16x64_i8 v[40:43], v[190:193], v[214:217], v[40:43]
	v_mfma_i32_16x16x64_i8 v[36:39], v[172:175], v[222:225], v[36:39]
	v_mfma_i32_16x16x64_i8 v[32:35], v[190:193], v[222:225], v[32:35]
	s_setprio 0
	s_barrier
; #define PG8_STAGE(bufoff, gbase, voff) do { _Pragma("unroll") for (int _i = 0; _i < 2; ++_i) \
;         __builtin_amdgcn_global_load_lds((const unsigned*)((const char*)(gbase) + (voff)[_i]), (LAS unsigned*)(lds + (bufoff) + ldsw + _i * 8192), 16, 0, 0); } while (0)
; #define PG8_LDA(dst, b, h) do { _Pragma("unroll") for (int m = 0; m < 4; ++m) _Pragma("unroll") for (int k = 0; k < 2; ++k) dst[m][k] = *(const LAS bf16x8*)(lds + PG8_SA(b, h) + aoff + m * 2048 + k * 1024); } while (0)
; #define PG8_WAIT_V(n) asm volatile("s_waitcnt vmcnt(" #n ")" ::: "memory")
; #define PG8_WAIT_L(n) asm volatile("s_waitcnt lgkmcnt(" #n ")" ::: "memory")
; #define PG8_BAR __builtin_amdgcn_s_barrier()
; #define PG8_SCHED __builtin_amdgcn_sched_barrier(0)
;     ...
;             PG8_LDA(At, 1, 1); PG8_STAGE(PG8_SB(1, 0), b3, voffB); PG8_STAGE(PG8_SB(1, 1), b3 + hstep, voffB); PG8_STAGE(PG8_SA(1, 0), a3, voffA);
;             PG8_WAIT_V(8); PG8_WAIT_L(0); PG8_BAR; PG8_MMA(1, 0, At, B0); PG8_MMA(1, 1, At, B1); PG8_BAR; PG8_SCHED;
;         }
	s_add_i32 s50, s76, s34
	v_lshl_add_u64 v[226:227], v[226:227], 0, s[18:19]
	s_mov_b32 m0, s50
	ds_read_b128 v[194:197], v185 offset:49152
	ds_read_b128 v[198:201], v185 offset:50176
	ds_read_b128 v[202:205], v185 offset:51200
	ds_read_b128 v[206:209], v185 offset:52224
	ds_read_b128 v[210:213], v185 offset:53248
	ds_read_b128 v[214:217], v185 offset:54272
	ds_read_b128 v[218:221], v185 offset:55296
	ds_read_b128 v[222:225], v185 offset:56320
	global_load_lds_dwordx4 v[226:227], off
	s_add_i32 m0, s50, 0x2000
	s_add_u32 s48, s48, 0x40080
	v_lshl_add_u64 v[226:227], v[228:229], 0, s[18:19]
	s_addc_u32 s49, s49, 0
	s_add_i32 s50, s77, s34
	global_load_lds_dwordx4 v[226:227], off
	v_lshl_add_u64 v[226:227], s[48:49], 0, v[130:131]
	s_mov_b32 m0, s50
	s_nop 0
	global_load_lds_dwordx4 v[226:227], off
	v_lshl_add_u64 v[226:227], s[48:49], 0, v[134:135]
	s_add_i32 m0, s50, 0x2000
	s_nop 0
	global_load_lds_dwordx4 v[226:227], off
	v_lshl_add_u64 v[226:227], v[230:231], 0, s[18:19]
	s_mov_b32 m0, s61
	s_nop 0
	global_load_lds_dwordx4 v[226:227], off
	v_lshl_add_u64 v[226:227], v[232:233], 0, s[18:19]
	s_mov_b32 m0, s62
	s_nop 0
	global_load_lds_dwordx4 v[226:227], off
	s_waitcnt vmcnt(8)
	s_waitcnt lgkmcnt(0)
	s_barrier
	s_setprio 1
	s_waitcnt lgkmcnt(0)
	v_mfma_i32_16x16x64_i8 v[92:95], v[152:155], v[194:197], v[92:95]
	v_mfma_i32_16x16x64_i8 v[88:91], v[160:163], v[194:197], v[88:91]
	v_mfma_i32_16x16x64_i8 v[84:87], v[152:155], v[202:205], v[84:87]
	v_mfma_i32_16x16x64_i8 v[80:83], v[160:163], v[202:205], v[80:83]
	v_mfma_i32_16x16x64_i8 v[76:79], v[152:155], v[210:213], v[76:79]
	v_mfma_i32_16x16x64_i8 v[72:75], v[160:163], v[210:213], v[72:75]
	v_mfma_i32_16x16x64_i8 v[68:71], v[152:155], v[218:221], v[68:71]
	v_mfma_i32_16x16x64_i8 v[64:67], v[160:163], v[218:221], v[64:67]
	v_mfma_i32_16x16x64_i8 v[92:95], v[156:159], v[198:201], v[92:95]
	v_mfma_i32_16x16x64_i8 v[88:91], v[164:167], v[198:201], v[88:91]
	v_mfma_i32_16x16x64_i8 v[84:87], v[156:159], v[206:209], v[84:87]
	v_mfma_i32_16x16x64_i8 v[80:83], v[164:167], v[206:209], v[80:83]
	v_mfma_i32_16x16x64_i8 v[76:79], v[156:159], v[214:217], v[76:79]
	v_mfma_i32_16x16x64_i8 v[72:75], v[164:167], v[214:217], v[72:75]
	v_mfma_i32_16x16x64_i8 v[68:71], v[156:159], v[222:225], v[68:71]
	v_mfma_i32_16x16x64_i8 v[64:67], v[164:167], v[222:225], v[64:67]
	s_setprio 0
	s_setprio 1
	v_mfma_i32_16x16x64_i8 v[28:31], v[168:171], v[194:197], v[28:31]
	v_mfma_i32_16x16x64_i8 v[24:27], v[176:179], v[194:197], v[24:27]
	v_mfma_i32_16x16x64_i8 v[20:23], v[168:171], v[202:205], v[20:23]
	v_mfma_i32_16x16x64_i8 v[16:19], v[176:179], v[202:205], v[16:19]
	v_mfma_i32_16x16x64_i8 v[12:15], v[168:171], v[210:213], v[12:15]
	v_mfma_i32_16x16x64_i8 v[8:11], v[176:179], v[210:213], v[8:11]
	v_mfma_i32_16x16x64_i8 v[4:7], v[168:171], v[218:221], v[4:7]
	v_mfma_i32_16x16x64_i8 v[0:3], v[176:179], v[218:221], v[0:3]
	v_mfma_i32_16x16x64_i8 v[28:31], v[172:175], v[198:201], v[28:31]
	v_mfma_i32_16x16x64_i8 v[24:27], v[190:193], v[198:201], v[24:27]
	v_mfma_i32_16x16x64_i8 v[20:23], v[172:175], v[206:209], v[20:23]
	v_mfma_i32_16x16x64_i8 v[16:19], v[190:193], v[206:209], v[16:19]
	v_mfma_i32_16x16x64_i8 v[12:15], v[172:175], v[214:217], v[12:15]
	v_mfma_i32_16x16x64_i8 v[8:11], v[190:193], v[214:217], v[8:11]
	v_mfma_i32_16x16x64_i8 v[4:7], v[172:175], v[222:225], v[4:7]
	v_mfma_i32_16x16x64_i8 v[0:3], v[190:193], v[222:225], v[0:3]
	s_setprio 0
	s_barrier
	s_add_i32 s75, s75, 2
	s_add_u32 s46, s46, 0x100
	s_addc_u32 s47, s47, 0
	s_add_u32 s73, s73, 0x100
	s_addc_u32 s74, s74, 0
	s_cmp_gt_u32 s75, 13
	s_cbranch_scc0 .LBB0_3955

; #define PG8_STAGE(bufoff, gbase, voff) do { _Pragma("unroll") for (int _i = 0; _i < 2; ++_i) \
;         __builtin_amdgcn_global_load_lds((const unsigned*)((const char*)(gbase) + (voff)[_i]), (LAS unsigned*)(lds + (bufoff) + ldsw + _i * 8192), 16, 0, 0); } while (0)
; #define PG8_LDA(dst, b, h) do { _Pragma("unroll") for (int m = 0; m < 4; ++m) _Pragma("unroll") for (int k = 0; k < 2; ++k) dst[m][k] = *(const LAS bf16x8*)(lds + PG8_SA(b, h) + aoff + m * 2048 + k * 1024); } while (0)
; #define PG8_LDB(dst, b, h) do { _Pragma("unroll") for (int n = 0; n < 2; ++n) _Pragma("unroll") for (int k = 0; k < 2; ++k) dst[n][k] = *(const LAS bf16x8*)(lds + PG8_SB(b, h) + boff + n * 2048 + k * 1024); } while (0)
; #define PG8_WAIT_V(n) asm volatile("s_waitcnt vmcnt(" #n ")" ::: "memory")
; #define PG8_WAIT_L(n) asm volatile("s_waitcnt lgkmcnt(" #n ")" ::: "memory")
; #define PG8_BAR __builtin_amdgcn_s_barrier()
; #define PG8_SCHED __builtin_amdgcn_sched_barrier(0)
;     ...
;         const char* nA = has_next ? (const char*)g.A + (size_t)nxt.pm * tstep + (size_t)nxt.kt0 * kstep : cA; const char* nB = has_next ? (const char*)g.Bt + (size_t)nxt.e * g.estride + (size_t)nxt.pn * tstep + (size_t)nxt.kt0 * kstep : cB;
;         const int nt = cur.nkt;
;         for (int t = 0; t < nt; t += 2) {
;             const bool last = (t == nt - 2);
;             const char* a1 = cA + (size_t)(t + 1) * kstep;
;             const char* a2 = last ? nA : cA + (size_t)(t + 2) * kstep; const char* b2 = last ? nB : cB + (size_t)(t + 2) * kstep;
;             const char* a3 = a2 + kstep; const char* b3 = b2 + kstep;
;             PG8_LDB(B0, 0, 0); PG8_LDB(B1, 0, 1); PG8_SCHED; PG8_LDA(At, 0, 0); PG8_STAGE(PG8_SA(1, 1), a1 + hstep, voffA);
;             PG8_WAIT_V(8); PG8_WAIT_L(0); PG8_BAR; PG8_MMA(0, 0, At, B0); PG8_MMA(0, 1, At, B1); PG8_BAR; PG8_SCHED;
;             PG8_LDA(At, 0, 1); PG8_STAGE(PG8_SB(0, 0), b2, voffB); PG8_STAGE(PG8_SB(0, 1), b2 + hstep, voffB); PG8_STAGE(PG8_SA(0, 0), a2, voffA);
;             PG8_WAIT_V(8); PG8_WAIT_L(0); PG8_BAR; PG8_MMA(1, 0, At, B0); PG8_MMA(1, 1, At, B1); PG8_BAR; PG8_SCHED;
.LBB0_4053:
	s_ashr_i32 s31, s30, 31
	s_lshl_b64 s[36:37], s[30:31], 17
	s_add_u32 s36, s34, s36
	s_addc_u32 s37, s35, s37
	s_and_b64 s[38:39], s[2:3], exec
	s_cselect_b32 s5, s37, s41
	s_cselect_b32 s31, s36, s40
	s_ashr_i32 s29, s28, 31
	s_lshl_b64 s[38:39], s[28:29], 17
	s_add_u32 s38, s55, s38
	s_addc_u32 s39, s64, s39
	s_and_b64 s[44:45], s[2:3], exec
	s_cselect_b32 s29, s39, s7
	s_cselect_b32 s43, s38, s6
	s_mov_b32 s48, 0
	s_mov_b64 s[44:45], -1
	s_mov_b64 s[46:47], 0
	s_add_u32 s49, s40, s48
	s_addc_u32 s60, s41, 0
	s_add_u32 s58, s49, 0x100
	s_addc_u32 s59, s60, 0
	s_and_b64 s[50:51], s[46:47], exec
	s_cselect_b32 s51, s5, s59
	s_cselect_b32 s50, s31, s58
	s_add_u32 s48, s6, s48
	s_addc_u32 s58, s7, 0
	s_add_u32 s48, s48, 0x100
	s_addc_u32 s58, s58, 0
	s_and_b64 s[46:47], s[46:47], exec
	s_cselect_b32 s59, s29, s58
	s_cselect_b32 s58, s43, s48
	s_add_u32 s62, s49, 0x10080
	s_addc_u32 s63, s60, 0
	s_add_i32 s89, s78, s65
	s_add_i32 m0, s66, 0xc000
	s_add_i32 s92, s66, 0xe000
	s_add_i32 s86, s89, 0x2000
	v_add_u32_e32 v136, s78, v160
	s_add_u32 s60, s58, 0x10000
	ds_read_b128 v[152:155], v136
	ds_read_b128 v[156:159], v136 offset:1024
	ds_read_b128 v[164:167], v136 offset:2048
	ds_read_b128 v[168:171], v136 offset:3072
	v_add_u32_e32 v136, s79, v160
	s_addc_u32 s61, s59, 0
	s_add_i32 s88, s79, s65
	ds_read_b128 v[172:175], v136
	ds_read_b128 v[176:179], v136 offset:1024
	ds_read_b128 v[180:183], v136 offset:2048
	ds_read_b128 v[184:187], v136 offset:3072
	s_add_i32 s87, s88, 0x2000
	s_add_i32 s85, 0, 0x18000
	s_add_i32 s84, 0, 0x1c000
	s_add_u32 s48, s50, 0x10000
	s_addc_u32 s49, s51, 0
	s_add_i32 s83, s85, s65
	s_add_i32 s82, s83, 0x2000
	s_add_u32 s46, s58, 0x10080
	s_addc_u32 s47, s59, 0
	s_add_i32 s91, s84, s65
	s_add_i32 s90, s91, 0x2000
	v_lshl_add_u64 v[220:221], s[62:63], 0, v[128:129]
	ds_read_b128 v[188:191], v161
	ds_read_b128 v[192:195], v161 offset:1024
	ds_read_b128 v[196:199], v161 offset:2048
	ds_read_b128 v[200:203], v161 offset:3072
	ds_read_b128 v[204:207], v161 offset:4096
	ds_read_b128 v[208:211], v161 offset:5120
	ds_read_b128 v[212:215], v161 offset:6144
	ds_read_b128 v[216:219], v161 offset:7168
	global_load_lds_dwordx4 v[220:221], off
	v_lshl_add_u64 v[220:221], s[62:63], 0, v[132:133]
	s_mov_b32 m0, s92
	s_nop 0
	global_load_lds_dwordx4 v[220:221], off
	s_waitcnt vmcnt(8)
	s_waitcnt lgkmcnt(0)
	s_barrier
	s_setprio 1
	s_waitcnt lgkmcnt(0)
	v_mfma_i32_16x16x64_i8 v[124:127], v[152:155], v[188:191], 0
	v_mfma_i32_16x16x64_i8 v[120:123], v[164:167], v[188:191], 0
	v_mfma_i32_16x16x64_i8 v[108:111], v[152:155], v[196:199], 0
	v_mfma_i32_16x16x64_i8 v[104:107], v[164:167], v[196:199], 0
	v_mfma_i32_16x16x64_i8 v[92:95], v[152:155], v[204:207], 0
	v_mfma_i32_16x16x64_i8 v[88:91], v[164:167], v[204:207], 0
	v_mfma_i32_16x16x64_i8 v[76:79], v[152:155], v[212:215], 0
	v_mfma_i32_16x16x64_i8 v[72:75], v[164:167], v[212:215], 0
	v_mfma_i32_16x16x64_i8 v[124:127], v[156:159], v[192:195], v[124:127]
	v_mfma_i32_16x16x64_i8 v[120:123], v[168:171], v[192:195], v[120:123]
	v_mfma_i32_16x16x64_i8 v[108:111], v[156:159], v[200:203], v[108:111]
	v_mfma_i32_16x16x64_i8 v[104:107], v[168:171], v[200:203], v[104:107]
	v_mfma_i32_16x16x64_i8 v[92:95], v[156:159], v[208:211], v[92:95]
	v_mfma_i32_16x16x64_i8 v[88:91], v[168:171], v[208:211], v[88:91]
	v_mfma_i32_16x16x64_i8 v[76:79], v[156:159], v[216:219], v[76:79]
	v_mfma_i32_16x16x64_i8 v[72:75], v[168:171], v[216:219], v[72:75]
	s_setprio 0
	s_setprio 1
	v_mfma_i32_16x16x64_i8 v[116:119], v[172:175], v[188:191], 0
	v_mfma_i32_16x16x64_i8 v[112:115], v[180:183], v[188:191], 0
	v_mfma_i32_16x16x64_i8 v[100:103], v[172:175], v[196:199], 0
	v_mfma_i32_16x16x64_i8 v[96:99], v[180:183], v[196:199], 0
	v_mfma_i32_16x16x64_i8 v[84:87], v[172:175], v[204:207], 0
	v_mfma_i32_16x16x64_i8 v[80:83], v[180:183], v[204:207], 0
	v_mfma_i32_16x16x64_i8 v[68:71], v[172:175], v[212:215], 0
	v_mfma_i32_16x16x64_i8 v[64:67], v[180:183], v[212:215], 0
	v_mfma_i32_16x16x64_i8 v[116:119], v[176:179], v[192:195], v[116:119]
	v_mfma_i32_16x16x64_i8 v[112:115], v[184:187], v[192:195], v[112:115]
	v_mfma_i32_16x16x64_i8 v[100:103], v[176:179], v[200:203], v[100:103]
	v_mfma_i32_16x16x64_i8 v[96:99], v[184:187], v[200:203], v[96:99]
	v_mfma_i32_16x16x64_i8 v[84:87], v[176:179], v[208:211], v[84:87]
	v_mfma_i32_16x16x64_i8 v[80:83], v[184:187], v[208:211], v[80:83]
	v_mfma_i32_16x16x64_i8 v[68:71], v[176:179], v[216:219], v[68:71]
	v_mfma_i32_16x16x64_i8 v[64:67], v[184:187], v[216:219], v[64:67]
	s_setprio 0
	s_barrier
	s_mov_b32 m0, s89
	v_lshl_add_u64 v[220:221], s[58:59], 0, v[130:131]
	ds_read_b128 v[188:191], v161 offset:16384
	ds_read_b128 v[192:195], v161 offset:17408
	ds_read_b128 v[196:199], v161 offset:18432
	ds_read_b128 v[200:203], v161 offset:19456
	ds_read_b128 v[204:207], v161 offset:20480
	ds_read_b128 v[208:211], v161 offset:21504
	ds_read_b128 v[212:215], v161 offset:22528
	ds_read_b128 v[216:219], v161 offset:23552
	global_load_lds_dwordx4 v[220:221], off
	v_lshl_add_u64 v[222:223], s[58:59], 0, v[134:135]
	s_mov_b32 m0, s86
	v_lshl_add_u64 v[224:225], s[60:61], 0, v[130:131]
	global_load_lds_dwordx4 v[222:223], off
	s_mov_b32 m0, s88
	v_lshl_add_u64 v[226:227], s[50:51], 0, v[132:133]
	global_load_lds_dwordx4 v[224:225], off
	v_lshl_add_u64 v[224:225], s[60:61], 0, v[134:135]
	s_mov_b32 m0, s87
	s_nop 0
	global_load_lds_dwordx4 v[224:225], off
	v_lshl_add_u64 v[224:225], s[50:51], 0, v[128:129]
	s_mov_b32 m0, s66
	s_nop 0
	global_load_lds_dwordx4 v[224:225], off
	s_mov_b32 m0, s67
	s_nop 0
	global_load_lds_dwordx4 v[226:227], off
	s_waitcnt vmcnt(8)
	s_waitcnt lgkmcnt(0)
	s_barrier
; #define PG8_STAGE(bufoff, gbase, voff) do { _Pragma("unroll") for (int _i = 0; _i < 2; ++_i) \
;         __builtin_amdgcn_global_load_lds((const unsigned*)((const char*)(gbase) + (voff)[_i]), (LAS unsigned*)(lds + (bufoff) + ldsw + _i * 8192), 16, 0, 0); } while (0)
; #define PG8_LDA(dst, b, h) do { _Pragma("unroll") for (int m = 0; m < 4; ++m) _Pragma("unroll") for (int k = 0; k < 2; ++k) dst[m][k] = *(const LAS bf16x8*)(lds + PG8_SA(b, h) + aoff + m * 2048 + k * 1024); } while (0)
; #define PG8_LDB(dst, b, h) do { _Pragma("unroll") for (int n = 0; n < 2; ++n) _Pragma("unroll") for (int k = 0; k < 2; ++k) dst[n][k] = *(const LAS bf16x8*)(lds + PG8_SB(b, h) + boff + n * 2048 + k * 1024); } while (0)
; #define PG8_WAIT_V(n) asm volatile("s_waitcnt vmcnt(" #n ")" ::: "memory")
; #define PG8_WAIT_L(n) asm volatile("s_waitcnt lgkmcnt(" #n ")" ::: "memory")
; #define PG8_BAR __builtin_amdgcn_s_barrier()
; #define PG8_SCHED __builtin_amdgcn_sched_barrier(0)
;     ...
;             PG8_WAIT_V(8); PG8_WAIT_L(0); PG8_BAR; PG8_MMA(1, 0, At, B0); PG8_MMA(1, 1, At, B1); PG8_BAR; PG8_SCHED;
;             PG8_LDB(B0, 1, 0); PG8_LDB(B1, 1, 1); PG8_SCHED; PG8_LDA(At, 1, 0); PG8_STAGE(PG8_SA(0, 1), a2 + hstep, voffA);
;             PG8_WAIT_V(8); PG8_WAIT_L(0); PG8_BAR; PG8_MMA(0, 0, At, B0); PG8_MMA(0, 1, At, B1); PG8_BAR; PG8_SCHED;
	s_setprio 1
	s_waitcnt lgkmcnt(0)
	v_mfma_i32_16x16x64_i8 v[60:63], v[152:155], v[188:191], 0
	v_mfma_i32_16x16x64_i8 v[56:59], v[164:167], v[188:191], 0
	v_mfma_i32_16x16x64_i8 v[44:47], v[152:155], v[196:199], 0
	v_mfma_i32_16x16x64_i8 v[40:43], v[164:167], v[196:199], 0
	v_mfma_i32_16x16x64_i8 v[28:31], v[152:155], v[204:207], 0
	v_mfma_i32_16x16x64_i8 v[24:27], v[164:167], v[204:207], 0
	v_mfma_i32_16x16x64_i8 v[12:15], v[152:155], v[212:215], 0
	v_mfma_i32_16x16x64_i8 v[8:11], v[164:167], v[212:215], 0
	v_mfma_i32_16x16x64_i8 v[60:63], v[156:159], v[192:195], v[60:63]
	v_mfma_i32_16x16x64_i8 v[56:59], v[168:171], v[192:195], v[56:59]
	v_mfma_i32_16x16x64_i8 v[44:47], v[156:159], v[200:203], v[44:47]
	v_mfma_i32_16x16x64_i8 v[40:43], v[168:171], v[200:203], v[40:43]
	v_mfma_i32_16x16x64_i8 v[28:31], v[156:159], v[208:211], v[28:31]
	v_mfma_i32_16x16x64_i8 v[24:27], v[168:171], v[208:211], v[24:27]
	v_mfma_i32_16x16x64_i8 v[12:15], v[156:159], v[216:219], v[12:15]
	v_mfma_i32_16x16x64_i8 v[8:11], v[168:171], v[216:219], v[8:11]
	s_setprio 0
	s_setprio 1
	v_mfma_i32_16x16x64_i8 v[52:55], v[172:175], v[188:191], 0
	v_mfma_i32_16x16x64_i8 v[48:51], v[180:183], v[188:191], 0
	v_mfma_i32_16x16x64_i8 v[36:39], v[172:175], v[196:199], 0
	v_mfma_i32_16x16x64_i8 v[32:35], v[180:183], v[196:199], 0
	v_mfma_i32_16x16x64_i8 v[20:23], v[172:175], v[204:207], 0
	v_mfma_i32_16x16x64_i8 v[16:19], v[180:183], v[204:207], 0
	v_mfma_i32_16x16x64_i8 v[4:7], v[172:175], v[212:215], 0
	v_mfma_i32_16x16x64_i8 v[0:3], v[180:183], v[212:215], 0
	v_mfma_i32_16x16x64_i8 v[52:55], v[176:179], v[192:195], v[52:55]
	v_mfma_i32_16x16x64_i8 v[48:51], v[184:187], v[192:195], v[48:51]
	v_mfma_i32_16x16x64_i8 v[36:39], v[176:179], v[200:203], v[36:39]
	v_mfma_i32_16x16x64_i8 v[32:35], v[184:187], v[200:203], v[32:35]
	v_mfma_i32_16x16x64_i8 v[20:23], v[176:179], v[208:211], v[20:23]
	v_mfma_i32_16x16x64_i8 v[16:19], v[184:187], v[208:211], v[16:19]
	v_mfma_i32_16x16x64_i8 v[4:7], v[176:179], v[216:219], v[4:7]
	v_mfma_i32_16x16x64_i8 v[0:3], v[184:187], v[216:219], v[0:3]
	s_setprio 0
	s_barrier
	v_add_u32_e32 v136, s85, v160
	ds_read_b128 v[152:155], v136
	ds_read_b128 v[156:159], v136 offset:1024
	ds_read_b128 v[164:167], v136 offset:2048
	ds_read_b128 v[168:171], v136 offset:3072
	v_add_u32_e32 v136, s84, v160
	ds_read_b128 v[172:175], v136
	ds_read_b128 v[176:179], v136 offset:1024
	ds_read_b128 v[180:183], v136 offset:2048
	ds_read_b128 v[184:187], v136 offset:3072
	s_mov_b32 m0, s68
	v_lshl_add_u64 v[228:229], s[48:49], 0, v[128:129]
	ds_read_b128 v[188:191], v161 offset:32768
	ds_read_b128 v[192:195], v161 offset:33792
	ds_read_b128 v[196:199], v161 offset:34816
	ds_read_b128 v[200:203], v161 offset:35840
	ds_read_b128 v[204:207], v161 offset:36864
	ds_read_b128 v[208:211], v161 offset:37888
	ds_read_b128 v[212:215], v161 offset:38912
	ds_read_b128 v[216:219], v161 offset:39936
	global_load_lds_dwordx4 v[228:229], off
	v_lshl_add_u64 v[228:229], s[48:49], 0, v[132:133]
	s_mov_b32 m0, s69
	s_nop 0
	global_load_lds_dwordx4 v[228:229], off
	s_waitcnt vmcnt(8)
	s_waitcnt lgkmcnt(0)
	s_barrier
	s_setprio 1
	s_waitcnt lgkmcnt(0)
	v_mfma_i32_16x16x64_i8 v[124:127], v[152:155], v[188:191], v[124:127]
	v_mfma_i32_16x16x64_i8 v[120:123], v[164:167], v[188:191], v[120:123]
	v_mfma_i32_16x16x64_i8 v[108:111], v[152:155], v[196:199], v[108:111]
	v_mfma_i32_16x16x64_i8 v[104:107], v[164:167], v[196:199], v[104:107]
	v_mfma_i32_16x16x64_i8 v[92:95], v[152:155], v[204:207], v[92:95]
	v_mfma_i32_16x16x64_i8 v[88:91], v[164:167], v[204:207], v[88:91]
	v_mfma_i32_16x16x64_i8 v[76:79], v[152:155], v[212:215], v[76:79]
	v_mfma_i32_16x16x64_i8 v[72:75], v[164:167], v[212:215], v[72:75]
	v_mfma_i32_16x16x64_i8 v[124:127], v[156:159], v[192:195], v[124:127]
	v_mfma_i32_16x16x64_i8 v[120:123], v[168:171], v[192:195], v[120:123]
	v_mfma_i32_16x16x64_i8 v[108:111], v[156:159], v[200:203], v[108:111]
	v_mfma_i32_16x16x64_i8 v[104:107], v[168:171], v[200:203], v[104:107]
	v_mfma_i32_16x16x64_i8 v[92:95], v[156:159], v[208:211], v[92:95]
	v_mfma_i32_16x16x64_i8 v[88:91], v[168:171], v[208:211], v[88:91]
	v_mfma_i32_16x16x64_i8 v[76:79], v[156:159], v[216:219], v[76:79]
	v_mfma_i32_16x16x64_i8 v[72:75], v[168:171], v[216:219], v[72:75]
	s_setprio 0
	s_setprio 1
	v_mfma_i32_16x16x64_i8 v[116:119], v[172:175], v[188:191], v[116:119]
	v_mfma_i32_16x16x64_i8 v[112:115], v[180:183], v[188:191], v[112:115]
	v_mfma_i32_16x16x64_i8 v[100:103], v[172:175], v[196:199], v[100:103]
	v_mfma_i32_16x16x64_i8 v[96:99], v[180:183], v[196:199], v[96:99]
	v_mfma_i32_16x16x64_i8 v[84:87], v[172:175], v[204:207], v[84:87]
	v_mfma_i32_16x16x64_i8 v[80:83], v[180:183], v[204:207], v[80:83]
	v_mfma_i32_16x16x64_i8 v[68:71], v[172:175], v[212:215], v[68:71]
	v_mfma_i32_16x16x64_i8 v[64:67], v[180:183], v[212:215], v[64:67]
	v_mfma_i32_16x16x64_i8 v[116:119], v[176:179], v[192:195], v[116:119]
	v_mfma_i32_16x16x64_i8 v[112:115], v[184:187], v[192:195], v[112:115]
	v_mfma_i32_16x16x64_i8 v[100:103], v[176:179], v[200:203], v[100:103]
	v_mfma_i32_16x16x64_i8 v[96:99], v[184:187], v[200:203], v[96:99]
	v_mfma_i32_16x16x64_i8 v[84:87], v[176:179], v[208:211], v[84:87]
	v_mfma_i32_16x16x64_i8 v[80:83], v[184:187], v[208:211], v[80:83]
	v_mfma_i32_16x16x64_i8 v[68:71], v[176:179], v[216:219], v[68:71]
	v_mfma_i32_16x16x64_i8 v[64:67], v[184:187], v[216:219], v[64:67]
	s_setprio 0
	s_barrier
; #define PG8_STAGE(bufoff, gbase, voff) do { _Pragma("unroll") for (int _i = 0; _i < 2; ++_i) \
;         __builtin_amdgcn_global_load_lds((const unsigned*)((const char*)(gbase) + (voff)[_i]), (LAS unsigned*)(lds + (bufoff) + ldsw + _i * 8192), 16, 0, 0); } while (0)
; #define PG8_LDA(dst, b, h) do { _Pragma("unroll") for (int m = 0; m < 4; ++m) _Pragma("unroll") for (int k = 0; k < 2; ++k) dst[m][k] = *(const LAS bf16x8*)(lds + PG8_SA(b, h) + aoff + m * 2048 + k * 1024); } while (0)
; #define PG8_WAIT_V(n) asm volatile("s_waitcnt vmcnt(" #n ")" ::: "memory")
; #define PG8_WAIT_L(n) asm volatile("s_waitcnt lgkmcnt(" #n ")" ::: "memory")
; #define PG8_BAR __builtin_amdgcn_s_barrier()
; #define PG8_SCHED __builtin_amdgcn_sched_barrier(0)
;     ...
;             PG8_LDA(At, 1, 1); PG8_STAGE(PG8_SB(1, 0), b3, voffB); PG8_STAGE(PG8_SB(1, 1), b3 + hstep, voffB); PG8_STAGE(PG8_SA(1, 0), a3, voffA);
;             PG8_WAIT_V(8); PG8_WAIT_L(0); PG8_BAR; PG8_MMA(1, 0, At, B0); PG8_MMA(1, 1, At, B1); PG8_BAR; PG8_SCHED;
;         }
	s_mov_b32 m0, s83
	v_lshl_add_u64 v[220:221], v[220:221], 0, s[14:15]
	ds_read_b128 v[188:191], v161 offset:49152
	ds_read_b128 v[192:195], v161 offset:50176
	ds_read_b128 v[196:199], v161 offset:51200
	ds_read_b128 v[200:203], v161 offset:52224
	ds_read_b128 v[204:207], v161 offset:53248
	ds_read_b128 v[208:211], v161 offset:54272
	ds_read_b128 v[212:215], v161 offset:55296
	ds_read_b128 v[216:219], v161 offset:56320
	global_load_lds_dwordx4 v[220:221], off
	v_lshl_add_u64 v[220:221], v[222:223], 0, s[14:15]
	s_mov_b32 m0, s82
	s_nop 0
	global_load_lds_dwordx4 v[220:221], off
	v_lshl_add_u64 v[220:221], s[46:47], 0, v[130:131]
	s_mov_b32 m0, s91
	s_nop 0
	global_load_lds_dwordx4 v[220:221], off
	v_lshl_add_u64 v[220:221], s[46:47], 0, v[134:135]
	s_mov_b32 m0, s90
	s_nop 0
	global_load_lds_dwordx4 v[220:221], off
	v_lshl_add_u64 v[220:221], v[224:225], 0, s[14:15]
	s_mov_b32 m0, s72
	s_nop 0
	global_load_lds_dwordx4 v[220:221], off
	v_lshl_add_u64 v[220:221], v[226:227], 0, s[14:15]
	s_mov_b32 m0, s73
	s_nop 0
	global_load_lds_dwordx4 v[220:221], off
	s_waitcnt vmcnt(8)
	s_waitcnt lgkmcnt(0)
	s_barrier
	s_setprio 1
	s_waitcnt lgkmcnt(0)
	v_mfma_i32_16x16x64_i8 v[60:63], v[152:155], v[188:191], v[60:63]
	v_mfma_i32_16x16x64_i8 v[56:59], v[164:167], v[188:191], v[56:59]
	v_mfma_i32_16x16x64_i8 v[44:47], v[152:155], v[196:199], v[44:47]
	v_mfma_i32_16x16x64_i8 v[40:43], v[164:167], v[196:199], v[40:43]
	v_mfma_i32_16x16x64_i8 v[28:31], v[152:155], v[204:207], v[28:31]
	v_mfma_i32_16x16x64_i8 v[24:27], v[164:167], v[204:207], v[24:27]
	v_mfma_i32_16x16x64_i8 v[12:15], v[152:155], v[212:215], v[12:15]
	v_mfma_i32_16x16x64_i8 v[8:11], v[164:167], v[212:215], v[8:11]
	v_mfma_i32_16x16x64_i8 v[60:63], v[156:159], v[192:195], v[60:63]
	v_mfma_i32_16x16x64_i8 v[56:59], v[168:171], v[192:195], v[56:59]
	v_mfma_i32_16x16x64_i8 v[44:47], v[156:159], v[200:203], v[44:47]
	v_mfma_i32_16x16x64_i8 v[40:43], v[168:171], v[200:203], v[40:43]
	v_mfma_i32_16x16x64_i8 v[28:31], v[156:159], v[208:211], v[28:31]
	v_mfma_i32_16x16x64_i8 v[24:27], v[168:171], v[208:211], v[24:27]
	v_mfma_i32_16x16x64_i8 v[12:15], v[156:159], v[216:219], v[12:15]
	v_mfma_i32_16x16x64_i8 v[8:11], v[168:171], v[216:219], v[8:11]
	s_setprio 0
	s_setprio 1
	v_mfma_i32_16x16x64_i8 v[52:55], v[172:175], v[188:191], v[52:55]
	v_mfma_i32_16x16x64_i8 v[48:51], v[180:183], v[188:191], v[48:51]
	v_mfma_i32_16x16x64_i8 v[36:39], v[172:175], v[196:199], v[36:39]
	v_mfma_i32_16x16x64_i8 v[32:35], v[180:183], v[196:199], v[32:35]
	v_mfma_i32_16x16x64_i8 v[20:23], v[172:175], v[204:207], v[20:23]
	v_mfma_i32_16x16x64_i8 v[16:19], v[180:183], v[204:207], v[16:19]
	v_mfma_i32_16x16x64_i8 v[4:7], v[172:175], v[212:215], v[4:7]
	v_mfma_i32_16x16x64_i8 v[0:3], v[180:183], v[212:215], v[0:3]
	v_mfma_i32_16x16x64_i8 v[52:55], v[176:179], v[192:195], v[52:55]
	v_mfma_i32_16x16x64_i8 v[48:51], v[184:187], v[192:195], v[48:51]
	v_mfma_i32_16x16x64_i8 v[36:39], v[176:179], v[200:203], v[36:39]
	v_mfma_i32_16x16x64_i8 v[32:35], v[184:187], v[200:203], v[32:35]
	v_mfma_i32_16x16x64_i8 v[20:23], v[176:179], v[208:211], v[20:23]
	v_mfma_i32_16x16x64_i8 v[16:19], v[184:187], v[208:211], v[16:19]
	v_mfma_i32_16x16x64_i8 v[4:7], v[176:179], v[216:219], v[4:7]
	v_mfma_i32_16x16x64_i8 v[0:3], v[184:187], v[216:219], v[0:3]
	s_setprio 0
	s_barrier
	s_movk_i32 s48, 0x100
	s_andn2_b64 vcc, exec, s[44:45]
	s_mov_b64 s[46:47], -1
	s_mov_b64 s[44:45], 0
	s_cbranch_vccz .LBB0_4054

; #define PG8_STAGE(bufoff, gbase, voff) do { _Pragma("unroll") for (int _i = 0; _i < 2; ++_i) \
;         __builtin_amdgcn_global_load_lds((const unsigned*)((const char*)(gbase) + (voff)[_i]), (LAS unsigned*)(lds + (bufoff) + ldsw + _i * 8192), 16, 0, 0); } while (0)
; #define PG8_LDA(dst, b, h) do { _Pragma("unroll") for (int m = 0; m < 4; ++m) _Pragma("unroll") for (int k = 0; k < 2; ++k) dst[m][k] = *(const LAS bf16x8*)(lds + PG8_SA(b, h) + aoff + m * 2048 + k * 1024); } while (0)
; #define PG8_LDB(dst, b, h) do { _Pragma("unroll") for (int n = 0; n < 2; ++n) _Pragma("unroll") for (int k = 0; k < 2; ++k) dst[n][k] = *(const LAS bf16x8*)(lds + PG8_SB(b, h) + boff + n * 2048 + k * 1024); } while (0)
; #define PG8_WAIT_V(n) asm volatile("s_waitcnt vmcnt(" #n ")" ::: "memory")
; #define PG8_WAIT_L(n) asm volatile("s_waitcnt lgkmcnt(" #n ")" ::: "memory")
; #define PG8_BAR __builtin_amdgcn_s_barrier()
; #define PG8_SCHED __builtin_amdgcn_sched_barrier(0)
;     ...
;         const char* nA = has_next ? (const char*)g.A + (size_t)nxt.pm * tstep + (size_t)nxt.kt0 * kstep : cA; const char* nB = has_next ? (const char*)g.Bt + (size_t)nxt.e * g.estride + (size_t)nxt.pn * tstep + (size_t)nxt.kt0 * kstep : cB;
;         const int nt = cur.nkt;
;         for (int t = 0; t < nt; t += 2) {
;             const bool last = (t == nt - 2);
;             const char* a1 = cA + (size_t)(t + 1) * kstep;
;             const char* a2 = last ? nA : cA + (size_t)(t + 2) * kstep; const char* b2 = last ? nB : cB + (size_t)(t + 2) * kstep;
;             const char* a3 = a2 + kstep; const char* b3 = b2 + kstep;
;             PG8_LDB(B0, 0, 0); PG8_LDB(B1, 0, 1); PG8_SCHED; PG8_LDA(At, 0, 0); PG8_STAGE(PG8_SA(1, 1), a1 + hstep, voffA);
;             PG8_WAIT_V(8); PG8_WAIT_L(0); PG8_BAR; PG8_MMA(0, 0, At, B0); PG8_MMA(0, 1, At, B1); PG8_BAR; PG8_SCHED;
;             PG8_LDA(At, 0, 1); PG8_STAGE(PG8_SB(0, 0), b2, voffB); PG8_STAGE(PG8_SB(0, 1), b2 + hstep, voffB); PG8_STAGE(PG8_SA(0, 0), a2, voffA);
;             PG8_WAIT_V(8); PG8_WAIT_L(0); PG8_BAR; PG8_MMA(1, 0, At, B0); PG8_MMA(1, 1, At, B1); PG8_BAR; PG8_SCHED;
.LBB0_4111:
	s_ashr_i32 s27, s26, 31
	s_lshl_b64 s[28:29], s[26:27], 19
	s_add_u32 s28, s19, s28
	s_addc_u32 s29, s34, s29
	s_and_b64 s[30:31], s[20:21], exec
	s_cselect_b32 s3, s29, s37
	s_cselect_b32 s27, s28, s36
	s_ashr_i32 s25, s24, 31
	s_lshl_b64 s[30:31], s[24:25], 19
	s_add_u32 s30, s4, s30
	s_addc_u32 s31, s5, s31
	s_and_b64 s[40:41], s[20:21], exec
	s_cselect_b32 s25, s31, s39
	s_cselect_b32 s62, s30, s38
	s_add_u32 s36, s36, 0x40080
	s_addc_u32 s37, s37, 0
	s_add_u32 s63, s38, 0x100
	s_addc_u32 s64, s39, 0
	s_mov_b32 s65, -2
	ds_read_b128 v[24:27], v106
	ds_read_b128 v[28:31], v106 offset:1024
	ds_read_b128 v[32:35], v106 offset:2048
	ds_read_b128 v[36:39], v106 offset:3072
	s_add_u32 s38, s36, 0xfffc0080
	s_addc_u32 s39, s37, -1
	s_cmp_eq_u32 s65, 12
	s_cselect_b32 s41, s3, s39
	s_cselect_b32 s40, s27, s38
	s_cselect_b32 s39, s25, s64
	s_cselect_b32 s38, s62, s63
	v_lshl_add_u64 v[102:103], s[36:37], 0, v[98:99]
	s_add_i32 m0, s42, 0xc000
	ds_read_b128 v[110:113], v107
	ds_read_b128 v[114:117], v107 offset:1024
	ds_read_b128 v[118:121], v107 offset:2048
	ds_read_b128 v[122:125], v107 offset:3072
	ds_read_b128 v[126:129], v107 offset:4096
	ds_read_b128 v[130:133], v107 offset:5120
	ds_read_b128 v[134:137], v107 offset:6144
	ds_read_b128 v[138:141], v107 offset:7168
	global_load_lds_dwordx4 v[102:103], off
	v_lshl_add_u64 v[102:103], s[36:37], 0, v[100:101]
	s_add_i32 m0, s42, 0xe000
	s_nop 0
	global_load_lds_dwordx4 v[102:103], off
	s_waitcnt vmcnt(8)
	s_waitcnt lgkmcnt(0)
	s_barrier
	s_setprio 1
	s_waitcnt lgkmcnt(0)
	v_mfma_i32_16x16x64_i8 v[76:79], v[24:27], v[110:113], 0
	v_mfma_i32_16x16x64_i8 v[72:75], v[32:35], v[110:113], 0
	v_mfma_i32_16x16x64_i8 v[68:71], v[24:27], v[118:121], 0
	v_mfma_i32_16x16x64_i8 v[64:67], v[32:35], v[118:121], 0
	v_mfma_i32_16x16x64_i8 v[60:63], v[24:27], v[126:129], 0
	v_mfma_i32_16x16x64_i8 v[56:59], v[32:35], v[126:129], 0
	v_mfma_i32_16x16x64_i8 v[52:55], v[24:27], v[134:137], 0
	v_mfma_i32_16x16x64_i8 v[48:51], v[32:35], v[134:137], 0
	v_mfma_i32_16x16x64_i8 v[76:79], v[28:31], v[114:117], v[76:79]
	v_mfma_i32_16x16x64_i8 v[72:75], v[36:39], v[114:117], v[72:75]
	v_mfma_i32_16x16x64_i8 v[68:71], v[28:31], v[122:125], v[68:71]
	v_mfma_i32_16x16x64_i8 v[64:67], v[36:39], v[122:125], v[64:67]
	v_mfma_i32_16x16x64_i8 v[60:63], v[28:31], v[130:133], v[60:63]
	v_mfma_i32_16x16x64_i8 v[56:59], v[36:39], v[130:133], v[56:59]
	v_mfma_i32_16x16x64_i8 v[52:55], v[28:31], v[138:141], v[52:55]
	v_mfma_i32_16x16x64_i8 v[48:51], v[36:39], v[138:141], v[48:51]
	s_setprio 0
	s_setprio 1
	s_setprio 0
	s_barrier
	s_add_i32 s66, s59, s35
	v_lshl_add_u64 v[102:103], s[38:39], 0, v[82:83]
	s_mov_b32 m0, s66
	ds_read_b128 v[110:113], v107 offset:16384
	ds_read_b128 v[114:117], v107 offset:17408
	ds_read_b128 v[118:121], v107 offset:18432
	ds_read_b128 v[122:125], v107 offset:19456
	ds_read_b128 v[126:129], v107 offset:20480
	ds_read_b128 v[130:133], v107 offset:21504
	ds_read_b128 v[134:137], v107 offset:22528
	ds_read_b128 v[138:141], v107 offset:23552
	global_load_lds_dwordx4 v[102:103], off
	s_add_i32 m0, s66, 0x2000
	s_add_u32 s66, s38, 0x40000
	v_lshl_add_u64 v[142:143], s[38:39], 0, v[86:87]
	s_addc_u32 s67, s39, 0
	global_load_lds_dwordx4 v[142:143], off
	v_lshl_add_u64 v[144:145], s[66:67], 0, v[82:83]
	s_mov_b32 m0, s43
	v_lshl_add_u64 v[146:147], s[40:41], 0, v[84:85]
	global_load_lds_dwordx4 v[144:145], off
	v_lshl_add_u64 v[144:145], s[66:67], 0, v[86:87]
	s_mov_b32 m0, s44
	s_nop 0
	global_load_lds_dwordx4 v[144:145], off
	v_lshl_add_u64 v[144:145], s[40:41], 0, v[80:81]
	s_mov_b32 m0, s42
	s_nop 0
	global_load_lds_dwordx4 v[144:145], off
	s_mov_b32 m0, s45
	s_nop 0
	global_load_lds_dwordx4 v[146:147], off
	s_waitcnt vmcnt(8)
	s_waitcnt lgkmcnt(0)
	s_barrier
	s_setprio 1
	s_waitcnt lgkmcnt(0)
	v_mfma_i32_16x16x64_i8 v[44:47], v[24:27], v[110:113], 0
	v_mfma_i32_16x16x64_i8 v[40:43], v[32:35], v[110:113], 0
	v_mfma_i32_16x16x64_i8 v[20:23], v[24:27], v[118:121], 0
	v_mfma_i32_16x16x64_i8 v[16:19], v[32:35], v[118:121], 0
	v_mfma_i32_16x16x64_i8 v[12:15], v[24:27], v[126:129], 0
	v_mfma_i32_16x16x64_i8 v[8:11], v[32:35], v[126:129], 0
	v_mfma_i32_16x16x64_i8 v[4:7], v[24:27], v[134:137], 0
	v_mfma_i32_16x16x64_i8 v[0:3], v[32:35], v[134:137], 0
	v_mfma_i32_16x16x64_i8 v[44:47], v[28:31], v[114:117], v[44:47]
	v_mfma_i32_16x16x64_i8 v[40:43], v[36:39], v[114:117], v[40:43]
	v_mfma_i32_16x16x64_i8 v[20:23], v[28:31], v[122:125], v[20:23]
	v_mfma_i32_16x16x64_i8 v[16:19], v[36:39], v[122:125], v[16:19]
	v_mfma_i32_16x16x64_i8 v[12:15], v[28:31], v[130:133], v[12:15]
	v_mfma_i32_16x16x64_i8 v[8:11], v[36:39], v[130:133], v[8:11]
	v_mfma_i32_16x16x64_i8 v[4:7], v[28:31], v[138:141], v[4:7]
	v_mfma_i32_16x16x64_i8 v[0:3], v[36:39], v[138:141], v[0:3]
	s_setprio 0
	s_setprio 1
	s_setprio 0
	s_barrier
; #define PG8_STAGE(bufoff, gbase, voff) do { _Pragma("unroll") for (int _i = 0; _i < 2; ++_i) \
;         __builtin_amdgcn_global_load_lds((const unsigned*)((const char*)(gbase) + (voff)[_i]), (LAS unsigned*)(lds + (bufoff) + ldsw + _i * 8192), 16, 0, 0); } while (0)
; #define PG8_LDA(dst, b, h) do { _Pragma("unroll") for (int m = 0; m < 4; ++m) _Pragma("unroll") for (int k = 0; k < 2; ++k) dst[m][k] = *(const LAS bf16x8*)(lds + PG8_SA(b, h) + aoff + m * 2048 + k * 1024); } while (0)
; #define PG8_LDB(dst, b, h) do { _Pragma("unroll") for (int n = 0; n < 2; ++n) _Pragma("unroll") for (int k = 0; k < 2; ++k) dst[n][k] = *(const LAS bf16x8*)(lds + PG8_SB(b, h) + boff + n * 2048 + k * 1024); } while (0)
; #define PG8_WAIT_V(n) asm volatile("s_waitcnt vmcnt(" #n ")" ::: "memory")
; #define PG8_WAIT_L(n) asm volatile("s_waitcnt lgkmcnt(" #n ")" ::: "memory")
; #define PG8_BAR __builtin_amdgcn_s_barrier()
; #define PG8_SCHED __builtin_amdgcn_sched_barrier(0)
;     ...
;             PG8_LDB(B0, 1, 0); PG8_LDB(B1, 1, 1); PG8_SCHED; PG8_LDA(At, 1, 0); PG8_STAGE(PG8_SA(0, 1), a2 + hstep, voffA);
;             PG8_WAIT_V(8); PG8_WAIT_L(0); PG8_BAR; PG8_MMA(0, 0, At, B0); PG8_MMA(0, 1, At, B1); PG8_BAR; PG8_SCHED;
;             PG8_LDA(At, 1, 1); PG8_STAGE(PG8_SB(1, 0), b3, voffB); PG8_STAGE(PG8_SB(1, 1), b3 + hstep, voffB); PG8_STAGE(PG8_SA(1, 0), a3, voffA);
;             PG8_WAIT_V(8); PG8_WAIT_L(0); PG8_BAR; PG8_MMA(1, 0, At, B0); PG8_MMA(1, 1, At, B1); PG8_BAR; PG8_SCHED;
;         }
	s_add_i32 s66, 0, 0x18000
	v_add_u32_e32 v36, s66, v105
	ds_read_b128 v[24:27], v36
	ds_read_b128 v[28:31], v36 offset:1024
	ds_read_b128 v[32:35], v36 offset:2048
	ds_read_b128 v[36:39], v36 offset:3072
	s_add_u32 s40, s40, 0x40000
	s_addc_u32 s41, s41, 0
	s_mov_b32 m0, s46
	v_lshl_add_u64 v[148:149], s[40:41], 0, v[80:81]
	ds_read_b128 v[110:113], v107 offset:32768
	ds_read_b128 v[114:117], v107 offset:33792
	ds_read_b128 v[118:121], v107 offset:34816
	ds_read_b128 v[122:125], v107 offset:35840
	ds_read_b128 v[126:129], v107 offset:36864
	ds_read_b128 v[130:133], v107 offset:37888
	ds_read_b128 v[134:137], v107 offset:38912
	ds_read_b128 v[138:141], v107 offset:39936
	global_load_lds_dwordx4 v[148:149], off
	v_lshl_add_u64 v[148:149], s[40:41], 0, v[84:85]
	s_mov_b32 m0, s47
	s_nop 0
	global_load_lds_dwordx4 v[148:149], off
	s_waitcnt vmcnt(8)
	s_waitcnt lgkmcnt(0)
	s_barrier
	s_setprio 1
	s_waitcnt lgkmcnt(0)
	v_mfma_i32_16x16x64_i8 v[76:79], v[24:27], v[110:113], v[76:79]
	v_mfma_i32_16x16x64_i8 v[72:75], v[32:35], v[110:113], v[72:75]
	v_mfma_i32_16x16x64_i8 v[68:71], v[24:27], v[118:121], v[68:71]
	v_mfma_i32_16x16x64_i8 v[64:67], v[32:35], v[118:121], v[64:67]
	v_mfma_i32_16x16x64_i8 v[60:63], v[24:27], v[126:129], v[60:63]
	v_mfma_i32_16x16x64_i8 v[56:59], v[32:35], v[126:129], v[56:59]
	v_mfma_i32_16x16x64_i8 v[52:55], v[24:27], v[134:137], v[52:55]
	v_mfma_i32_16x16x64_i8 v[48:51], v[32:35], v[134:137], v[48:51]
	v_mfma_i32_16x16x64_i8 v[76:79], v[28:31], v[114:117], v[76:79]
	v_mfma_i32_16x16x64_i8 v[72:75], v[36:39], v[114:117], v[72:75]
	v_mfma_i32_16x16x64_i8 v[68:71], v[28:31], v[122:125], v[68:71]
	v_mfma_i32_16x16x64_i8 v[64:67], v[36:39], v[122:125], v[64:67]
	v_mfma_i32_16x16x64_i8 v[60:63], v[28:31], v[130:133], v[60:63]
	v_mfma_i32_16x16x64_i8 v[56:59], v[36:39], v[130:133], v[56:59]
	v_mfma_i32_16x16x64_i8 v[52:55], v[28:31], v[138:141], v[52:55]
	v_mfma_i32_16x16x64_i8 v[48:51], v[36:39], v[138:141], v[48:51]
	s_setprio 0
	s_setprio 1
	s_setprio 0
	s_barrier
	s_add_i32 s40, s66, s35
	v_lshl_add_u64 v[102:103], v[102:103], 0, s[8:9]
	s_mov_b32 m0, s40
	ds_read_b128 v[110:113], v107 offset:49152
	ds_read_b128 v[114:117], v107 offset:50176
	ds_read_b128 v[118:121], v107 offset:51200
	ds_read_b128 v[122:125], v107 offset:52224
	ds_read_b128 v[126:129], v107 offset:53248
	ds_read_b128 v[130:133], v107 offset:54272
	ds_read_b128 v[134:137], v107 offset:55296
	ds_read_b128 v[138:141], v107 offset:56320
	global_load_lds_dwordx4 v[102:103], off
	s_add_i32 m0, s40, 0x2000
	s_add_u32 s38, s38, 0x40080
	v_lshl_add_u64 v[102:103], v[142:143], 0, s[8:9]
	s_addc_u32 s39, s39, 0
	global_load_lds_dwordx4 v[102:103], off
	v_lshl_add_u64 v[102:103], s[38:39], 0, v[82:83]
	s_mov_b32 m0, s51
	s_nop 0
	global_load_lds_dwordx4 v[102:103], off
	v_lshl_add_u64 v[102:103], s[38:39], 0, v[86:87]
	s_mov_b32 m0, s55
	s_nop 0
	global_load_lds_dwordx4 v[102:103], off
	v_lshl_add_u64 v[102:103], v[144:145], 0, s[8:9]
	s_mov_b32 m0, s49
	s_nop 0
	global_load_lds_dwordx4 v[102:103], off
	v_lshl_add_u64 v[102:103], v[146:147], 0, s[8:9]
	s_mov_b32 m0, s50
	s_nop 0
	global_load_lds_dwordx4 v[102:103], off
	s_waitcnt vmcnt(8)
	s_waitcnt lgkmcnt(0)
	s_barrier
	s_setprio 1
	s_waitcnt lgkmcnt(0)
	v_mfma_i32_16x16x64_i8 v[44:47], v[24:27], v[110:113], v[44:47]
	v_mfma_i32_16x16x64_i8 v[40:43], v[32:35], v[110:113], v[40:43]
	v_mfma_i32_16x16x64_i8 v[20:23], v[24:27], v[118:121], v[20:23]
	v_mfma_i32_16x16x64_i8 v[16:19], v[32:35], v[118:121], v[16:19]
	v_mfma_i32_16x16x64_i8 v[12:15], v[24:27], v[126:129], v[12:15]
	v_mfma_i32_16x16x64_i8 v[8:11], v[32:35], v[126:129], v[8:11]
	v_mfma_i32_16x16x64_i8 v[4:7], v[24:27], v[134:137], v[4:7]
	v_mfma_i32_16x16x64_i8 v[0:3], v[32:35], v[134:137], v[0:3]
	v_mfma_i32_16x16x64_i8 v[44:47], v[28:31], v[114:117], v[44:47]
	v_mfma_i32_16x16x64_i8 v[40:43], v[36:39], v[114:117], v[40:43]
	v_mfma_i32_16x16x64_i8 v[20:23], v[28:31], v[122:125], v[20:23]
	v_mfma_i32_16x16x64_i8 v[16:19], v[36:39], v[122:125], v[16:19]
	v_mfma_i32_16x16x64_i8 v[12:15], v[28:31], v[130:133], v[12:15]
	v_mfma_i32_16x16x64_i8 v[8:11], v[36:39], v[130:133], v[8:11]
	v_mfma_i32_16x16x64_i8 v[4:7], v[28:31], v[138:141], v[4:7]
	v_mfma_i32_16x16x64_i8 v[0:3], v[36:39], v[138:141], v[0:3]
	s_setprio 0
	s_setprio 1
	s_setprio 0
	s_barrier
	s_add_i32 s65, s65, 2
	s_add_u32 s36, s36, 0x100
	s_addc_u32 s37, s37, 0
	s_add_u32 s63, s63, 0x100
	s_addc_u32 s64, s64, 0
	s_cmp_gt_u32 s65, 13
	s_cbranch_scc0 .LBB0_4112

; #define PG8_STAGE(bufoff, gbase, voff) do { _Pragma("unroll") for (int _i = 0; _i < 2; ++_i) \
;         __builtin_amdgcn_global_load_lds((const unsigned*)((const char*)(gbase) + (voff)[_i]), (LAS unsigned*)(lds + (bufoff) + ldsw + _i * 8192), 16, 0, 0); } while (0)
; #define PG8_LDA(dst, b, h) do { _Pragma("unroll") for (int m = 0; m < 4; ++m) _Pragma("unroll") for (int k = 0; k < 2; ++k) dst[m][k] = *(const LAS bf16x8*)(lds + PG8_SA(b, h) + aoff + m * 2048 + k * 1024); } while (0)
; #define PG8_LDB(dst, b, h) do { _Pragma("unroll") for (int n = 0; n < 2; ++n) _Pragma("unroll") for (int k = 0; k < 2; ++k) dst[n][k] = *(const LAS bf16x8*)(lds + PG8_SB(b, h) + boff + n * 2048 + k * 1024); } while (0)
; #define PG8_WAIT_V(n) asm volatile("s_waitcnt vmcnt(" #n ")" ::: "memory")
; #define PG8_WAIT_L(n) asm volatile("s_waitcnt lgkmcnt(" #n ")" ::: "memory")
; #define PG8_BAR __builtin_amdgcn_s_barrier()
; #define PG8_SCHED __builtin_amdgcn_sched_barrier(0)
;     ...
;         const char* nA = has_next ? (const char*)g.A + (size_t)nxt.pm * tstep + (size_t)nxt.kt0 * kstep : cA; const char* nB = has_next ? (const char*)g.Bt + (size_t)nxt.e * g.estride + (size_t)nxt.pn * tstep + (size_t)nxt.kt0 * kstep : cB;
;         const int nt = cur.nkt;
;         for (int t = 0; t < nt; t += 2) {
;             const bool last = (t == nt - 2);
;             const char* a1 = cA + (size_t)(t + 1) * kstep;
;             const char* a2 = last ? nA : cA + (size_t)(t + 2) * kstep; const char* b2 = last ? nB : cB + (size_t)(t + 2) * kstep;
;             const char* a3 = a2 + kstep; const char* b3 = b2 + kstep;
;             PG8_LDB(B0, 0, 0); PG8_LDB(B1, 0, 1); PG8_SCHED; PG8_LDA(At, 0, 0); PG8_STAGE(PG8_SA(1, 1), a1 + hstep, voffA);
;             PG8_WAIT_V(8); PG8_WAIT_L(0); PG8_BAR; PG8_MMA(0, 0, At, B0); PG8_MMA(0, 1, At, B1); PG8_BAR; PG8_SCHED;
;             PG8_LDA(At, 0, 1); PG8_STAGE(PG8_SB(0, 0), b2, voffB); PG8_STAGE(PG8_SB(0, 1), b2 + hstep, voffB); PG8_STAGE(PG8_SA(0, 0), a2, voffA);
;             PG8_WAIT_V(8); PG8_WAIT_L(0); PG8_BAR; PG8_MMA(1, 0, At, B0); PG8_MMA(1, 1, At, B1); PG8_BAR; PG8_SCHED;
.LBB0_4137:
	s_ashr_i32 s27, s26, 31
	s_lshl_b64 s[28:29], s[26:27], 17
	s_add_u32 s28, s23, s28
	s_addc_u32 s29, s34, s29
	s_and_b64 s[30:31], s[2:3], exec
	s_cselect_b32 s14, s29, s39
	s_cselect_b32 s27, s28, s38
	s_ashr_i32 s25, s24, 31
	s_lshl_b64 s[30:31], s[24:25], 17
	s_add_u32 s30, s55, s30
	s_addc_u32 s31, s60, s31
	s_and_b64 s[40:41], s[2:3], exec
	s_cselect_b32 s25, s31, s37
	s_cselect_b32 s76, s30, s36
	s_mov_b32 s44, 0
	s_mov_b64 s[40:41], -1
	s_mov_b64 s[42:43], 0
	s_add_u32 s45, s38, s44
	s_addc_u32 s50, s39, 0
	s_add_u32 s48, s45, 0x100
	s_addc_u32 s49, s50, 0
	s_and_b64 s[46:47], s[42:43], exec
	s_cselect_b32 s47, s14, s49
	s_cselect_b32 s46, s27, s48
	s_add_u32 s44, s36, s44
	s_addc_u32 s48, s37, 0
	s_add_u32 s44, s44, 0x100
	s_addc_u32 s48, s48, 0
	s_and_b64 s[42:43], s[42:43], exec
	s_cselect_b32 s49, s25, s48
	s_cselect_b32 s48, s76, s44
	s_add_u32 s58, s45, 0x10080
	s_addc_u32 s59, s50, 0
	s_add_i32 s84, s71, s61
	s_add_i32 m0, s62, 0xc000
	s_add_i32 s87, s62, 0xe000
	s_add_i32 s81, s84, 0x2000
	v_add_u32_e32 v144, s71, v147
	s_add_u32 s50, s48, 0x10000
	ds_read_b128 v[154:157], v144
	ds_read_b128 v[158:161], v144 offset:1024
	ds_read_b128 v[162:165], v144 offset:2048
	ds_read_b128 v[166:169], v144 offset:3072
	v_add_u32_e32 v144, s72, v147
	s_addc_u32 s51, s49, 0
	s_add_i32 s83, s72, s61
	ds_read_b128 v[170:173], v144
	ds_read_b128 v[174:177], v144 offset:1024
	ds_read_b128 v[178:181], v144 offset:2048
	ds_read_b128 v[182:185], v144 offset:3072
	s_add_i32 s82, s83, 0x2000
	s_add_i32 s80, 0, 0x18000
	s_add_i32 s79, 0, 0x1c000
	s_add_u32 s44, s46, 0x10000
	s_addc_u32 s45, s47, 0
	s_add_i32 s78, s80, s61
	s_add_i32 s77, s78, 0x2000
	s_add_u32 s42, s48, 0x10080
	s_addc_u32 s43, s49, 0
	s_add_i32 s86, s79, s61
	s_add_i32 s85, s86, 0x2000
	v_lshl_add_u64 v[144:145], s[58:59], 0, v[128:129]
	ds_read_b128 v[186:189], v148
	ds_read_b128 v[190:193], v148 offset:1024
	ds_read_b128 v[194:197], v148 offset:2048
	ds_read_b128 v[198:201], v148 offset:3072
	ds_read_b128 v[202:205], v148 offset:4096
	ds_read_b128 v[206:209], v148 offset:5120
	ds_read_b128 v[210:213], v148 offset:6144
	ds_read_b128 v[214:217], v148 offset:7168
	global_load_lds_dwordx4 v[144:145], off
	v_lshl_add_u64 v[144:145], s[58:59], 0, v[132:133]
	s_mov_b32 m0, s87
	s_nop 0
	global_load_lds_dwordx4 v[144:145], off
	s_waitcnt vmcnt(8)
	s_waitcnt lgkmcnt(0)
	s_barrier
	s_setprio 1
	s_waitcnt lgkmcnt(0)
	v_mfma_i32_16x16x64_i8 v[124:127], v[154:157], v[186:189], 0
	v_mfma_i32_16x16x64_i8 v[120:123], v[162:165], v[186:189], 0
	v_mfma_i32_16x16x64_i8 v[108:111], v[154:157], v[194:197], 0
	v_mfma_i32_16x16x64_i8 v[104:107], v[162:165], v[194:197], 0
	v_mfma_i32_16x16x64_i8 v[92:95], v[154:157], v[202:205], 0
	v_mfma_i32_16x16x64_i8 v[88:91], v[162:165], v[202:205], 0
	v_mfma_i32_16x16x64_i8 v[76:79], v[154:157], v[210:213], 0
	v_mfma_i32_16x16x64_i8 v[72:75], v[162:165], v[210:213], 0
	v_mfma_i32_16x16x64_i8 v[124:127], v[158:161], v[190:193], v[124:127]
	v_mfma_i32_16x16x64_i8 v[120:123], v[166:169], v[190:193], v[120:123]
	v_mfma_i32_16x16x64_i8 v[108:111], v[158:161], v[198:201], v[108:111]
	v_mfma_i32_16x16x64_i8 v[104:107], v[166:169], v[198:201], v[104:107]
	v_mfma_i32_16x16x64_i8 v[92:95], v[158:161], v[206:209], v[92:95]
	v_mfma_i32_16x16x64_i8 v[88:91], v[166:169], v[206:209], v[88:91]
	v_mfma_i32_16x16x64_i8 v[76:79], v[158:161], v[214:217], v[76:79]
	v_mfma_i32_16x16x64_i8 v[72:75], v[166:169], v[214:217], v[72:75]
	s_setprio 0
	s_setprio 1
	v_mfma_i32_16x16x64_i8 v[116:119], v[170:173], v[186:189], 0
	v_mfma_i32_16x16x64_i8 v[112:115], v[178:181], v[186:189], 0
	v_mfma_i32_16x16x64_i8 v[100:103], v[170:173], v[194:197], 0
	v_mfma_i32_16x16x64_i8 v[96:99], v[178:181], v[194:197], 0
	v_mfma_i32_16x16x64_i8 v[84:87], v[170:173], v[202:205], 0
	v_mfma_i32_16x16x64_i8 v[80:83], v[178:181], v[202:205], 0
	v_mfma_i32_16x16x64_i8 v[68:71], v[170:173], v[210:213], 0
	v_mfma_i32_16x16x64_i8 v[64:67], v[178:181], v[210:213], 0
	v_mfma_i32_16x16x64_i8 v[116:119], v[174:177], v[190:193], v[116:119]
	v_mfma_i32_16x16x64_i8 v[112:115], v[182:185], v[190:193], v[112:115]
	v_mfma_i32_16x16x64_i8 v[100:103], v[174:177], v[198:201], v[100:103]
	v_mfma_i32_16x16x64_i8 v[96:99], v[182:185], v[198:201], v[96:99]
	v_mfma_i32_16x16x64_i8 v[84:87], v[174:177], v[206:209], v[84:87]
	v_mfma_i32_16x16x64_i8 v[80:83], v[182:185], v[206:209], v[80:83]
	v_mfma_i32_16x16x64_i8 v[68:71], v[174:177], v[214:217], v[68:71]
	v_mfma_i32_16x16x64_i8 v[64:67], v[182:185], v[214:217], v[64:67]
	s_setprio 0
	s_barrier
	s_mov_b32 m0, s84
	v_lshl_add_u64 v[144:145], s[48:49], 0, v[130:131]
	ds_read_b128 v[186:189], v148 offset:16384
	ds_read_b128 v[190:193], v148 offset:17408
	ds_read_b128 v[194:197], v148 offset:18432
	ds_read_b128 v[198:201], v148 offset:19456
	ds_read_b128 v[202:205], v148 offset:20480
	ds_read_b128 v[206:209], v148 offset:21504
	ds_read_b128 v[210:213], v148 offset:22528
	ds_read_b128 v[214:217], v148 offset:23552
	global_load_lds_dwordx4 v[144:145], off
	v_lshl_add_u64 v[218:219], s[48:49], 0, v[134:135]
	s_mov_b32 m0, s81
	v_lshl_add_u64 v[220:221], s[50:51], 0, v[130:131]
	global_load_lds_dwordx4 v[218:219], off
	s_mov_b32 m0, s83
	v_lshl_add_u64 v[222:223], s[46:47], 0, v[132:133]
	global_load_lds_dwordx4 v[220:221], off
	v_lshl_add_u64 v[220:221], s[50:51], 0, v[134:135]
	s_mov_b32 m0, s82
	s_nop 0
	global_load_lds_dwordx4 v[220:221], off
	v_lshl_add_u64 v[220:221], s[46:47], 0, v[128:129]
	s_mov_b32 m0, s62
	s_nop 0
	global_load_lds_dwordx4 v[220:221], off
	s_mov_b32 m0, s63
	s_nop 0
	global_load_lds_dwordx4 v[222:223], off
	s_waitcnt vmcnt(8)
	s_waitcnt lgkmcnt(0)
	s_barrier
; #define PG8_STAGE(bufoff, gbase, voff) do { _Pragma("unroll") for (int _i = 0; _i < 2; ++_i) \
;         __builtin_amdgcn_global_load_lds((const unsigned*)((const char*)(gbase) + (voff)[_i]), (LAS unsigned*)(lds + (bufoff) + ldsw + _i * 8192), 16, 0, 0); } while (0)
; #define PG8_LDA(dst, b, h) do { _Pragma("unroll") for (int m = 0; m < 4; ++m) _Pragma("unroll") for (int k = 0; k < 2; ++k) dst[m][k] = *(const LAS bf16x8*)(lds + PG8_SA(b, h) + aoff + m * 2048 + k * 1024); } while (0)
; #define PG8_LDB(dst, b, h) do { _Pragma("unroll") for (int n = 0; n < 2; ++n) _Pragma("unroll") for (int k = 0; k < 2; ++k) dst[n][k] = *(const LAS bf16x8*)(lds + PG8_SB(b, h) + boff + n * 2048 + k * 1024); } while (0)
; #define PG8_WAIT_V(n) asm volatile("s_waitcnt vmcnt(" #n ")" ::: "memory")
; #define PG8_WAIT_L(n) asm volatile("s_waitcnt lgkmcnt(" #n ")" ::: "memory")
; #define PG8_BAR __builtin_amdgcn_s_barrier()
; #define PG8_SCHED __builtin_amdgcn_sched_barrier(0)
;     ...
;             PG8_WAIT_V(8); PG8_WAIT_L(0); PG8_BAR; PG8_MMA(1, 0, At, B0); PG8_MMA(1, 1, At, B1); PG8_BAR; PG8_SCHED;
;             PG8_LDB(B0, 1, 0); PG8_LDB(B1, 1, 1); PG8_SCHED; PG8_LDA(At, 1, 0); PG8_STAGE(PG8_SA(0, 1), a2 + hstep, voffA);
;             PG8_WAIT_V(8); PG8_WAIT_L(0); PG8_BAR; PG8_MMA(0, 0, At, B0); PG8_MMA(0, 1, At, B1); PG8_BAR; PG8_SCHED;
	s_setprio 1
	s_waitcnt lgkmcnt(0)
	v_mfma_i32_16x16x64_i8 v[60:63], v[154:157], v[186:189], 0
	v_mfma_i32_16x16x64_i8 v[56:59], v[162:165], v[186:189], 0
	v_mfma_i32_16x16x64_i8 v[44:47], v[154:157], v[194:197], 0
	v_mfma_i32_16x16x64_i8 v[40:43], v[162:165], v[194:197], 0
	v_mfma_i32_16x16x64_i8 v[28:31], v[154:157], v[202:205], 0
	v_mfma_i32_16x16x64_i8 v[24:27], v[162:165], v[202:205], 0
	v_mfma_i32_16x16x64_i8 v[12:15], v[154:157], v[210:213], 0
	v_mfma_i32_16x16x64_i8 v[8:11], v[162:165], v[210:213], 0
	v_mfma_i32_16x16x64_i8 v[60:63], v[158:161], v[190:193], v[60:63]
	v_mfma_i32_16x16x64_i8 v[56:59], v[166:169], v[190:193], v[56:59]
	v_mfma_i32_16x16x64_i8 v[44:47], v[158:161], v[198:201], v[44:47]
	v_mfma_i32_16x16x64_i8 v[40:43], v[166:169], v[198:201], v[40:43]
	v_mfma_i32_16x16x64_i8 v[28:31], v[158:161], v[206:209], v[28:31]
	v_mfma_i32_16x16x64_i8 v[24:27], v[166:169], v[206:209], v[24:27]
	v_mfma_i32_16x16x64_i8 v[12:15], v[158:161], v[214:217], v[12:15]
	v_mfma_i32_16x16x64_i8 v[8:11], v[166:169], v[214:217], v[8:11]
	s_setprio 0
	s_setprio 1
	v_mfma_i32_16x16x64_i8 v[52:55], v[170:173], v[186:189], 0
	v_mfma_i32_16x16x64_i8 v[48:51], v[178:181], v[186:189], 0
	v_mfma_i32_16x16x64_i8 v[36:39], v[170:173], v[194:197], 0
	v_mfma_i32_16x16x64_i8 v[32:35], v[178:181], v[194:197], 0
	v_mfma_i32_16x16x64_i8 v[20:23], v[170:173], v[202:205], 0
	v_mfma_i32_16x16x64_i8 v[16:19], v[178:181], v[202:205], 0
	v_mfma_i32_16x16x64_i8 v[4:7], v[170:173], v[210:213], 0
	v_mfma_i32_16x16x64_i8 v[0:3], v[178:181], v[210:213], 0
	v_mfma_i32_16x16x64_i8 v[52:55], v[174:177], v[190:193], v[52:55]
	v_mfma_i32_16x16x64_i8 v[48:51], v[182:185], v[190:193], v[48:51]
	v_mfma_i32_16x16x64_i8 v[36:39], v[174:177], v[198:201], v[36:39]
	v_mfma_i32_16x16x64_i8 v[32:35], v[182:185], v[198:201], v[32:35]
	v_mfma_i32_16x16x64_i8 v[20:23], v[174:177], v[206:209], v[20:23]
	v_mfma_i32_16x16x64_i8 v[16:19], v[182:185], v[206:209], v[16:19]
	v_mfma_i32_16x16x64_i8 v[4:7], v[174:177], v[214:217], v[4:7]
	v_mfma_i32_16x16x64_i8 v[0:3], v[182:185], v[214:217], v[0:3]
	s_setprio 0
	s_barrier
	v_add_u32_e32 v166, s80, v147
	v_add_u32_e32 v182, s79, v147
	ds_read_b128 v[154:157], v166
	ds_read_b128 v[158:161], v166 offset:1024
	ds_read_b128 v[162:165], v166 offset:2048
	ds_read_b128 v[166:169], v166 offset:3072
	ds_read_b128 v[170:173], v182
	ds_read_b128 v[174:177], v182 offset:1024
	ds_read_b128 v[178:181], v182 offset:2048
	ds_read_b128 v[182:185], v182 offset:3072
	s_mov_b32 m0, s64
	v_lshl_add_u64 v[224:225], s[44:45], 0, v[128:129]
	ds_read_b128 v[186:189], v148 offset:32768
	ds_read_b128 v[190:193], v148 offset:33792
	ds_read_b128 v[194:197], v148 offset:34816
	ds_read_b128 v[198:201], v148 offset:35840
	ds_read_b128 v[202:205], v148 offset:36864
	ds_read_b128 v[206:209], v148 offset:37888
	ds_read_b128 v[210:213], v148 offset:38912
	ds_read_b128 v[214:217], v148 offset:39936
	global_load_lds_dwordx4 v[224:225], off
	v_lshl_add_u64 v[224:225], s[44:45], 0, v[132:133]
	s_mov_b32 m0, s65
	s_nop 0
	global_load_lds_dwordx4 v[224:225], off
	s_waitcnt vmcnt(8)
	s_waitcnt lgkmcnt(0)
	s_barrier
	s_setprio 1
	s_waitcnt lgkmcnt(0)
	v_mfma_i32_16x16x64_i8 v[124:127], v[154:157], v[186:189], v[124:127]
	v_mfma_i32_16x16x64_i8 v[120:123], v[162:165], v[186:189], v[120:123]
	v_mfma_i32_16x16x64_i8 v[108:111], v[154:157], v[194:197], v[108:111]
	v_mfma_i32_16x16x64_i8 v[104:107], v[162:165], v[194:197], v[104:107]
	v_mfma_i32_16x16x64_i8 v[92:95], v[154:157], v[202:205], v[92:95]
	v_mfma_i32_16x16x64_i8 v[88:91], v[162:165], v[202:205], v[88:91]
	v_mfma_i32_16x16x64_i8 v[76:79], v[154:157], v[210:213], v[76:79]
	v_mfma_i32_16x16x64_i8 v[72:75], v[162:165], v[210:213], v[72:75]
	v_mfma_i32_16x16x64_i8 v[124:127], v[158:161], v[190:193], v[124:127]
	v_mfma_i32_16x16x64_i8 v[120:123], v[166:169], v[190:193], v[120:123]
	v_mfma_i32_16x16x64_i8 v[108:111], v[158:161], v[198:201], v[108:111]
	v_mfma_i32_16x16x64_i8 v[104:107], v[166:169], v[198:201], v[104:107]
	v_mfma_i32_16x16x64_i8 v[92:95], v[158:161], v[206:209], v[92:95]
	v_mfma_i32_16x16x64_i8 v[88:91], v[166:169], v[206:209], v[88:91]
	v_mfma_i32_16x16x64_i8 v[76:79], v[158:161], v[214:217], v[76:79]
	v_mfma_i32_16x16x64_i8 v[72:75], v[166:169], v[214:217], v[72:75]
	s_setprio 0
	s_setprio 1
	v_mfma_i32_16x16x64_i8 v[116:119], v[170:173], v[186:189], v[116:119]
	v_mfma_i32_16x16x64_i8 v[112:115], v[178:181], v[186:189], v[112:115]
	v_mfma_i32_16x16x64_i8 v[100:103], v[170:173], v[194:197], v[100:103]
	v_mfma_i32_16x16x64_i8 v[96:99], v[178:181], v[194:197], v[96:99]
	v_mfma_i32_16x16x64_i8 v[84:87], v[170:173], v[202:205], v[84:87]
	v_mfma_i32_16x16x64_i8 v[80:83], v[178:181], v[202:205], v[80:83]
	v_mfma_i32_16x16x64_i8 v[68:71], v[170:173], v[210:213], v[68:71]
	v_mfma_i32_16x16x64_i8 v[64:67], v[178:181], v[210:213], v[64:67]
	v_mfma_i32_16x16x64_i8 v[116:119], v[174:177], v[190:193], v[116:119]
	v_mfma_i32_16x16x64_i8 v[112:115], v[182:185], v[190:193], v[112:115]
	v_mfma_i32_16x16x64_i8 v[100:103], v[174:177], v[198:201], v[100:103]
	v_mfma_i32_16x16x64_i8 v[96:99], v[182:185], v[198:201], v[96:99]
	v_mfma_i32_16x16x64_i8 v[84:87], v[174:177], v[206:209], v[84:87]
	v_mfma_i32_16x16x64_i8 v[80:83], v[182:185], v[206:209], v[80:83]
	v_mfma_i32_16x16x64_i8 v[68:71], v[174:177], v[214:217], v[68:71]
	v_mfma_i32_16x16x64_i8 v[64:67], v[182:185], v[214:217], v[64:67]
	s_setprio 0
	s_barrier
; #define PG8_STAGE(bufoff, gbase, voff) do { _Pragma("unroll") for (int _i = 0; _i < 2; ++_i) \
;         __builtin_amdgcn_global_load_lds((const unsigned*)((const char*)(gbase) + (voff)[_i]), (LAS unsigned*)(lds + (bufoff) + ldsw + _i * 8192), 16, 0, 0); } while (0)
; #define PG8_LDA(dst, b, h) do { _Pragma("unroll") for (int m = 0; m < 4; ++m) _Pragma("unroll") for (int k = 0; k < 2; ++k) dst[m][k] = *(const LAS bf16x8*)(lds + PG8_SA(b, h) + aoff + m * 2048 + k * 1024); } while (0)
; #define PG8_WAIT_V(n) asm volatile("s_waitcnt vmcnt(" #n ")" ::: "memory")
; #define PG8_WAIT_L(n) asm volatile("s_waitcnt lgkmcnt(" #n ")" ::: "memory")
; #define PG8_BAR __builtin_amdgcn_s_barrier()
; #define PG8_SCHED __builtin_amdgcn_sched_barrier(0)
;     ...
;             PG8_LDA(At, 1, 1); PG8_STAGE(PG8_SB(1, 0), b3, voffB); PG8_STAGE(PG8_SB(1, 1), b3 + hstep, voffB); PG8_STAGE(PG8_SA(1, 0), a3, voffA);
;             PG8_WAIT_V(8); PG8_WAIT_L(0); PG8_BAR; PG8_MMA(1, 0, At, B0); PG8_MMA(1, 1, At, B1); PG8_BAR; PG8_SCHED;
;         }
	s_mov_b32 m0, s78
	v_lshl_add_u64 v[144:145], v[144:145], 0, s[18:19]
	ds_read_b128 v[186:189], v148 offset:49152
	ds_read_b128 v[190:193], v148 offset:50176
	ds_read_b128 v[194:197], v148 offset:51200
	ds_read_b128 v[198:201], v148 offset:52224
	ds_read_b128 v[202:205], v148 offset:53248
	ds_read_b128 v[206:209], v148 offset:54272
	ds_read_b128 v[210:213], v148 offset:55296
	ds_read_b128 v[214:217], v148 offset:56320
	global_load_lds_dwordx4 v[144:145], off
	v_lshl_add_u64 v[144:145], v[218:219], 0, s[18:19]
	s_mov_b32 m0, s77
	s_nop 0
	global_load_lds_dwordx4 v[144:145], off
	v_lshl_add_u64 v[144:145], s[42:43], 0, v[130:131]
	s_mov_b32 m0, s86
	s_nop 0
	global_load_lds_dwordx4 v[144:145], off
	v_lshl_add_u64 v[144:145], s[42:43], 0, v[134:135]
	s_mov_b32 m0, s85
	s_nop 0
	global_load_lds_dwordx4 v[144:145], off
	v_lshl_add_u64 v[144:145], v[220:221], 0, s[18:19]
	s_mov_b32 m0, s68
	s_nop 0
	global_load_lds_dwordx4 v[144:145], off
	v_lshl_add_u64 v[144:145], v[222:223], 0, s[18:19]
	s_mov_b32 m0, s69
	s_nop 0
	global_load_lds_dwordx4 v[144:145], off
	s_waitcnt vmcnt(8)
	s_waitcnt lgkmcnt(0)
	s_barrier
	s_setprio 1
	s_waitcnt lgkmcnt(0)
	v_mfma_i32_16x16x64_i8 v[60:63], v[154:157], v[186:189], v[60:63]
	v_mfma_i32_16x16x64_i8 v[56:59], v[162:165], v[186:189], v[56:59]
	v_mfma_i32_16x16x64_i8 v[44:47], v[154:157], v[194:197], v[44:47]
	v_mfma_i32_16x16x64_i8 v[40:43], v[162:165], v[194:197], v[40:43]
	v_mfma_i32_16x16x64_i8 v[28:31], v[154:157], v[202:205], v[28:31]
	v_mfma_i32_16x16x64_i8 v[24:27], v[162:165], v[202:205], v[24:27]
	v_mfma_i32_16x16x64_i8 v[12:15], v[154:157], v[210:213], v[12:15]
	v_mfma_i32_16x16x64_i8 v[8:11], v[162:165], v[210:213], v[8:11]
	v_mfma_i32_16x16x64_i8 v[60:63], v[158:161], v[190:193], v[60:63]
	v_mfma_i32_16x16x64_i8 v[56:59], v[166:169], v[190:193], v[56:59]
	v_mfma_i32_16x16x64_i8 v[44:47], v[158:161], v[198:201], v[44:47]
	v_mfma_i32_16x16x64_i8 v[40:43], v[166:169], v[198:201], v[40:43]
	v_mfma_i32_16x16x64_i8 v[28:31], v[158:161], v[206:209], v[28:31]
	v_mfma_i32_16x16x64_i8 v[24:27], v[166:169], v[206:209], v[24:27]
	v_mfma_i32_16x16x64_i8 v[12:15], v[158:161], v[214:217], v[12:15]
	v_mfma_i32_16x16x64_i8 v[8:11], v[166:169], v[214:217], v[8:11]
	s_setprio 0
	s_setprio 1
	v_mfma_i32_16x16x64_i8 v[52:55], v[170:173], v[186:189], v[52:55]
	v_mfma_i32_16x16x64_i8 v[48:51], v[178:181], v[186:189], v[48:51]
	v_mfma_i32_16x16x64_i8 v[36:39], v[170:173], v[194:197], v[36:39]
	v_mfma_i32_16x16x64_i8 v[32:35], v[178:181], v[194:197], v[32:35]
	v_mfma_i32_16x16x64_i8 v[20:23], v[170:173], v[202:205], v[20:23]
	v_mfma_i32_16x16x64_i8 v[16:19], v[178:181], v[202:205], v[16:19]
	v_mfma_i32_16x16x64_i8 v[4:7], v[170:173], v[210:213], v[4:7]
	v_mfma_i32_16x16x64_i8 v[0:3], v[178:181], v[210:213], v[0:3]
	v_mfma_i32_16x16x64_i8 v[52:55], v[174:177], v[190:193], v[52:55]
	v_mfma_i32_16x16x64_i8 v[48:51], v[182:185], v[190:193], v[48:51]
	v_mfma_i32_16x16x64_i8 v[36:39], v[174:177], v[198:201], v[36:39]
	v_mfma_i32_16x16x64_i8 v[32:35], v[182:185], v[198:201], v[32:35]
	v_mfma_i32_16x16x64_i8 v[20:23], v[174:177], v[206:209], v[20:23]
	v_mfma_i32_16x16x64_i8 v[16:19], v[182:185], v[206:209], v[16:19]
	v_mfma_i32_16x16x64_i8 v[4:7], v[174:177], v[214:217], v[4:7]
	v_mfma_i32_16x16x64_i8 v[0:3], v[182:185], v[214:217], v[0:3]
	s_setprio 0
	s_barrier
	s_movk_i32 s44, 0x100
	s_andn2_b64 vcc, exec, s[40:41]
	s_mov_b64 s[42:43], -1
	s_mov_b64 s[40:41], 0
	s_cbranch_vccz .LBB0_4138

; #define PG8_STAGE(bufoff, gbase, voff) do { _Pragma("unroll") for (int _i = 0; _i < 2; ++_i) \
;         __builtin_amdgcn_global_load_lds((const unsigned*)((const char*)(gbase) + (voff)[_i]), (LAS unsigned*)(lds + (bufoff) + ldsw + _i * 8192), 16, 0, 0); } while (0)
; #define PG8_LDA(dst, b, h) do { _Pragma("unroll") for (int m = 0; m < 4; ++m) _Pragma("unroll") for (int k = 0; k < 2; ++k) dst[m][k] = *(const LAS bf16x8*)(lds + PG8_SA(b, h) + aoff + m * 2048 + k * 1024); } while (0)
; #define PG8_LDB(dst, b, h) do { _Pragma("unroll") for (int n = 0; n < 2; ++n) _Pragma("unroll") for (int k = 0; k < 2; ++k) dst[n][k] = *(const LAS bf16x8*)(lds + PG8_SB(b, h) + boff + n * 2048 + k * 1024); } while (0)
; #define PG8_WAIT_V(n) asm volatile("s_waitcnt vmcnt(" #n ")" ::: "memory")
; #define PG8_WAIT_L(n) asm volatile("s_waitcnt lgkmcnt(" #n ")" ::: "memory")
; #define PG8_BAR __builtin_amdgcn_s_barrier()
; #define PG8_SCHED __builtin_amdgcn_sched_barrier(0)
;     ...
;         const char* nA = has_next ? (const char*)g.A + (size_t)nxt.pm * tstep + (size_t)nxt.kt0 * kstep : cA; const char* nB = has_next ? (const char*)g.Bt + (size_t)nxt.e * g.estride + (size_t)nxt.pn * tstep + (size_t)nxt.kt0 * kstep : cB;
;         const int nt = cur.nkt;
;         for (int t = 0; t < nt; t += 2) {
;             const bool last = (t == nt - 2);
;             const char* a1 = cA + (size_t)(t + 1) * kstep;
;             const char* a2 = last ? nA : cA + (size_t)(t + 2) * kstep; const char* b2 = last ? nB : cB + (size_t)(t + 2) * kstep;
;             const char* a3 = a2 + kstep; const char* b3 = b2 + kstep;
;             PG8_LDB(B0, 0, 0); PG8_LDB(B1, 0, 1); PG8_SCHED; PG8_LDA(At, 0, 0); PG8_STAGE(PG8_SA(1, 1), a1 + hstep, voffA);
;             PG8_WAIT_V(8); PG8_WAIT_L(0); PG8_BAR; PG8_MMA(0, 0, At, B0); PG8_MMA(0, 1, At, B1); PG8_BAR; PG8_SCHED;
;             PG8_LDA(At, 0, 1); PG8_STAGE(PG8_SB(0, 0), b2, voffB); PG8_STAGE(PG8_SB(0, 1), b2 + hstep, voffB); PG8_STAGE(PG8_SA(0, 0), a2, voffA);
;             PG8_WAIT_V(8); PG8_WAIT_L(0); PG8_BAR; PG8_MMA(1, 0, At, B0); PG8_MMA(1, 1, At, B1); PG8_BAR; PG8_SCHED;
.LBB0_4161:
	s_ashr_i32 s27, s26, 31
	s_lshl_b64 s[6:7], s[26:27], 17
	s_add_u32 s28, s23, s6
	s_addc_u32 s29, s34, s7
	s_and_b64 s[6:7], s[2:3], exec
	s_cselect_b32 s27, s29, s39
	s_cselect_b32 s70, s28, s38
	s_ashr_i32 s25, s24, 31
	s_lshl_b64 s[6:7], s[24:25], 17
	s_add_u32 s30, s21, s6
	s_addc_u32 s31, s35, s7
	s_and_b64 s[6:7], s[2:3], exec
	s_cselect_b32 s25, s31, s37
	s_cselect_b32 s71, s30, s36
	s_mov_b32 s42, 0
	s_mov_b64 s[6:7], -1
	s_mov_b64 s[40:41], 0
	s_add_u32 s43, s38, s42
	s_addc_u32 s48, s39, 0
	s_add_u32 s46, s43, 0x100
	s_addc_u32 s47, s48, 0
	s_and_b64 s[44:45], s[40:41], exec
	s_cselect_b32 s45, s27, s47
	s_cselect_b32 s44, s70, s46
	s_add_u32 s42, s36, s42
	s_addc_u32 s46, s37, 0
	s_add_u32 s42, s42, 0x100
	s_addc_u32 s46, s46, 0
	s_and_b64 s[40:41], s[40:41], exec
	s_cselect_b32 s47, s25, s46
	s_cselect_b32 s46, s71, s42
	s_add_u32 s50, s43, 0x10080
	s_addc_u32 s51, s48, 0
	s_add_i32 s79, s66, s55
	s_add_i32 m0, s58, 0xc000
	s_add_i32 s82, s58, 0xe000
	s_add_i32 s76, s79, 0x2000
	v_add_u32_e32 v142, s66, v144
	s_add_u32 s48, s46, 0x10000
	ds_read_b128 v[152:155], v142
	ds_read_b128 v[156:159], v142 offset:1024
	ds_read_b128 v[160:163], v142 offset:2048
	ds_read_b128 v[164:167], v142 offset:3072
	v_add_u32_e32 v142, s67, v144
	s_addc_u32 s49, s47, 0
	s_add_i32 s78, s67, s55
	ds_read_b128 v[168:171], v142
	ds_read_b128 v[172:175], v142 offset:1024
	ds_read_b128 v[176:179], v142 offset:2048
	ds_read_b128 v[180:183], v142 offset:3072
	s_add_i32 s77, s78, 0x2000
	s_add_i32 s75, 0, 0x18000
	s_add_i32 s74, 0, 0x1c000
	s_add_u32 s42, s44, 0x10000
	s_addc_u32 s43, s45, 0
	s_add_i32 s73, s75, s55
	s_add_i32 s72, s73, 0x2000
	s_add_u32 s40, s46, 0x10080
	s_addc_u32 s41, s47, 0
	s_add_i32 s81, s74, s55
	s_add_i32 s80, s81, 0x2000
	v_lshl_add_u64 v[142:143], s[50:51], 0, v[128:129]
	ds_read_b128 v[184:187], v147
	ds_read_b128 v[188:191], v147 offset:1024
	ds_read_b128 v[192:195], v147 offset:2048
	ds_read_b128 v[196:199], v147 offset:3072
	ds_read_b128 v[200:203], v147 offset:4096
	ds_read_b128 v[204:207], v147 offset:5120
	ds_read_b128 v[208:211], v147 offset:6144
	ds_read_b128 v[212:215], v147 offset:7168
	global_load_lds_dwordx4 v[142:143], off
	v_lshl_add_u64 v[142:143], s[50:51], 0, v[132:133]
	s_mov_b32 m0, s82
	s_nop 0
	global_load_lds_dwordx4 v[142:143], off
	s_waitcnt vmcnt(8)
	s_waitcnt lgkmcnt(0)
	s_barrier
	s_setprio 1
	s_waitcnt lgkmcnt(0)
	v_mfma_i32_16x16x64_i8 v[124:127], v[184:187], v[152:155], 0
	v_mfma_i32_16x16x64_i8 v[120:123], v[184:187], v[160:163], 0
	v_mfma_i32_16x16x64_i8 v[108:111], v[192:195], v[152:155], 0
	v_mfma_i32_16x16x64_i8 v[104:107], v[192:195], v[160:163], 0
	v_mfma_i32_16x16x64_i8 v[92:95], v[200:203], v[152:155], 0
	v_mfma_i32_16x16x64_i8 v[88:91], v[200:203], v[160:163], 0
	v_mfma_i32_16x16x64_i8 v[76:79], v[208:211], v[152:155], 0
	v_mfma_i32_16x16x64_i8 v[72:75], v[208:211], v[160:163], 0
	v_mfma_i32_16x16x64_i8 v[124:127], v[188:191], v[156:159], v[124:127]
	v_mfma_i32_16x16x64_i8 v[120:123], v[188:191], v[164:167], v[120:123]
	v_mfma_i32_16x16x64_i8 v[108:111], v[196:199], v[156:159], v[108:111]
	v_mfma_i32_16x16x64_i8 v[104:107], v[196:199], v[164:167], v[104:107]
	v_mfma_i32_16x16x64_i8 v[92:95], v[204:207], v[156:159], v[92:95]
	v_mfma_i32_16x16x64_i8 v[88:91], v[204:207], v[164:167], v[88:91]
	v_mfma_i32_16x16x64_i8 v[76:79], v[212:215], v[156:159], v[76:79]
	v_mfma_i32_16x16x64_i8 v[72:75], v[212:215], v[164:167], v[72:75]
	s_setprio 0
	s_setprio 1
	v_mfma_i32_16x16x64_i8 v[116:119], v[184:187], v[168:171], 0
	v_mfma_i32_16x16x64_i8 v[112:115], v[184:187], v[176:179], 0
	v_mfma_i32_16x16x64_i8 v[100:103], v[192:195], v[168:171], 0
	v_mfma_i32_16x16x64_i8 v[96:99], v[192:195], v[176:179], 0
	v_mfma_i32_16x16x64_i8 v[84:87], v[200:203], v[168:171], 0
	v_mfma_i32_16x16x64_i8 v[80:83], v[200:203], v[176:179], 0
	v_mfma_i32_16x16x64_i8 v[68:71], v[208:211], v[168:171], 0
	v_mfma_i32_16x16x64_i8 v[64:67], v[208:211], v[176:179], 0
	v_mfma_i32_16x16x64_i8 v[116:119], v[188:191], v[172:175], v[116:119]
	v_mfma_i32_16x16x64_i8 v[112:115], v[188:191], v[180:183], v[112:115]
	v_mfma_i32_16x16x64_i8 v[100:103], v[196:199], v[172:175], v[100:103]
	v_mfma_i32_16x16x64_i8 v[96:99], v[196:199], v[180:183], v[96:99]
	v_mfma_i32_16x16x64_i8 v[84:87], v[204:207], v[172:175], v[84:87]
	v_mfma_i32_16x16x64_i8 v[80:83], v[204:207], v[180:183], v[80:83]
	v_mfma_i32_16x16x64_i8 v[68:71], v[212:215], v[172:175], v[68:71]
	v_mfma_i32_16x16x64_i8 v[64:67], v[212:215], v[180:183], v[64:67]
	s_setprio 0
	s_barrier
	s_mov_b32 m0, s79
	v_lshl_add_u64 v[142:143], s[46:47], 0, v[130:131]
	ds_read_b128 v[184:187], v147 offset:16384
	ds_read_b128 v[188:191], v147 offset:17408
	ds_read_b128 v[192:195], v147 offset:18432
	ds_read_b128 v[196:199], v147 offset:19456
	ds_read_b128 v[200:203], v147 offset:20480
	ds_read_b128 v[204:207], v147 offset:21504
	ds_read_b128 v[208:211], v147 offset:22528
	ds_read_b128 v[212:215], v147 offset:23552
	global_load_lds_dwordx4 v[142:143], off
	v_lshl_add_u64 v[216:217], s[46:47], 0, v[134:135]
	s_mov_b32 m0, s76
	v_lshl_add_u64 v[218:219], s[48:49], 0, v[130:131]
	global_load_lds_dwordx4 v[216:217], off
	s_mov_b32 m0, s78
	v_lshl_add_u64 v[220:221], s[44:45], 0, v[132:133]
	global_load_lds_dwordx4 v[218:219], off
	v_lshl_add_u64 v[218:219], s[48:49], 0, v[134:135]
	s_mov_b32 m0, s77
	s_nop 0
	global_load_lds_dwordx4 v[218:219], off
	v_lshl_add_u64 v[218:219], s[44:45], 0, v[128:129]
	s_mov_b32 m0, s58
	s_nop 0
	global_load_lds_dwordx4 v[218:219], off
	s_mov_b32 m0, s59
	s_nop 0
	global_load_lds_dwordx4 v[220:221], off
	s_waitcnt vmcnt(8)
	s_waitcnt lgkmcnt(0)
	s_barrier
; #define PG8_STAGE(bufoff, gbase, voff) do { _Pragma("unroll") for (int _i = 0; _i < 2; ++_i) \
;         __builtin_amdgcn_global_load_lds((const unsigned*)((const char*)(gbase) + (voff)[_i]), (LAS unsigned*)(lds + (bufoff) + ldsw + _i * 8192), 16, 0, 0); } while (0)
; #define PG8_LDA(dst, b, h) do { _Pragma("unroll") for (int m = 0; m < 4; ++m) _Pragma("unroll") for (int k = 0; k < 2; ++k) dst[m][k] = *(const LAS bf16x8*)(lds + PG8_SA(b, h) + aoff + m * 2048 + k * 1024); } while (0)
; #define PG8_LDB(dst, b, h) do { _Pragma("unroll") for (int n = 0; n < 2; ++n) _Pragma("unroll") for (int k = 0; k < 2; ++k) dst[n][k] = *(const LAS bf16x8*)(lds + PG8_SB(b, h) + boff + n * 2048 + k * 1024); } while (0)
; #define PG8_WAIT_V(n) asm volatile("s_waitcnt vmcnt(" #n ")" ::: "memory")
; #define PG8_WAIT_L(n) asm volatile("s_waitcnt lgkmcnt(" #n ")" ::: "memory")
; #define PG8_BAR __builtin_amdgcn_s_barrier()
; #define PG8_SCHED __builtin_amdgcn_sched_barrier(0)
;     ...
;             PG8_WAIT_V(8); PG8_WAIT_L(0); PG8_BAR; PG8_MMA(1, 0, At, B0); PG8_MMA(1, 1, At, B1); PG8_BAR; PG8_SCHED;
;             PG8_LDB(B0, 1, 0); PG8_LDB(B1, 1, 1); PG8_SCHED; PG8_LDA(At, 1, 0); PG8_STAGE(PG8_SA(0, 1), a2 + hstep, voffA);
;             PG8_WAIT_V(8); PG8_WAIT_L(0); PG8_BAR; PG8_MMA(0, 0, At, B0); PG8_MMA(0, 1, At, B1); PG8_BAR; PG8_SCHED;
	s_setprio 1
	s_waitcnt lgkmcnt(0)
	v_mfma_i32_16x16x64_i8 v[60:63], v[184:187], v[152:155], 0
	v_mfma_i32_16x16x64_i8 v[56:59], v[184:187], v[160:163], 0
	v_mfma_i32_16x16x64_i8 v[44:47], v[192:195], v[152:155], 0
	v_mfma_i32_16x16x64_i8 v[40:43], v[192:195], v[160:163], 0
	v_mfma_i32_16x16x64_i8 v[28:31], v[200:203], v[152:155], 0
	v_mfma_i32_16x16x64_i8 v[24:27], v[200:203], v[160:163], 0
	v_mfma_i32_16x16x64_i8 v[12:15], v[208:211], v[152:155], 0
	v_mfma_i32_16x16x64_i8 v[8:11], v[208:211], v[160:163], 0
	v_mfma_i32_16x16x64_i8 v[60:63], v[188:191], v[156:159], v[60:63]
	v_mfma_i32_16x16x64_i8 v[56:59], v[188:191], v[164:167], v[56:59]
	v_mfma_i32_16x16x64_i8 v[44:47], v[196:199], v[156:159], v[44:47]
	v_mfma_i32_16x16x64_i8 v[40:43], v[196:199], v[164:167], v[40:43]
	v_mfma_i32_16x16x64_i8 v[28:31], v[204:207], v[156:159], v[28:31]
	v_mfma_i32_16x16x64_i8 v[24:27], v[204:207], v[164:167], v[24:27]
	v_mfma_i32_16x16x64_i8 v[12:15], v[212:215], v[156:159], v[12:15]
	v_mfma_i32_16x16x64_i8 v[8:11], v[212:215], v[164:167], v[8:11]
	s_setprio 0
	s_setprio 1
	v_mfma_i32_16x16x64_i8 v[52:55], v[184:187], v[168:171], 0
	v_mfma_i32_16x16x64_i8 v[48:51], v[184:187], v[176:179], 0
	v_mfma_i32_16x16x64_i8 v[36:39], v[192:195], v[168:171], 0
	v_mfma_i32_16x16x64_i8 v[32:35], v[192:195], v[176:179], 0
	v_mfma_i32_16x16x64_i8 v[20:23], v[200:203], v[168:171], 0
	v_mfma_i32_16x16x64_i8 v[16:19], v[200:203], v[176:179], 0
	v_mfma_i32_16x16x64_i8 v[4:7], v[208:211], v[168:171], 0
	v_mfma_i32_16x16x64_i8 v[0:3], v[208:211], v[176:179], 0
	v_mfma_i32_16x16x64_i8 v[52:55], v[188:191], v[172:175], v[52:55]
	v_mfma_i32_16x16x64_i8 v[48:51], v[188:191], v[180:183], v[48:51]
	v_mfma_i32_16x16x64_i8 v[36:39], v[196:199], v[172:175], v[36:39]
	v_mfma_i32_16x16x64_i8 v[32:35], v[196:199], v[180:183], v[32:35]
	v_mfma_i32_16x16x64_i8 v[20:23], v[204:207], v[172:175], v[20:23]
	v_mfma_i32_16x16x64_i8 v[16:19], v[204:207], v[180:183], v[16:19]
	v_mfma_i32_16x16x64_i8 v[4:7], v[212:215], v[172:175], v[4:7]
	v_mfma_i32_16x16x64_i8 v[0:3], v[212:215], v[180:183], v[0:3]
	s_setprio 0
	s_barrier
	v_add_u32_e32 v151, s75, v144
	ds_read_b128 v[152:155], v151
	ds_read_b128 v[156:159], v151 offset:1024
	ds_read_b128 v[160:163], v151 offset:2048
	ds_read_b128 v[164:167], v151 offset:3072
	v_add_u32_e32 v151, s74, v144
	ds_read_b128 v[168:171], v151
	ds_read_b128 v[172:175], v151 offset:1024
	ds_read_b128 v[176:179], v151 offset:2048
	ds_read_b128 v[180:183], v151 offset:3072
	s_mov_b32 m0, s60
	v_lshl_add_u64 v[222:223], s[42:43], 0, v[128:129]
	ds_read_b128 v[184:187], v147 offset:32768
	ds_read_b128 v[188:191], v147 offset:33792
	ds_read_b128 v[192:195], v147 offset:34816
	ds_read_b128 v[196:199], v147 offset:35840
	ds_read_b128 v[200:203], v147 offset:36864
	ds_read_b128 v[204:207], v147 offset:37888
	ds_read_b128 v[208:211], v147 offset:38912
	ds_read_b128 v[212:215], v147 offset:39936
	global_load_lds_dwordx4 v[222:223], off
	v_lshl_add_u64 v[222:223], s[42:43], 0, v[132:133]
	s_mov_b32 m0, s61
	s_nop 0
	global_load_lds_dwordx4 v[222:223], off
	s_waitcnt vmcnt(8)
	s_waitcnt lgkmcnt(0)
	s_barrier
	s_setprio 1
	s_waitcnt lgkmcnt(0)
	v_mfma_i32_16x16x64_i8 v[124:127], v[184:187], v[152:155], v[124:127]
	v_mfma_i32_16x16x64_i8 v[120:123], v[184:187], v[160:163], v[120:123]
	v_mfma_i32_16x16x64_i8 v[108:111], v[192:195], v[152:155], v[108:111]
	v_mfma_i32_16x16x64_i8 v[104:107], v[192:195], v[160:163], v[104:107]
	v_mfma_i32_16x16x64_i8 v[92:95], v[200:203], v[152:155], v[92:95]
	v_mfma_i32_16x16x64_i8 v[88:91], v[200:203], v[160:163], v[88:91]
	v_mfma_i32_16x16x64_i8 v[76:79], v[208:211], v[152:155], v[76:79]
	v_mfma_i32_16x16x64_i8 v[72:75], v[208:211], v[160:163], v[72:75]
	v_mfma_i32_16x16x64_i8 v[124:127], v[188:191], v[156:159], v[124:127]
	v_mfma_i32_16x16x64_i8 v[120:123], v[188:191], v[164:167], v[120:123]
	v_mfma_i32_16x16x64_i8 v[108:111], v[196:199], v[156:159], v[108:111]
	v_mfma_i32_16x16x64_i8 v[104:107], v[196:199], v[164:167], v[104:107]
	v_mfma_i32_16x16x64_i8 v[92:95], v[204:207], v[156:159], v[92:95]
	v_mfma_i32_16x16x64_i8 v[88:91], v[204:207], v[164:167], v[88:91]
	v_mfma_i32_16x16x64_i8 v[76:79], v[212:215], v[156:159], v[76:79]
	v_mfma_i32_16x16x64_i8 v[72:75], v[212:215], v[164:167], v[72:75]
	s_setprio 0
	s_setprio 1
	v_mfma_i32_16x16x64_i8 v[116:119], v[184:187], v[168:171], v[116:119]
	v_mfma_i32_16x16x64_i8 v[112:115], v[184:187], v[176:179], v[112:115]
	v_mfma_i32_16x16x64_i8 v[100:103], v[192:195], v[168:171], v[100:103]
	v_mfma_i32_16x16x64_i8 v[96:99], v[192:195], v[176:179], v[96:99]
	v_mfma_i32_16x16x64_i8 v[84:87], v[200:203], v[168:171], v[84:87]
	v_mfma_i32_16x16x64_i8 v[80:83], v[200:203], v[176:179], v[80:83]
	v_mfma_i32_16x16x64_i8 v[68:71], v[208:211], v[168:171], v[68:71]
	v_mfma_i32_16x16x64_i8 v[64:67], v[208:211], v[176:179], v[64:67]
	v_mfma_i32_16x16x64_i8 v[116:119], v[188:191], v[172:175], v[116:119]
	v_mfma_i32_16x16x64_i8 v[112:115], v[188:191], v[180:183], v[112:115]
	v_mfma_i32_16x16x64_i8 v[100:103], v[196:199], v[172:175], v[100:103]
	v_mfma_i32_16x16x64_i8 v[96:99], v[196:199], v[180:183], v[96:99]
	v_mfma_i32_16x16x64_i8 v[84:87], v[204:207], v[172:175], v[84:87]
	v_mfma_i32_16x16x64_i8 v[80:83], v[204:207], v[180:183], v[80:83]
	v_mfma_i32_16x16x64_i8 v[68:71], v[212:215], v[172:175], v[68:71]
	v_mfma_i32_16x16x64_i8 v[64:67], v[212:215], v[180:183], v[64:67]
	s_setprio 0
	s_barrier
; #define PG8_STAGE(bufoff, gbase, voff) do { _Pragma("unroll") for (int _i = 0; _i < 2; ++_i) \
;         __builtin_amdgcn_global_load_lds((const unsigned*)((const char*)(gbase) + (voff)[_i]), (LAS unsigned*)(lds + (bufoff) + ldsw + _i * 8192), 16, 0, 0); } while (0)
; #define PG8_LDA(dst, b, h) do { _Pragma("unroll") for (int m = 0; m < 4; ++m) _Pragma("unroll") for (int k = 0; k < 2; ++k) dst[m][k] = *(const LAS bf16x8*)(lds + PG8_SA(b, h) + aoff + m * 2048 + k * 1024); } while (0)
; #define PG8_WAIT_V(n) asm volatile("s_waitcnt vmcnt(" #n ")" ::: "memory")
; #define PG8_WAIT_L(n) asm volatile("s_waitcnt lgkmcnt(" #n ")" ::: "memory")
; #define PG8_BAR __builtin_amdgcn_s_barrier()
; #define PG8_SCHED __builtin_amdgcn_sched_barrier(0)
;     ...
;             PG8_LDA(At, 1, 1); PG8_STAGE(PG8_SB(1, 0), b3, voffB); PG8_STAGE(PG8_SB(1, 1), b3 + hstep, voffB); PG8_STAGE(PG8_SA(1, 0), a3, voffA);
;             PG8_WAIT_V(8); PG8_WAIT_L(0); PG8_BAR; PG8_MMA(1, 0, At, B0); PG8_MMA(1, 1, At, B1); PG8_BAR; PG8_SCHED;
;         }
	s_mov_b32 m0, s73
	v_lshl_add_u64 v[142:143], v[142:143], 0, s[14:15]
	ds_read_b128 v[184:187], v147 offset:49152
	ds_read_b128 v[188:191], v147 offset:50176
	ds_read_b128 v[192:195], v147 offset:51200
	ds_read_b128 v[196:199], v147 offset:52224
	ds_read_b128 v[200:203], v147 offset:53248
	ds_read_b128 v[204:207], v147 offset:54272
	ds_read_b128 v[208:211], v147 offset:55296
	ds_read_b128 v[212:215], v147 offset:56320
	global_load_lds_dwordx4 v[142:143], off
	v_lshl_add_u64 v[142:143], v[216:217], 0, s[14:15]
	s_mov_b32 m0, s72
	s_nop 0
	global_load_lds_dwordx4 v[142:143], off
	v_lshl_add_u64 v[142:143], s[40:41], 0, v[130:131]
	s_mov_b32 m0, s81
	s_nop 0
	global_load_lds_dwordx4 v[142:143], off
	v_lshl_add_u64 v[142:143], s[40:41], 0, v[134:135]
	s_mov_b32 m0, s80
	s_nop 0
	global_load_lds_dwordx4 v[142:143], off
	v_lshl_add_u64 v[142:143], v[218:219], 0, s[14:15]
	s_mov_b32 m0, s64
	s_nop 0
	global_load_lds_dwordx4 v[142:143], off
	v_lshl_add_u64 v[142:143], v[220:221], 0, s[14:15]
	s_mov_b32 m0, s65
	s_nop 0
	global_load_lds_dwordx4 v[142:143], off
	s_waitcnt vmcnt(8)
	s_waitcnt lgkmcnt(0)
	s_barrier
	s_setprio 1
	s_waitcnt lgkmcnt(0)
	v_mfma_i32_16x16x64_i8 v[60:63], v[184:187], v[152:155], v[60:63]
	v_mfma_i32_16x16x64_i8 v[56:59], v[184:187], v[160:163], v[56:59]
	v_mfma_i32_16x16x64_i8 v[44:47], v[192:195], v[152:155], v[44:47]
	v_mfma_i32_16x16x64_i8 v[40:43], v[192:195], v[160:163], v[40:43]
	v_mfma_i32_16x16x64_i8 v[28:31], v[200:203], v[152:155], v[28:31]
	v_mfma_i32_16x16x64_i8 v[24:27], v[200:203], v[160:163], v[24:27]
	v_mfma_i32_16x16x64_i8 v[12:15], v[208:211], v[152:155], v[12:15]
	v_mfma_i32_16x16x64_i8 v[8:11], v[208:211], v[160:163], v[8:11]
	v_mfma_i32_16x16x64_i8 v[60:63], v[188:191], v[156:159], v[60:63]
	v_mfma_i32_16x16x64_i8 v[56:59], v[188:191], v[164:167], v[56:59]
	v_mfma_i32_16x16x64_i8 v[44:47], v[196:199], v[156:159], v[44:47]
	v_mfma_i32_16x16x64_i8 v[40:43], v[196:199], v[164:167], v[40:43]
	v_mfma_i32_16x16x64_i8 v[28:31], v[204:207], v[156:159], v[28:31]
	v_mfma_i32_16x16x64_i8 v[24:27], v[204:207], v[164:167], v[24:27]
	v_mfma_i32_16x16x64_i8 v[12:15], v[212:215], v[156:159], v[12:15]
	v_mfma_i32_16x16x64_i8 v[8:11], v[212:215], v[164:167], v[8:11]
	s_setprio 0
	s_setprio 1
	v_mfma_i32_16x16x64_i8 v[52:55], v[184:187], v[168:171], v[52:55]
	v_mfma_i32_16x16x64_i8 v[48:51], v[184:187], v[176:179], v[48:51]
	v_mfma_i32_16x16x64_i8 v[36:39], v[192:195], v[168:171], v[36:39]
	v_mfma_i32_16x16x64_i8 v[32:35], v[192:195], v[176:179], v[32:35]
	v_mfma_i32_16x16x64_i8 v[20:23], v[200:203], v[168:171], v[20:23]
	v_mfma_i32_16x16x64_i8 v[16:19], v[200:203], v[176:179], v[16:19]
	v_mfma_i32_16x16x64_i8 v[4:7], v[208:211], v[168:171], v[4:7]
	v_mfma_i32_16x16x64_i8 v[0:3], v[208:211], v[176:179], v[0:3]
	v_mfma_i32_16x16x64_i8 v[52:55], v[188:191], v[172:175], v[52:55]
	v_mfma_i32_16x16x64_i8 v[48:51], v[188:191], v[180:183], v[48:51]
	v_mfma_i32_16x16x64_i8 v[36:39], v[196:199], v[172:175], v[36:39]
	v_mfma_i32_16x16x64_i8 v[32:35], v[196:199], v[180:183], v[32:35]
	v_mfma_i32_16x16x64_i8 v[20:23], v[204:207], v[172:175], v[20:23]
	v_mfma_i32_16x16x64_i8 v[16:19], v[204:207], v[180:183], v[16:19]
	v_mfma_i32_16x16x64_i8 v[4:7], v[212:215], v[172:175], v[4:7]
	v_mfma_i32_16x16x64_i8 v[0:3], v[212:215], v[180:183], v[0:3]
	s_setprio 0
	s_barrier
	s_movk_i32 s42, 0x100
	s_andn2_b64 vcc, exec, s[6:7]
	s_mov_b64 s[40:41], -1
	s_mov_b64 s[6:7], 0
	s_cbranch_vccz .LBB0_4162

; #define PG8_STAGE(bufoff, gbase, voff) do { _Pragma("unroll") for (int _i = 0; _i < 2; ++_i) \
;         __builtin_amdgcn_global_load_lds((const unsigned*)((const char*)(gbase) + (voff)[_i]), (LAS unsigned*)(lds + (bufoff) + ldsw + _i * 8192), 16, 0, 0); } while (0)
; #define PG8_LDA(dst, b, h) do { _Pragma("unroll") for (int m = 0; m < 4; ++m) _Pragma("unroll") for (int k = 0; k < 2; ++k) dst[m][k] = *(const LAS bf16x8*)(lds + PG8_SA(b, h) + aoff + m * 2048 + k * 1024); } while (0)
; #define PG8_LDB(dst, b, h) do { _Pragma("unroll") for (int n = 0; n < 2; ++n) _Pragma("unroll") for (int k = 0; k < 2; ++k) dst[n][k] = *(const LAS bf16x8*)(lds + PG8_SB(b, h) + boff + n * 2048 + k * 1024); } while (0)
; #define PG8_WAIT_V(n) asm volatile("s_waitcnt vmcnt(" #n ")" ::: "memory")
; #define PG8_WAIT_L(n) asm volatile("s_waitcnt lgkmcnt(" #n ")" ::: "memory")
; #define PG8_BAR __builtin_amdgcn_s_barrier()
; #define PG8_SCHED __builtin_amdgcn_sched_barrier(0)
;     ...
;         const char* nA = has_next ? (const char*)g.A + (size_t)nxt.pm * tstep + (size_t)nxt.kt0 * kstep : cA; const char* nB = has_next ? (const char*)g.Bt + (size_t)nxt.e * g.estride + (size_t)nxt.pn * tstep + (size_t)nxt.kt0 * kstep : cB;
;         const int nt = cur.nkt;
;         for (int t = 0; t < nt; t += 2) {
;             const bool last = (t == nt - 2);
;             const char* a1 = cA + (size_t)(t + 1) * kstep;
;             const char* a2 = last ? nA : cA + (size_t)(t + 2) * kstep; const char* b2 = last ? nB : cB + (size_t)(t + 2) * kstep;
;             const char* a3 = a2 + kstep; const char* b3 = b2 + kstep;
;             PG8_LDB(B0, 0, 0); PG8_LDB(B1, 0, 1); PG8_SCHED; PG8_LDA(At, 0, 0); PG8_STAGE(PG8_SA(1, 1), a1 + hstep, voffA);
;             PG8_WAIT_V(8); PG8_WAIT_L(0); PG8_BAR; PG8_MMA(0, 0, At, B0); PG8_MMA(0, 1, At, B1); PG8_BAR; PG8_SCHED;
;             PG8_LDA(At, 0, 1); PG8_STAGE(PG8_SB(0, 0), b2, voffB); PG8_STAGE(PG8_SB(0, 1), b2 + hstep, voffB); PG8_STAGE(PG8_SA(0, 0), a2, voffA);
;             PG8_WAIT_V(8); PG8_WAIT_L(0); PG8_BAR; PG8_MMA(1, 0, At, B0); PG8_MMA(1, 1, At, B1); PG8_BAR; PG8_SCHED;
.LBB0_4501:
	s_ashr_i32 s37, s36, 31
	s_lshl_b64 s[38:39], s[36:37], 19
	s_add_u32 s38, s25, s38
	s_addc_u32 s39, s27, s39
	s_and_b64 s[40:41], s[2:3], exec
	s_cselect_b32 s37, s39, s43
	s_cselect_b32 s63, s38, s42
	s_ashr_i32 s31, s30, 31
	s_lshl_b64 s[40:41], s[30:31], 19
	s_add_u32 s40, s29, s40
	s_addc_u32 s41, s34, s41
	s_and_b64 s[46:47], s[2:3], exec
	s_cselect_b32 s31, s41, s45
	s_cselect_b32 s64, s40, s44
	s_add_u32 s42, s42, 0x40080
	s_addc_u32 s43, s43, 0
	s_add_u32 s65, s44, 0x100
	s_addc_u32 s66, s45, 0
	s_mov_b32 s67, -2
	ds_read_b128 v[24:27], v187
	ds_read_b128 v[28:31], v187 offset:1024
	ds_read_b128 v[16:19], v187 offset:2048
	ds_read_b128 v[20:23], v187 offset:3072
	ds_read_b128 v[8:11], v188
	ds_read_b128 v[12:15], v188 offset:1024
	ds_read_b128 v[0:3], v188 offset:2048
	ds_read_b128 v[4:7], v188 offset:3072
	s_add_u32 s44, s42, 0xfffc0080
	s_addc_u32 s45, s43, -1
	s_cmp_eq_u32 s67, 12
	s_cselect_b32 s47, s37, s45
	s_cselect_b32 s46, s63, s44
	s_cselect_b32 s45, s31, s66
	s_cselect_b32 s44, s64, s65
	v_lshl_add_u64 v[216:217], s[42:43], 0, v[168:169]
	s_add_i32 m0, s48, 0xc000
	ds_read_b128 v[176:179], v189
	ds_read_b128 v[180:183], v189 offset:1024
	ds_read_b128 v[192:195], v189 offset:2048
	ds_read_b128 v[196:199], v189 offset:3072
	ds_read_b128 v[200:203], v189 offset:4096
	ds_read_b128 v[204:207], v189 offset:5120
	ds_read_b128 v[208:211], v189 offset:6144
	ds_read_b128 v[212:215], v189 offset:7168
	global_load_lds_dwordx4 v[216:217], off
	v_lshl_add_u64 v[216:217], s[42:43], 0, v[170:171]
	s_add_i32 m0, s48, 0xe000
	s_nop 0
	global_load_lds_dwordx4 v[216:217], off
	s_waitcnt vmcnt(8)
	s_waitcnt lgkmcnt(0)
	s_barrier
	s_setprio 1
	s_waitcnt lgkmcnt(0)
	v_mfma_scale_f32_16x16x128_f8f6f4 v[156:159], v[24:31], v[176:183], 0, v190, v190 op_sel_hi:[0,0,0]
	v_mfma_scale_f32_16x16x128_f8f6f4 v[152:155], v[16:23], v[176:183], 0, v190, v190 op_sel_hi:[0,0,0]
	v_mfma_scale_f32_16x16x128_f8f6f4 v[140:143], v[24:31], v[192:199], 0, v190, v190 op_sel_hi:[0,0,0]
	v_mfma_scale_f32_16x16x128_f8f6f4 v[136:139], v[16:23], v[192:199], 0, v190, v190 op_sel_hi:[0,0,0]
	v_mfma_scale_f32_16x16x128_f8f6f4 v[124:127], v[24:31], v[200:207], 0, v190, v190 op_sel_hi:[0,0,0]
	v_mfma_scale_f32_16x16x128_f8f6f4 v[120:123], v[16:23], v[200:207], 0, v190, v190 op_sel_hi:[0,0,0]
	v_mfma_scale_f32_16x16x128_f8f6f4 v[108:111], v[24:31], v[208:215], 0, v190, v190 op_sel_hi:[0,0,0]
	v_mfma_scale_f32_16x16x128_f8f6f4 v[104:107], v[16:23], v[208:215], 0, v190, v190 op_sel_hi:[0,0,0]
	s_setprio 0
	s_setprio 1
	v_mfma_scale_f32_16x16x128_f8f6f4 v[148:151], v[8:15], v[176:183], 0, v190, v190 op_sel_hi:[0,0,0]
	v_mfma_scale_f32_16x16x128_f8f6f4 v[144:147], v[0:7], v[176:183], 0, v190, v190 op_sel_hi:[0,0,0]
	v_mfma_scale_f32_16x16x128_f8f6f4 v[132:135], v[8:15], v[192:199], 0, v190, v190 op_sel_hi:[0,0,0]
	v_mfma_scale_f32_16x16x128_f8f6f4 v[128:131], v[0:7], v[192:199], 0, v190, v190 op_sel_hi:[0,0,0]
	v_mfma_scale_f32_16x16x128_f8f6f4 v[116:119], v[8:15], v[200:207], 0, v190, v190 op_sel_hi:[0,0,0]
	v_mfma_scale_f32_16x16x128_f8f6f4 v[112:115], v[0:7], v[200:207], 0, v190, v190 op_sel_hi:[0,0,0]
	v_mfma_scale_f32_16x16x128_f8f6f4 v[100:103], v[8:15], v[208:215], 0, v190, v190 op_sel_hi:[0,0,0]
	v_mfma_scale_f32_16x16x128_f8f6f4 v[96:99], v[0:7], v[208:215], 0, v190, v190 op_sel_hi:[0,0,0]
	s_setprio 0
	s_barrier
	s_add_i32 s68, s60, s35
	v_lshl_add_u64 v[176:177], s[44:45], 0, v[162:163]
	s_mov_b32 m0, s68
	ds_read_b128 v[192:195], v189 offset:16384
	ds_read_b128 v[196:199], v189 offset:17408
	ds_read_b128 v[200:203], v189 offset:18432
	ds_read_b128 v[204:207], v189 offset:19456
	ds_read_b128 v[208:211], v189 offset:20480
	ds_read_b128 v[212:215], v189 offset:21504
	ds_read_b128 v[216:219], v189 offset:22528
	ds_read_b128 v[220:223], v189 offset:23552
	global_load_lds_dwordx4 v[176:177], off
	s_add_i32 m0, s68, 0x2000
	s_add_u32 s68, s44, 0x40000
	v_lshl_add_u64 v[178:179], s[44:45], 0, v[166:167]
	s_addc_u32 s69, s45, 0
	s_add_i32 s70, s61, s35
	global_load_lds_dwordx4 v[178:179], off
	v_lshl_add_u64 v[180:181], s[68:69], 0, v[162:163]
	s_mov_b32 m0, s70
	v_lshl_add_u64 v[182:183], s[46:47], 0, v[164:165]
	global_load_lds_dwordx4 v[180:181], off
	v_lshl_add_u64 v[180:181], s[68:69], 0, v[166:167]
	s_add_i32 m0, s70, 0x2000
	s_nop 0
	global_load_lds_dwordx4 v[180:181], off
	v_lshl_add_u64 v[180:181], s[46:47], 0, v[160:161]
	s_mov_b32 m0, s48
	s_nop 0
	global_load_lds_dwordx4 v[180:181], off
	s_mov_b32 m0, s49
	s_nop 0
	global_load_lds_dwordx4 v[182:183], off
	s_waitcnt vmcnt(8)
	s_waitcnt lgkmcnt(0)
	s_barrier
	s_setprio 1
	s_waitcnt lgkmcnt(0)
	v_mfma_scale_f32_16x16x128_f8f6f4 v[92:95], v[24:31], v[192:199], 0, v190, v190 op_sel_hi:[0,0,0]
	v_mfma_scale_f32_16x16x128_f8f6f4 v[88:91], v[16:23], v[192:199], 0, v190, v190 op_sel_hi:[0,0,0]
	v_mfma_scale_f32_16x16x128_f8f6f4 v[76:79], v[24:31], v[200:207], 0, v190, v190 op_sel_hi:[0,0,0]
	v_mfma_scale_f32_16x16x128_f8f6f4 v[72:75], v[16:23], v[200:207], 0, v190, v190 op_sel_hi:[0,0,0]
	v_mfma_scale_f32_16x16x128_f8f6f4 v[60:63], v[24:31], v[208:215], 0, v190, v190 op_sel_hi:[0,0,0]
	v_mfma_scale_f32_16x16x128_f8f6f4 v[56:59], v[16:23], v[208:215], 0, v190, v190 op_sel_hi:[0,0,0]
	v_mfma_scale_f32_16x16x128_f8f6f4 v[44:47], v[24:31], v[216:223], 0, v190, v190 op_sel_hi:[0,0,0]
	v_mfma_scale_f32_16x16x128_f8f6f4 v[40:43], v[16:23], v[216:223], 0, v190, v190 op_sel_hi:[0,0,0]
	s_setprio 0
	s_setprio 1
	v_mfma_scale_f32_16x16x128_f8f6f4 v[84:87], v[8:15], v[192:199], 0, v190, v190 op_sel_hi:[0,0,0]
	v_mfma_scale_f32_16x16x128_f8f6f4 v[80:83], v[0:7], v[192:199], 0, v190, v190 op_sel_hi:[0,0,0]
	v_mfma_scale_f32_16x16x128_f8f6f4 v[68:71], v[8:15], v[200:207], 0, v190, v190 op_sel_hi:[0,0,0]
	v_mfma_scale_f32_16x16x128_f8f6f4 v[64:67], v[0:7], v[200:207], 0, v190, v190 op_sel_hi:[0,0,0]
	v_mfma_scale_f32_16x16x128_f8f6f4 v[52:55], v[8:15], v[208:215], 0, v190, v190 op_sel_hi:[0,0,0]
	v_mfma_scale_f32_16x16x128_f8f6f4 v[48:51], v[0:7], v[208:215], 0, v190, v190 op_sel_hi:[0,0,0]
	v_mfma_scale_f32_16x16x128_f8f6f4 v[36:39], v[8:15], v[216:223], 0, v190, v190 op_sel_hi:[0,0,0]
	v_mfma_scale_f32_16x16x128_f8f6f4 v[32:35], v[0:7], v[216:223], 0, v190, v190 op_sel_hi:[0,0,0]
	s_setprio 0
	s_barrier
; #define PG8_STAGE(bufoff, gbase, voff) do { _Pragma("unroll") for (int _i = 0; _i < 2; ++_i) \
;         __builtin_amdgcn_global_load_lds((const unsigned*)((const char*)(gbase) + (voff)[_i]), (LAS unsigned*)(lds + (bufoff) + ldsw + _i * 8192), 16, 0, 0); } while (0)
; #define PG8_LDA(dst, b, h) do { _Pragma("unroll") for (int m = 0; m < 4; ++m) _Pragma("unroll") for (int k = 0; k < 2; ++k) dst[m][k] = *(const LAS bf16x8*)(lds + PG8_SA(b, h) + aoff + m * 2048 + k * 1024); } while (0)
; #define PG8_LDB(dst, b, h) do { _Pragma("unroll") for (int n = 0; n < 2; ++n) _Pragma("unroll") for (int k = 0; k < 2; ++k) dst[n][k] = *(const LAS bf16x8*)(lds + PG8_SB(b, h) + boff + n * 2048 + k * 1024); } while (0)
; #define PG8_WAIT_V(n) asm volatile("s_waitcnt vmcnt(" #n ")" ::: "memory")
; #define PG8_WAIT_L(n) asm volatile("s_waitcnt lgkmcnt(" #n ")" ::: "memory")
; #define PG8_BAR __builtin_amdgcn_s_barrier()
; #define PG8_SCHED __builtin_amdgcn_sched_barrier(0)
;     ...
;             PG8_LDB(B0, 1, 0); PG8_LDB(B1, 1, 1); PG8_SCHED; PG8_LDA(At, 1, 0); PG8_STAGE(PG8_SA(0, 1), a2 + hstep, voffA);
;             PG8_WAIT_V(8); PG8_WAIT_L(0); PG8_BAR; PG8_MMA(0, 0, At, B0); PG8_MMA(0, 1, At, B1); PG8_BAR; PG8_SCHED;
;             PG8_LDA(At, 1, 1); PG8_STAGE(PG8_SB(1, 0), b3, voffB); PG8_STAGE(PG8_SB(1, 1), b3 + hstep, voffB); PG8_STAGE(PG8_SA(1, 0), a3, voffA);
;             PG8_WAIT_V(8); PG8_WAIT_L(0); PG8_BAR; PG8_MMA(1, 0, At, B0); PG8_MMA(1, 1, At, B1); PG8_BAR; PG8_SCHED;
;         }
	s_add_i32 s68, 0, 0x18000
	s_add_i32 s69, 0, 0x1c000
	v_add_u32_e32 v12, s68, v185
	v_add_u32_e32 v28, s69, v185
	ds_read_b128 v[0:3], v12
	ds_read_b128 v[4:7], v12 offset:1024
	ds_read_b128 v[8:11], v12 offset:2048
	ds_read_b128 v[12:15], v12 offset:3072
	ds_read_b128 v[16:19], v28
	ds_read_b128 v[20:23], v28 offset:1024
	ds_read_b128 v[24:27], v28 offset:2048
	ds_read_b128 v[28:31], v28 offset:3072
	s_add_u32 s46, s46, 0x40000
	s_addc_u32 s47, s47, 0
	s_mov_b32 m0, s50
	v_lshl_add_u64 v[224:225], s[46:47], 0, v[160:161]
	ds_read_b128 v[192:195], v189 offset:32768
	ds_read_b128 v[196:199], v189 offset:33792
	ds_read_b128 v[200:203], v189 offset:34816
	ds_read_b128 v[204:207], v189 offset:35840
	ds_read_b128 v[208:211], v189 offset:36864
	ds_read_b128 v[212:215], v189 offset:37888
	ds_read_b128 v[216:219], v189 offset:38912
	ds_read_b128 v[220:223], v189 offset:39936
	global_load_lds_dwordx4 v[224:225], off
	v_lshl_add_u64 v[224:225], s[46:47], 0, v[164:165]
	s_mov_b32 m0, s51
	s_nop 0
	global_load_lds_dwordx4 v[224:225], off
	s_waitcnt vmcnt(8)
	s_waitcnt lgkmcnt(0)
	s_barrier
	s_setprio 1
	s_waitcnt lgkmcnt(0)
	v_mfma_scale_f32_16x16x128_f8f6f4 v[156:159], v[0:7], v[192:199], v[156:159], v190, v190 op_sel_hi:[0,0,0]
	v_mfma_scale_f32_16x16x128_f8f6f4 v[152:155], v[8:15], v[192:199], v[152:155], v190, v190 op_sel_hi:[0,0,0]
	v_mfma_scale_f32_16x16x128_f8f6f4 v[140:143], v[0:7], v[200:207], v[140:143], v190, v190 op_sel_hi:[0,0,0]
	v_mfma_scale_f32_16x16x128_f8f6f4 v[136:139], v[8:15], v[200:207], v[136:139], v190, v190 op_sel_hi:[0,0,0]
	v_mfma_scale_f32_16x16x128_f8f6f4 v[124:127], v[0:7], v[208:215], v[124:127], v190, v190 op_sel_hi:[0,0,0]
	v_mfma_scale_f32_16x16x128_f8f6f4 v[120:123], v[8:15], v[208:215], v[120:123], v190, v190 op_sel_hi:[0,0,0]
	v_mfma_scale_f32_16x16x128_f8f6f4 v[108:111], v[0:7], v[216:223], v[108:111], v190, v190 op_sel_hi:[0,0,0]
	v_mfma_scale_f32_16x16x128_f8f6f4 v[104:107], v[8:15], v[216:223], v[104:107], v190, v190 op_sel_hi:[0,0,0]
	s_setprio 0
	s_setprio 1
	v_mfma_scale_f32_16x16x128_f8f6f4 v[148:151], v[16:23], v[192:199], v[148:151], v190, v190 op_sel_hi:[0,0,0]
	v_mfma_scale_f32_16x16x128_f8f6f4 v[144:147], v[24:31], v[192:199], v[144:147], v190, v190 op_sel_hi:[0,0,0]
	v_mfma_scale_f32_16x16x128_f8f6f4 v[132:135], v[16:23], v[200:207], v[132:135], v190, v190 op_sel_hi:[0,0,0]
	v_mfma_scale_f32_16x16x128_f8f6f4 v[128:131], v[24:31], v[200:207], v[128:131], v190, v190 op_sel_hi:[0,0,0]
	v_mfma_scale_f32_16x16x128_f8f6f4 v[116:119], v[16:23], v[208:215], v[116:119], v190, v190 op_sel_hi:[0,0,0]
	v_mfma_scale_f32_16x16x128_f8f6f4 v[112:115], v[24:31], v[208:215], v[112:115], v190, v190 op_sel_hi:[0,0,0]
	v_mfma_scale_f32_16x16x128_f8f6f4 v[100:103], v[16:23], v[216:223], v[100:103], v190, v190 op_sel_hi:[0,0,0]
	v_mfma_scale_f32_16x16x128_f8f6f4 v[96:99], v[24:31], v[216:223], v[96:99], v190, v190 op_sel_hi:[0,0,0]
	s_setprio 0
	s_barrier
	s_add_i32 s46, s68, s35
	v_lshl_add_u64 v[176:177], v[176:177], 0, s[18:19]
	s_mov_b32 m0, s46
	ds_read_b128 v[192:195], v189 offset:49152
	ds_read_b128 v[196:199], v189 offset:50176
	ds_read_b128 v[200:203], v189 offset:51200
	ds_read_b128 v[204:207], v189 offset:52224
	ds_read_b128 v[208:211], v189 offset:53248
	ds_read_b128 v[212:215], v189 offset:54272
	ds_read_b128 v[216:219], v189 offset:55296
	ds_read_b128 v[220:223], v189 offset:56320
	global_load_lds_dwordx4 v[176:177], off
	s_add_i32 m0, s46, 0x2000
	s_add_u32 s44, s44, 0x40080
	v_lshl_add_u64 v[176:177], v[178:179], 0, s[18:19]
	s_addc_u32 s45, s45, 0
	s_add_i32 s46, s69, s35
	global_load_lds_dwordx4 v[176:177], off
	v_lshl_add_u64 v[176:177], s[44:45], 0, v[162:163]
	s_mov_b32 m0, s46
	s_nop 0
	global_load_lds_dwordx4 v[176:177], off
	v_lshl_add_u64 v[176:177], s[44:45], 0, v[166:167]
	s_add_i32 m0, s46, 0x2000
	s_nop 0
	global_load_lds_dwordx4 v[176:177], off
	v_lshl_add_u64 v[176:177], v[180:181], 0, s[18:19]
	s_mov_b32 m0, s55
	s_nop 0
	global_load_lds_dwordx4 v[176:177], off
	v_lshl_add_u64 v[176:177], v[182:183], 0, s[18:19]
	s_mov_b32 m0, s58
	s_nop 0
	global_load_lds_dwordx4 v[176:177], off
	s_waitcnt vmcnt(8)
	s_waitcnt lgkmcnt(0)
	s_barrier
	s_setprio 1
	s_waitcnt lgkmcnt(0)
	v_mfma_scale_f32_16x16x128_f8f6f4 v[92:95], v[0:7], v[192:199], v[92:95], v190, v190 op_sel_hi:[0,0,0]
	v_mfma_scale_f32_16x16x128_f8f6f4 v[88:91], v[8:15], v[192:199], v[88:91], v190, v190 op_sel_hi:[0,0,0]
	v_mfma_scale_f32_16x16x128_f8f6f4 v[76:79], v[0:7], v[200:207], v[76:79], v190, v190 op_sel_hi:[0,0,0]
	v_mfma_scale_f32_16x16x128_f8f6f4 v[72:75], v[8:15], v[200:207], v[72:75], v190, v190 op_sel_hi:[0,0,0]
	v_mfma_scale_f32_16x16x128_f8f6f4 v[60:63], v[0:7], v[208:215], v[60:63], v190, v190 op_sel_hi:[0,0,0]
	v_mfma_scale_f32_16x16x128_f8f6f4 v[56:59], v[8:15], v[208:215], v[56:59], v190, v190 op_sel_hi:[0,0,0]
	v_mfma_scale_f32_16x16x128_f8f6f4 v[44:47], v[0:7], v[216:223], v[44:47], v190, v190 op_sel_hi:[0,0,0]
	v_mfma_scale_f32_16x16x128_f8f6f4 v[40:43], v[8:15], v[216:223], v[40:43], v190, v190 op_sel_hi:[0,0,0]
	s_setprio 0
	s_setprio 1
	v_mfma_scale_f32_16x16x128_f8f6f4 v[84:87], v[16:23], v[192:199], v[84:87], v190, v190 op_sel_hi:[0,0,0]
	v_mfma_scale_f32_16x16x128_f8f6f4 v[80:83], v[24:31], v[192:199], v[80:83], v190, v190 op_sel_hi:[0,0,0]
	v_mfma_scale_f32_16x16x128_f8f6f4 v[68:71], v[16:23], v[200:207], v[68:71], v190, v190 op_sel_hi:[0,0,0]
	v_mfma_scale_f32_16x16x128_f8f6f4 v[64:67], v[24:31], v[200:207], v[64:67], v190, v190 op_sel_hi:[0,0,0]
	v_mfma_scale_f32_16x16x128_f8f6f4 v[52:55], v[16:23], v[208:215], v[52:55], v190, v190 op_sel_hi:[0,0,0]
	v_mfma_scale_f32_16x16x128_f8f6f4 v[48:51], v[24:31], v[208:215], v[48:51], v190, v190 op_sel_hi:[0,0,0]
	v_mfma_scale_f32_16x16x128_f8f6f4 v[36:39], v[16:23], v[216:223], v[36:39], v190, v190 op_sel_hi:[0,0,0]
	v_mfma_scale_f32_16x16x128_f8f6f4 v[32:35], v[24:31], v[216:223], v[32:35], v190, v190 op_sel_hi:[0,0,0]
	s_setprio 0
	s_barrier
	s_add_i32 s67, s67, 2
	s_add_u32 s42, s42, 0x100
	s_addc_u32 s43, s43, 0
	s_add_u32 s65, s65, 0x100
	s_addc_u32 s66, s66, 0
	s_cmp_gt_u32 s67, 13
	s_cbranch_scc0 .LBB0_4502

; #define PG8_STAGE(bufoff, gbase, voff) do { _Pragma("unroll") for (int _i = 0; _i < 2; ++_i) \
;         __builtin_amdgcn_global_load_lds((const unsigned*)((const char*)(gbase) + (voff)[_i]), (LAS unsigned*)(lds + (bufoff) + ldsw + _i * 8192), 16, 0, 0); } while (0)
; #define PG8_LDA(dst, b, h) do { _Pragma("unroll") for (int m = 0; m < 4; ++m) _Pragma("unroll") for (int k = 0; k < 2; ++k) dst[m][k] = *(const LAS bf16x8*)(lds + PG8_SA(b, h) + aoff + m * 2048 + k * 1024); } while (0)
; #define PG8_LDB(dst, b, h) do { _Pragma("unroll") for (int n = 0; n < 2; ++n) _Pragma("unroll") for (int k = 0; k < 2; ++k) dst[n][k] = *(const LAS bf16x8*)(lds + PG8_SB(b, h) + boff + n * 2048 + k * 1024); } while (0)
; #define PG8_WAIT_V(n) asm volatile("s_waitcnt vmcnt(" #n ")" ::: "memory")
; #define PG8_WAIT_L(n) asm volatile("s_waitcnt lgkmcnt(" #n ")" ::: "memory")
; #define PG8_BAR __builtin_amdgcn_s_barrier()
; #define PG8_SCHED __builtin_amdgcn_sched_barrier(0)
;     ...
;         const char* nA = has_next ? (const char*)g.A + (size_t)nxt.pm * tstep + (size_t)nxt.kt0 * kstep : cA; const char* nB = has_next ? (const char*)g.Bt + (size_t)nxt.e * g.estride + (size_t)nxt.pn * tstep + (size_t)nxt.kt0 * kstep : cB;
;         const int nt = cur.nkt;
;         for (int t = 0; t < nt; t += 2) {
;             const bool last = (t == nt - 2);
;             const char* a1 = cA + (size_t)(t + 1) * kstep;
;             const char* a2 = last ? nA : cA + (size_t)(t + 2) * kstep; const char* b2 = last ? nB : cB + (size_t)(t + 2) * kstep;
;             const char* a3 = a2 + kstep; const char* b3 = b2 + kstep;
;             PG8_LDB(B0, 0, 0); PG8_LDB(B1, 0, 1); PG8_SCHED; PG8_LDA(At, 0, 0); PG8_STAGE(PG8_SA(1, 1), a1 + hstep, voffA);
;             PG8_WAIT_V(8); PG8_WAIT_L(0); PG8_BAR; PG8_MMA(0, 0, At, B0); PG8_MMA(0, 1, At, B1); PG8_BAR; PG8_SCHED;
;             PG8_LDA(At, 0, 1); PG8_STAGE(PG8_SB(0, 0), b2, voffB); PG8_STAGE(PG8_SB(0, 1), b2 + hstep, voffB); PG8_STAGE(PG8_SA(0, 0), a2, voffA);
;             PG8_WAIT_V(8); PG8_WAIT_L(0); PG8_BAR; PG8_MMA(1, 0, At, B0); PG8_MMA(1, 1, At, B1); PG8_BAR; PG8_SCHED;
.LBB0_4737:
	s_ashr_i32 s39, s38, 31
	s_lshl_b64 s[40:41], s[38:39], 19
	s_add_u32 s40, s29, s40
	s_addc_u32 s41, s31, s41
	s_and_b64 s[4:5], s[4:5], exec
	s_cselect_b32 s37, s41, s47
	s_cselect_b32 s39, s40, s46
	s_add_u32 s4, s46, 0x40080
	v_lshl_add_u64 v[144:145], v[0:1], 0, s[26:27]
	s_addc_u32 s5, s47, 0
	s_mov_b32 s65, -2
	ds_read_b128 v[156:159], v151
	ds_read_b128 v[160:163], v151 offset:1024
	ds_read_b128 v[164:167], v151 offset:2048
	ds_read_b128 v[168:171], v151 offset:3072
	ds_read_b128 v[172:175], v152
	ds_read_b128 v[176:179], v152 offset:1024
	ds_read_b128 v[180:183], v152 offset:2048
	ds_read_b128 v[184:187], v152 offset:3072
	s_add_u32 s46, s4, 0xfffc0080
	s_addc_u32 s47, s5, -1
	s_cmp_eq_u32 s65, 12
	s_cselect_b64 vcc, -1, 0
	s_cselect_b32 s47, s37, s47
	s_cselect_b32 s46, s39, s46
	v_cndmask_b32_e32 v147, v145, v143, vcc
	v_cndmask_b32_e32 v146, v144, v142, vcc
	v_lshl_add_u64 v[220:221], s[4:5], 0, v[138:139]
	s_add_i32 m0, s43, 0xc000
	ds_read_b128 v[188:191], v153
	ds_read_b128 v[192:195], v153 offset:1024
	ds_read_b128 v[196:199], v153 offset:2048
	ds_read_b128 v[200:203], v153 offset:3072
	ds_read_b128 v[204:207], v153 offset:4096
	ds_read_b128 v[208:211], v153 offset:5120
	ds_read_b128 v[212:215], v153 offset:6144
	ds_read_b128 v[216:219], v153 offset:7168
	global_load_lds_dwordx4 v[220:221], off
	v_lshl_add_u64 v[220:221], s[4:5], 0, v[140:141]
	s_add_i32 m0, s43, 0xe000
	s_nop 0
	global_load_lds_dwordx4 v[220:221], off
	s_waitcnt vmcnt(8)
	s_waitcnt lgkmcnt(0)
	s_barrier
	s_setprio 1
	s_waitcnt lgkmcnt(0)
	v_mfma_i32_16x16x64_i8 v[124:127], v[156:159], v[188:191], 0
	v_mfma_i32_16x16x64_i8 v[120:123], v[164:167], v[188:191], 0
	v_mfma_i32_16x16x64_i8 v[116:119], v[156:159], v[196:199], 0
	v_mfma_i32_16x16x64_i8 v[112:115], v[164:167], v[196:199], 0
	v_mfma_i32_16x16x64_i8 v[108:111], v[156:159], v[204:207], 0
	v_mfma_i32_16x16x64_i8 v[104:107], v[164:167], v[204:207], 0
	v_mfma_i32_16x16x64_i8 v[100:103], v[156:159], v[212:215], 0
	v_mfma_i32_16x16x64_i8 v[96:99], v[164:167], v[212:215], 0
	v_mfma_i32_16x16x64_i8 v[124:127], v[160:163], v[192:195], v[124:127]
	v_mfma_i32_16x16x64_i8 v[120:123], v[168:171], v[192:195], v[120:123]
	v_mfma_i32_16x16x64_i8 v[116:119], v[160:163], v[200:203], v[116:119]
	v_mfma_i32_16x16x64_i8 v[112:115], v[168:171], v[200:203], v[112:115]
	v_mfma_i32_16x16x64_i8 v[108:111], v[160:163], v[208:211], v[108:111]
	v_mfma_i32_16x16x64_i8 v[104:107], v[168:171], v[208:211], v[104:107]
	v_mfma_i32_16x16x64_i8 v[100:103], v[160:163], v[216:219], v[100:103]
	v_mfma_i32_16x16x64_i8 v[96:99], v[168:171], v[216:219], v[96:99]
	s_setprio 0
	s_setprio 1
	v_mfma_i32_16x16x64_i8 v[92:95], v[172:175], v[188:191], 0
	v_mfma_i32_16x16x64_i8 v[88:91], v[180:183], v[188:191], 0
	v_mfma_i32_16x16x64_i8 v[84:87], v[172:175], v[196:199], 0
	v_mfma_i32_16x16x64_i8 v[80:83], v[180:183], v[196:199], 0
	v_mfma_i32_16x16x64_i8 v[76:79], v[172:175], v[204:207], 0
	v_mfma_i32_16x16x64_i8 v[72:75], v[180:183], v[204:207], 0
	v_mfma_i32_16x16x64_i8 v[68:71], v[172:175], v[212:215], 0
	v_mfma_i32_16x16x64_i8 v[64:67], v[180:183], v[212:215], 0
	v_mfma_i32_16x16x64_i8 v[92:95], v[176:179], v[192:195], v[92:95]
	v_mfma_i32_16x16x64_i8 v[88:91], v[184:187], v[192:195], v[88:91]
	v_mfma_i32_16x16x64_i8 v[84:87], v[176:179], v[200:203], v[84:87]
	v_mfma_i32_16x16x64_i8 v[80:83], v[184:187], v[200:203], v[80:83]
	v_mfma_i32_16x16x64_i8 v[76:79], v[176:179], v[208:211], v[76:79]
	v_mfma_i32_16x16x64_i8 v[72:75], v[184:187], v[208:211], v[72:75]
	v_mfma_i32_16x16x64_i8 v[68:71], v[176:179], v[216:219], v[68:71]
	v_mfma_i32_16x16x64_i8 v[64:67], v[184:187], v[216:219], v[64:67]
	s_setprio 0
	s_barrier
	s_add_i32 s66, s61, s34
	v_lshl_add_u64 v[220:221], v[146:147], 0, v[128:129]
	s_mov_b32 m0, s66
	ds_read_b128 v[188:191], v153 offset:16384
	ds_read_b128 v[192:195], v153 offset:17408
	ds_read_b128 v[196:199], v153 offset:18432
	ds_read_b128 v[200:203], v153 offset:19456
	ds_read_b128 v[204:207], v153 offset:20480
	ds_read_b128 v[208:211], v153 offset:21504
	ds_read_b128 v[212:215], v153 offset:22528
	ds_read_b128 v[216:219], v153 offset:23552
	global_load_lds_dwordx4 v[220:221], off
	v_lshl_add_u64 v[222:223], v[146:147], 0, v[134:135]
	s_add_i32 m0, s66, 0x2000
	v_lshl_add_u64 v[224:225], v[146:147], 0, s[12:13]
	s_add_i32 s66, s62, s34
	global_load_lds_dwordx4 v[222:223], off
	v_lshl_add_u64 v[226:227], v[224:225], 0, v[128:129]
	s_mov_b32 m0, s66
	v_lshl_add_u64 v[224:225], v[224:225], 0, v[134:135]
	global_load_lds_dwordx4 v[226:227], off
	s_add_i32 m0, s66, 0x2000
	v_lshl_add_u64 v[226:227], s[46:47], 0, v[136:137]
	global_load_lds_dwordx4 v[224:225], off
	v_lshl_add_u64 v[224:225], s[46:47], 0, v[132:133]
	s_mov_b32 m0, s43
	s_nop 0
	global_load_lds_dwordx4 v[224:225], off
	s_mov_b32 m0, s45
	s_nop 0
	global_load_lds_dwordx4 v[226:227], off
	s_waitcnt vmcnt(8)
	s_waitcnt lgkmcnt(0)
	s_barrier
; #define PG8_STAGE(bufoff, gbase, voff) do { _Pragma("unroll") for (int _i = 0; _i < 2; ++_i) \
;         __builtin_amdgcn_global_load_lds((const unsigned*)((const char*)(gbase) + (voff)[_i]), (LAS unsigned*)(lds + (bufoff) + ldsw + _i * 8192), 16, 0, 0); } while (0)
; #define PG8_LDA(dst, b, h) do { _Pragma("unroll") for (int m = 0; m < 4; ++m) _Pragma("unroll") for (int k = 0; k < 2; ++k) dst[m][k] = *(const LAS bf16x8*)(lds + PG8_SA(b, h) + aoff + m * 2048 + k * 1024); } while (0)
; #define PG8_LDB(dst, b, h) do { _Pragma("unroll") for (int n = 0; n < 2; ++n) _Pragma("unroll") for (int k = 0; k < 2; ++k) dst[n][k] = *(const LAS bf16x8*)(lds + PG8_SB(b, h) + boff + n * 2048 + k * 1024); } while (0)
; #define PG8_WAIT_V(n) asm volatile("s_waitcnt vmcnt(" #n ")" ::: "memory")
; #define PG8_WAIT_L(n) asm volatile("s_waitcnt lgkmcnt(" #n ")" ::: "memory")
; #define PG8_BAR __builtin_amdgcn_s_barrier()
; #define PG8_SCHED __builtin_amdgcn_sched_barrier(0)
;     ...
;             PG8_LDB(B0, 0, 0); PG8_LDB(B1, 0, 1); PG8_SCHED; PG8_LDA(At, 0, 0); PG8_STAGE(PG8_SA(1, 1), a1 + hstep, voffA);
;             PG8_WAIT_V(8); PG8_WAIT_L(0); PG8_BAR; PG8_MMA(0, 0, At, B0); PG8_MMA(0, 1, At, B1); PG8_BAR; PG8_SCHED;
;             PG8_LDA(At, 0, 1); PG8_STAGE(PG8_SB(0, 0), b2, voffB); PG8_STAGE(PG8_SB(0, 1), b2 + hstep, voffB); PG8_STAGE(PG8_SA(0, 0), a2, voffA);
;             PG8_WAIT_V(8); PG8_WAIT_L(0); PG8_BAR; PG8_MMA(1, 0, At, B0); PG8_MMA(1, 1, At, B1); PG8_BAR; PG8_SCHED;
;             PG8_LDB(B0, 1, 0); PG8_LDB(B1, 1, 1); PG8_SCHED; PG8_LDA(At, 1, 0); PG8_STAGE(PG8_SA(0, 1), a2 + hstep, voffA);
;             PG8_WAIT_V(8); PG8_WAIT_L(0); PG8_BAR; PG8_MMA(0, 0, At, B0); PG8_MMA(0, 1, At, B1); PG8_BAR; PG8_SCHED;
;             PG8_LDA(At, 1, 1); PG8_STAGE(PG8_SB(1, 0), b3, voffB); PG8_STAGE(PG8_SB(1, 1), b3 + hstep, voffB); PG8_STAGE(PG8_SA(1, 0), a3, voffA);
;             PG8_WAIT_V(8); PG8_WAIT_L(0); PG8_BAR; PG8_MMA(1, 0, At, B0); PG8_MMA(1, 1, At, B1); PG8_BAR; PG8_SCHED;
	s_setprio 1
	s_waitcnt lgkmcnt(0)
	v_mfma_i32_16x16x64_i8 v[60:63], v[156:159], v[188:191], 0
	v_mfma_i32_16x16x64_i8 v[56:59], v[164:167], v[188:191], 0
	v_mfma_i32_16x16x64_i8 v[52:55], v[156:159], v[196:199], 0
	v_mfma_i32_16x16x64_i8 v[48:51], v[164:167], v[196:199], 0
	v_mfma_i32_16x16x64_i8 v[44:47], v[156:159], v[204:207], 0
	v_mfma_i32_16x16x64_i8 v[40:43], v[164:167], v[204:207], 0
	v_mfma_i32_16x16x64_i8 v[36:39], v[156:159], v[212:215], 0
	v_mfma_i32_16x16x64_i8 v[32:35], v[164:167], v[212:215], 0
	v_mfma_i32_16x16x64_i8 v[60:63], v[160:163], v[192:195], v[60:63]
	v_mfma_i32_16x16x64_i8 v[56:59], v[168:171], v[192:195], v[56:59]
	v_mfma_i32_16x16x64_i8 v[52:55], v[160:163], v[200:203], v[52:55]
	v_mfma_i32_16x16x64_i8 v[48:51], v[168:171], v[200:203], v[48:51]
	v_mfma_i32_16x16x64_i8 v[44:47], v[160:163], v[208:211], v[44:47]
	v_mfma_i32_16x16x64_i8 v[40:43], v[168:171], v[208:211], v[40:43]
	v_mfma_i32_16x16x64_i8 v[36:39], v[160:163], v[216:219], v[36:39]
	v_mfma_i32_16x16x64_i8 v[32:35], v[168:171], v[216:219], v[32:35]
	s_setprio 0
	s_setprio 1
	v_mfma_i32_16x16x64_i8 v[28:31], v[172:175], v[188:191], 0
	v_mfma_i32_16x16x64_i8 v[24:27], v[180:183], v[188:191], 0
	v_mfma_i32_16x16x64_i8 v[20:23], v[172:175], v[196:199], 0
	v_mfma_i32_16x16x64_i8 v[16:19], v[180:183], v[196:199], 0
	v_mfma_i32_16x16x64_i8 v[12:15], v[172:175], v[204:207], 0
	v_mfma_i32_16x16x64_i8 v[8:11], v[180:183], v[204:207], 0
	v_mfma_i32_16x16x64_i8 v[4:7], v[172:175], v[212:215], 0
	v_mfma_i32_16x16x64_i8 v[0:3], v[180:183], v[212:215], 0
	v_mfma_i32_16x16x64_i8 v[28:31], v[176:179], v[192:195], v[28:31]
	v_mfma_i32_16x16x64_i8 v[24:27], v[184:187], v[192:195], v[24:27]
	v_mfma_i32_16x16x64_i8 v[20:23], v[176:179], v[200:203], v[20:23]
	v_mfma_i32_16x16x64_i8 v[16:19], v[184:187], v[200:203], v[16:19]
	v_mfma_i32_16x16x64_i8 v[12:15], v[176:179], v[208:211], v[12:15]
	v_mfma_i32_16x16x64_i8 v[8:11], v[184:187], v[208:211], v[8:11]
	v_mfma_i32_16x16x64_i8 v[4:7], v[176:179], v[216:219], v[4:7]
	v_mfma_i32_16x16x64_i8 v[0:3], v[184:187], v[216:219], v[0:3]
	s_setprio 0
	s_barrier
	s_add_i32 s66, 0, 0x18000
	s_add_i32 s67, 0, 0x1c000
	v_add_u32_e32 v168, s66, v149
	v_add_u32_e32 v184, s67, v149
	ds_read_b128 v[156:159], v168
	ds_read_b128 v[160:163], v168 offset:1024
	ds_read_b128 v[164:167], v168 offset:2048
	ds_read_b128 v[168:171], v168 offset:3072
	ds_read_b128 v[172:175], v184
	ds_read_b128 v[176:179], v184 offset:1024
	ds_read_b128 v[180:183], v184 offset:2048
	ds_read_b128 v[184:187], v184 offset:3072
	s_add_u32 s46, s46, 0x40000
	s_addc_u32 s47, s47, 0
	s_mov_b32 m0, s51
	v_lshl_add_u64 v[228:229], s[46:47], 0, v[132:133]
	ds_read_b128 v[188:191], v153 offset:32768
	ds_read_b128 v[192:195], v153 offset:33792
	ds_read_b128 v[196:199], v153 offset:34816
	ds_read_b128 v[200:203], v153 offset:35840
	ds_read_b128 v[204:207], v153 offset:36864
	ds_read_b128 v[208:211], v153 offset:37888
	ds_read_b128 v[212:215], v153 offset:38912
	ds_read_b128 v[216:219], v153 offset:39936
	global_load_lds_dwordx4 v[228:229], off
	v_lshl_add_u64 v[228:229], s[46:47], 0, v[136:137]
	s_mov_b32 m0, s54
	s_nop 0
	global_load_lds_dwordx4 v[228:229], off
	s_waitcnt vmcnt(8)
	s_waitcnt lgkmcnt(0)
	s_barrier
	s_setprio 1
	s_waitcnt lgkmcnt(0)
	v_mfma_i32_16x16x64_i8 v[124:127], v[156:159], v[188:191], v[124:127]
	v_mfma_i32_16x16x64_i8 v[120:123], v[164:167], v[188:191], v[120:123]
	v_mfma_i32_16x16x64_i8 v[116:119], v[156:159], v[196:199], v[116:119]
	v_mfma_i32_16x16x64_i8 v[112:115], v[164:167], v[196:199], v[112:115]
	v_mfma_i32_16x16x64_i8 v[108:111], v[156:159], v[204:207], v[108:111]
	v_mfma_i32_16x16x64_i8 v[104:107], v[164:167], v[204:207], v[104:107]
	v_mfma_i32_16x16x64_i8 v[100:103], v[156:159], v[212:215], v[100:103]
	v_mfma_i32_16x16x64_i8 v[96:99], v[164:167], v[212:215], v[96:99]
	v_mfma_i32_16x16x64_i8 v[124:127], v[160:163], v[192:195], v[124:127]
	v_mfma_i32_16x16x64_i8 v[120:123], v[168:171], v[192:195], v[120:123]
	v_mfma_i32_16x16x64_i8 v[116:119], v[160:163], v[200:203], v[116:119]
	v_mfma_i32_16x16x64_i8 v[112:115], v[168:171], v[200:203], v[112:115]
	v_mfma_i32_16x16x64_i8 v[108:111], v[160:163], v[208:211], v[108:111]
	v_mfma_i32_16x16x64_i8 v[104:107], v[168:171], v[208:211], v[104:107]
	v_mfma_i32_16x16x64_i8 v[100:103], v[160:163], v[216:219], v[100:103]
	v_mfma_i32_16x16x64_i8 v[96:99], v[168:171], v[216:219], v[96:99]
	s_setprio 0
	s_setprio 1
	v_mfma_i32_16x16x64_i8 v[92:95], v[172:175], v[188:191], v[92:95]
	v_mfma_i32_16x16x64_i8 v[88:91], v[180:183], v[188:191], v[88:91]
	v_mfma_i32_16x16x64_i8 v[84:87], v[172:175], v[196:199], v[84:87]
	v_mfma_i32_16x16x64_i8 v[80:83], v[180:183], v[196:199], v[80:83]
	v_mfma_i32_16x16x64_i8 v[76:79], v[172:175], v[204:207], v[76:79]
	v_mfma_i32_16x16x64_i8 v[72:75], v[180:183], v[204:207], v[72:75]
	v_mfma_i32_16x16x64_i8 v[68:71], v[172:175], v[212:215], v[68:71]
	v_mfma_i32_16x16x64_i8 v[64:67], v[180:183], v[212:215], v[64:67]
	v_mfma_i32_16x16x64_i8 v[92:95], v[176:179], v[192:195], v[92:95]
	v_mfma_i32_16x16x64_i8 v[88:91], v[184:187], v[192:195], v[88:91]
	v_mfma_i32_16x16x64_i8 v[84:87], v[176:179], v[200:203], v[84:87]
	v_mfma_i32_16x16x64_i8 v[80:83], v[184:187], v[200:203], v[80:83]
	v_mfma_i32_16x16x64_i8 v[76:79], v[176:179], v[208:211], v[76:79]
	v_mfma_i32_16x16x64_i8 v[72:75], v[184:187], v[208:211], v[72:75]
	v_mfma_i32_16x16x64_i8 v[68:71], v[176:179], v[216:219], v[68:71]
	v_mfma_i32_16x16x64_i8 v[64:67], v[184:187], v[216:219], v[64:67]
	s_setprio 0
	s_barrier
; #define PG8_STAGE(bufoff, gbase, voff) do { _Pragma("unroll") for (int _i = 0; _i < 2; ++_i) \
;         __builtin_amdgcn_global_load_lds((const unsigned*)((const char*)(gbase) + (voff)[_i]), (LAS unsigned*)(lds + (bufoff) + ldsw + _i * 8192), 16, 0, 0); } while (0)
; #define PG8_LDA(dst, b, h) do { _Pragma("unroll") for (int m = 0; m < 4; ++m) _Pragma("unroll") for (int k = 0; k < 2; ++k) dst[m][k] = *(const LAS bf16x8*)(lds + PG8_SA(b, h) + aoff + m * 2048 + k * 1024); } while (0)
; #define PG8_LDB(dst, b, h) do { _Pragma("unroll") for (int n = 0; n < 2; ++n) _Pragma("unroll") for (int k = 0; k < 2; ++k) dst[n][k] = *(const LAS bf16x8*)(lds + PG8_SB(b, h) + boff + n * 2048 + k * 1024); } while (0)
; #define PG8_WAIT_V(n) asm volatile("s_waitcnt vmcnt(" #n ")" ::: "memory")
; #define PG8_WAIT_L(n) asm volatile("s_waitcnt lgkmcnt(" #n ")" ::: "memory")
; #define PG8_BAR __builtin_amdgcn_s_barrier()
; #define PG8_SCHED __builtin_amdgcn_sched_barrier(0)
;     ...
;             PG8_LDB(B0, 1, 0); PG8_LDB(B1, 1, 1); PG8_SCHED; PG8_LDA(At, 1, 0); PG8_STAGE(PG8_SA(0, 1), a2 + hstep, voffA);
;             PG8_WAIT_V(8); PG8_WAIT_L(0); PG8_BAR; PG8_MMA(0, 0, At, B0); PG8_MMA(0, 1, At, B1); PG8_BAR; PG8_SCHED;
;             PG8_LDA(At, 1, 1); PG8_STAGE(PG8_SB(1, 0), b3, voffB); PG8_STAGE(PG8_SB(1, 1), b3 + hstep, voffB); PG8_STAGE(PG8_SA(1, 0), a3, voffA);
;             PG8_WAIT_V(8); PG8_WAIT_L(0); PG8_BAR; PG8_MMA(1, 0, At, B0); PG8_MMA(1, 1, At, B1); PG8_BAR; PG8_SCHED;
;         }
	s_add_i32 s46, s66, s34
	v_lshl_add_u64 v[220:221], v[220:221], 0, s[18:19]
	s_mov_b32 m0, s46
	ds_read_b128 v[188:191], v153 offset:49152
	ds_read_b128 v[192:195], v153 offset:50176
	ds_read_b128 v[196:199], v153 offset:51200
	ds_read_b128 v[200:203], v153 offset:52224
	ds_read_b128 v[204:207], v153 offset:53248
	ds_read_b128 v[208:211], v153 offset:54272
	ds_read_b128 v[212:215], v153 offset:55296
	ds_read_b128 v[216:219], v153 offset:56320
	global_load_lds_dwordx4 v[220:221], off
	v_lshl_add_u64 v[220:221], v[222:223], 0, s[18:19]
	s_add_i32 m0, s46, 0x2000
	v_lshl_add_u64 v[146:147], v[146:147], 0, s[20:21]
	s_add_i32 s46, s67, s34
	global_load_lds_dwordx4 v[220:221], off
	v_lshl_add_u64 v[220:221], v[146:147], 0, v[128:129]
	s_mov_b32 m0, s46
	v_lshl_add_u64 v[146:147], v[146:147], 0, v[134:135]
	global_load_lds_dwordx4 v[220:221], off
	s_add_i32 m0, s46, 0x2000
	s_nop 0
	global_load_lds_dwordx4 v[146:147], off
	v_lshl_add_u64 v[146:147], v[224:225], 0, s[18:19]
	s_mov_b32 m0, s58
	s_nop 0
	global_load_lds_dwordx4 v[146:147], off
	v_lshl_add_u64 v[146:147], v[226:227], 0, s[18:19]
	s_mov_b32 m0, s59
	s_nop 0
	global_load_lds_dwordx4 v[146:147], off
	s_waitcnt vmcnt(8)
	s_waitcnt lgkmcnt(0)
	s_barrier
	s_setprio 1
	s_waitcnt lgkmcnt(0)
	v_mfma_i32_16x16x64_i8 v[60:63], v[156:159], v[188:191], v[60:63]
	v_mfma_i32_16x16x64_i8 v[56:59], v[164:167], v[188:191], v[56:59]
	v_mfma_i32_16x16x64_i8 v[52:55], v[156:159], v[196:199], v[52:55]
	v_mfma_i32_16x16x64_i8 v[48:51], v[164:167], v[196:199], v[48:51]
	v_mfma_i32_16x16x64_i8 v[44:47], v[156:159], v[204:207], v[44:47]
	v_mfma_i32_16x16x64_i8 v[40:43], v[164:167], v[204:207], v[40:43]
	v_mfma_i32_16x16x64_i8 v[36:39], v[156:159], v[212:215], v[36:39]
	v_mfma_i32_16x16x64_i8 v[32:35], v[164:167], v[212:215], v[32:35]
	v_mfma_i32_16x16x64_i8 v[60:63], v[160:163], v[192:195], v[60:63]
	v_mfma_i32_16x16x64_i8 v[56:59], v[168:171], v[192:195], v[56:59]
	v_mfma_i32_16x16x64_i8 v[52:55], v[160:163], v[200:203], v[52:55]
	v_mfma_i32_16x16x64_i8 v[48:51], v[168:171], v[200:203], v[48:51]
	v_mfma_i32_16x16x64_i8 v[44:47], v[160:163], v[208:211], v[44:47]
	v_mfma_i32_16x16x64_i8 v[40:43], v[168:171], v[208:211], v[40:43]
	v_mfma_i32_16x16x64_i8 v[36:39], v[160:163], v[216:219], v[36:39]
	v_mfma_i32_16x16x64_i8 v[32:35], v[168:171], v[216:219], v[32:35]
	s_setprio 0
	s_setprio 1
	v_mfma_i32_16x16x64_i8 v[28:31], v[172:175], v[188:191], v[28:31]
	v_mfma_i32_16x16x64_i8 v[24:27], v[180:183], v[188:191], v[24:27]
	v_mfma_i32_16x16x64_i8 v[20:23], v[172:175], v[196:199], v[20:23]
	v_mfma_i32_16x16x64_i8 v[16:19], v[180:183], v[196:199], v[16:19]
	v_mfma_i32_16x16x64_i8 v[12:15], v[172:175], v[204:207], v[12:15]
	v_mfma_i32_16x16x64_i8 v[8:11], v[180:183], v[204:207], v[8:11]
	v_mfma_i32_16x16x64_i8 v[4:7], v[172:175], v[212:215], v[4:7]
	v_mfma_i32_16x16x64_i8 v[0:3], v[180:183], v[212:215], v[0:3]
	v_mfma_i32_16x16x64_i8 v[28:31], v[176:179], v[192:195], v[28:31]
	v_mfma_i32_16x16x64_i8 v[24:27], v[184:187], v[192:195], v[24:27]
	v_mfma_i32_16x16x64_i8 v[20:23], v[176:179], v[200:203], v[20:23]
	v_mfma_i32_16x16x64_i8 v[16:19], v[184:187], v[200:203], v[16:19]
	v_mfma_i32_16x16x64_i8 v[12:15], v[176:179], v[208:211], v[12:15]
	v_mfma_i32_16x16x64_i8 v[8:11], v[184:187], v[208:211], v[8:11]
	v_mfma_i32_16x16x64_i8 v[4:7], v[176:179], v[216:219], v[4:7]
	v_mfma_i32_16x16x64_i8 v[0:3], v[184:187], v[216:219], v[0:3]
	s_setprio 0
	s_barrier
	s_add_i32 s65, s65, 2
	s_add_u32 s4, s4, 0x100
	s_addc_u32 s5, s5, 0
	s_cmp_gt_u32 s65, 13
	v_lshl_add_u64 v[144:145], v[144:145], 0, s[26:27]
	s_cbranch_scc0 .LBB0_4738

; #define PG8_STAGE(bufoff, gbase, voff) do { _Pragma("unroll") for (int _i = 0; _i < 2; ++_i) \
;         __builtin_amdgcn_global_load_lds((const unsigned*)((const char*)(gbase) + (voff)[_i]), (LAS unsigned*)(lds + (bufoff) + ldsw + _i * 8192), 16, 0, 0); } while (0)
; #define PG8_LDA(dst, b, h) do { _Pragma("unroll") for (int m = 0; m < 4; ++m) _Pragma("unroll") for (int k = 0; k < 2; ++k) dst[m][k] = *(const LAS bf16x8*)(lds + PG8_SA(b, h) + aoff + m * 2048 + k * 1024); } while (0)
; #define PG8_LDB(dst, b, h) do { _Pragma("unroll") for (int n = 0; n < 2; ++n) _Pragma("unroll") for (int k = 0; k < 2; ++k) dst[n][k] = *(const LAS bf16x8*)(lds + PG8_SB(b, h) + boff + n * 2048 + k * 1024); } while (0)
; #define PG8_WAIT_V(n) asm volatile("s_waitcnt vmcnt(" #n ")" ::: "memory")
; #define PG8_WAIT_L(n) asm volatile("s_waitcnt lgkmcnt(" #n ")" ::: "memory")
; #define PG8_BAR __builtin_amdgcn_s_barrier()
; #define PG8_SCHED __builtin_amdgcn_sched_barrier(0)
;     ...
;             PG8_LDB(B0, 0, 0); PG8_LDB(B1, 0, 1); PG8_SCHED; PG8_LDA(At, 0, 0); PG8_STAGE(PG8_SA(1, 1), a1 + hstep, voffA);
;             PG8_WAIT_V(8); PG8_WAIT_L(0); PG8_BAR; PG8_MMA(0, 0, At, B0); PG8_MMA(0, 1, At, B1); PG8_BAR; PG8_SCHED;
;             PG8_LDA(At, 0, 1); PG8_STAGE(PG8_SB(0, 0), b2, voffB); PG8_STAGE(PG8_SB(0, 1), b2 + hstep, voffB); PG8_STAGE(PG8_SA(0, 0), a2, voffA);
;             PG8_WAIT_V(8); PG8_WAIT_L(0); PG8_BAR; PG8_MMA(1, 0, At, B0); PG8_MMA(1, 1, At, B1); PG8_BAR; PG8_SCHED;
;     ...
; #pragma unroll
;         for (int a = 0; a < 2; ++a)
; #pragma unroll
;             for (int b = 0; b < 2; ++b)
; #pragma unroll
;                 for (int m = 0; m < 4; ++m)
; #pragma unroll
;                     for (int n = 0; n < 2; ++n) acc[a][b][m][n] = (f32x4){0.f, 0.f, 0.f, 0.f};
.LBB0_4812:
	v_lshl_add_u64 v[178:179], v[0:1], 0, s[26:27]
	s_mov_b32 s66, -2
	ds_read_b128 v[24:27], v168
	ds_read_b128 v[28:31], v168 offset:1024
	ds_read_b128 v[16:19], v168 offset:2048
	ds_read_b128 v[20:23], v168 offset:3072
	ds_read_b128 v[8:11], v193
	ds_read_b128 v[12:15], v193 offset:1024
	ds_read_b128 v[0:3], v193 offset:2048
	ds_read_b128 v[4:7], v193 offset:3072
	s_add_u32 s36, s30, 0x100
	s_addc_u32 s37, s31, 0
	s_cmp_eq_u32 s66, 52
	s_cselect_b64 vcc, -1, 0
	s_cselect_b32 s39, s5, s37
	s_cselect_b32 s38, s4, s36
	v_cndmask_b32_e32 v181, v179, v177, vcc
	v_cndmask_b32_e32 v180, v178, v176, vcc
	v_lshl_add_u64 v[222:223], s[30:31], 0, v[170:171]
	s_add_i32 m0, s44, 0xc000
	ds_read_b128 v[182:185], v194
	ds_read_b128 v[186:189], v194 offset:1024
	ds_read_b128 v[198:201], v194 offset:2048
	ds_read_b128 v[202:205], v194 offset:3072
	ds_read_b128 v[206:209], v194 offset:4096
	ds_read_b128 v[210:213], v194 offset:5120
	ds_read_b128 v[214:217], v194 offset:6144
	ds_read_b128 v[218:221], v194 offset:7168
	global_load_lds_dwordx4 v[222:223], off
	v_lshl_add_u64 v[222:223], s[30:31], 0, v[172:173]
	s_add_i32 m0, s44, 0xe000
	s_nop 0
	global_load_lds_dwordx4 v[222:223], off
	s_waitcnt vmcnt(8)
	s_waitcnt lgkmcnt(0)
	s_barrier
	s_setprio 1
	s_waitcnt lgkmcnt(0)
	v_mfma_scale_f32_16x16x128_f8f6f4 v[156:159], v[24:31], v[182:189], 0, v195, v195 op_sel_hi:[0,0,0]
	v_mfma_scale_f32_16x16x128_f8f6f4 v[152:155], v[16:23], v[182:189], 0, v195, v195 op_sel_hi:[0,0,0]
	v_mfma_scale_f32_16x16x128_f8f6f4 v[140:143], v[24:31], v[198:205], 0, v195, v195 op_sel_hi:[0,0,0]
	v_mfma_scale_f32_16x16x128_f8f6f4 v[136:139], v[16:23], v[198:205], 0, v195, v195 op_sel_hi:[0,0,0]
	v_mfma_scale_f32_16x16x128_f8f6f4 v[124:127], v[24:31], v[206:213], 0, v195, v195 op_sel_hi:[0,0,0]
	v_mfma_scale_f32_16x16x128_f8f6f4 v[120:123], v[16:23], v[206:213], 0, v195, v195 op_sel_hi:[0,0,0]
	v_mfma_scale_f32_16x16x128_f8f6f4 v[108:111], v[24:31], v[214:221], 0, v195, v195 op_sel_hi:[0,0,0]
	v_mfma_scale_f32_16x16x128_f8f6f4 v[104:107], v[16:23], v[214:221], 0, v195, v195 op_sel_hi:[0,0,0]
	s_setprio 0
	s_setprio 1
	v_mfma_scale_f32_16x16x128_f8f6f4 v[148:151], v[8:15], v[182:189], 0, v195, v195 op_sel_hi:[0,0,0]
	v_mfma_scale_f32_16x16x128_f8f6f4 v[144:147], v[0:7], v[182:189], 0, v195, v195 op_sel_hi:[0,0,0]
	v_mfma_scale_f32_16x16x128_f8f6f4 v[132:135], v[8:15], v[198:205], 0, v195, v195 op_sel_hi:[0,0,0]
	v_mfma_scale_f32_16x16x128_f8f6f4 v[128:131], v[0:7], v[198:205], 0, v195, v195 op_sel_hi:[0,0,0]
	v_mfma_scale_f32_16x16x128_f8f6f4 v[116:119], v[8:15], v[206:213], 0, v195, v195 op_sel_hi:[0,0,0]
	v_mfma_scale_f32_16x16x128_f8f6f4 v[112:115], v[0:7], v[206:213], 0, v195, v195 op_sel_hi:[0,0,0]
	v_mfma_scale_f32_16x16x128_f8f6f4 v[100:103], v[8:15], v[214:221], 0, v195, v195 op_sel_hi:[0,0,0]
	v_mfma_scale_f32_16x16x128_f8f6f4 v[96:99], v[0:7], v[214:221], 0, v195, v195 op_sel_hi:[0,0,0]
	s_setprio 0
	s_barrier
	s_add_i32 s30, s54, s42
	v_lshl_add_u64 v[182:183], v[180:181], 0, v[160:161]
	s_mov_b32 m0, s30
	ds_read_b128 v[198:201], v194 offset:16384
	ds_read_b128 v[202:205], v194 offset:17408
	ds_read_b128 v[206:209], v194 offset:18432
	ds_read_b128 v[210:213], v194 offset:19456
	ds_read_b128 v[214:217], v194 offset:20480
	ds_read_b128 v[218:221], v194 offset:21504
	ds_read_b128 v[222:225], v194 offset:22528
	ds_read_b128 v[226:229], v194 offset:23552
	global_load_lds_dwordx4 v[182:183], off
	v_lshl_add_u64 v[184:185], v[180:181], 0, v[166:167]
	s_add_i32 m0, s30, 0x2000
	v_lshl_add_u64 v[186:187], v[180:181], 0, s[12:13]
	s_add_i32 s30, s55, s42
	global_load_lds_dwordx4 v[184:185], off
	v_lshl_add_u64 v[188:189], v[186:187], 0, v[160:161]
	s_mov_b32 m0, s30
	v_lshl_add_u64 v[186:187], v[186:187], 0, v[166:167]
	global_load_lds_dwordx4 v[188:189], off
	s_add_i32 m0, s30, 0x2000
	v_lshl_add_u64 v[188:189], s[38:39], 0, v[164:165]
	global_load_lds_dwordx4 v[186:187], off
	v_lshl_add_u64 v[186:187], s[38:39], 0, v[162:163]
	s_mov_b32 m0, s44
	s_nop 0
	global_load_lds_dwordx4 v[186:187], off
	s_mov_b32 m0, s45
	s_nop 0
	global_load_lds_dwordx4 v[188:189], off
	s_waitcnt vmcnt(8)
	s_waitcnt lgkmcnt(0)
	s_barrier
	s_setprio 1
	s_waitcnt lgkmcnt(0)
	v_mfma_scale_f32_16x16x128_f8f6f4 v[92:95], v[24:31], v[198:205], 0, v195, v195 op_sel_hi:[0,0,0]
	v_mfma_scale_f32_16x16x128_f8f6f4 v[88:91], v[16:23], v[198:205], 0, v195, v195 op_sel_hi:[0,0,0]
	v_mfma_scale_f32_16x16x128_f8f6f4 v[76:79], v[24:31], v[206:213], 0, v195, v195 op_sel_hi:[0,0,0]
	v_mfma_scale_f32_16x16x128_f8f6f4 v[72:75], v[16:23], v[206:213], 0, v195, v195 op_sel_hi:[0,0,0]
	v_mfma_scale_f32_16x16x128_f8f6f4 v[60:63], v[24:31], v[214:221], 0, v195, v195 op_sel_hi:[0,0,0]
	v_mfma_scale_f32_16x16x128_f8f6f4 v[56:59], v[16:23], v[214:221], 0, v195, v195 op_sel_hi:[0,0,0]
	v_mfma_scale_f32_16x16x128_f8f6f4 v[44:47], v[24:31], v[222:229], 0, v195, v195 op_sel_hi:[0,0,0]
	v_mfma_scale_f32_16x16x128_f8f6f4 v[40:43], v[16:23], v[222:229], 0, v195, v195 op_sel_hi:[0,0,0]
	s_setprio 0
	s_setprio 1
	v_mfma_scale_f32_16x16x128_f8f6f4 v[84:87], v[8:15], v[198:205], 0, v195, v195 op_sel_hi:[0,0,0]
	v_mfma_scale_f32_16x16x128_f8f6f4 v[80:83], v[0:7], v[198:205], 0, v195, v195 op_sel_hi:[0,0,0]
	v_mfma_scale_f32_16x16x128_f8f6f4 v[68:71], v[8:15], v[206:213], 0, v195, v195 op_sel_hi:[0,0,0]
	v_mfma_scale_f32_16x16x128_f8f6f4 v[64:67], v[0:7], v[206:213], 0, v195, v195 op_sel_hi:[0,0,0]
	v_mfma_scale_f32_16x16x128_f8f6f4 v[52:55], v[8:15], v[214:221], 0, v195, v195 op_sel_hi:[0,0,0]
	v_mfma_scale_f32_16x16x128_f8f6f4 v[48:51], v[0:7], v[214:221], 0, v195, v195 op_sel_hi:[0,0,0]
	v_mfma_scale_f32_16x16x128_f8f6f4 v[36:39], v[8:15], v[222:229], 0, v195, v195 op_sel_hi:[0,0,0]
	v_mfma_scale_f32_16x16x128_f8f6f4 v[32:35], v[0:7], v[222:229], 0, v195, v195 op_sel_hi:[0,0,0]
	s_setprio 0
	s_barrier
; #define PG8_STAGE(bufoff, gbase, voff) do { _Pragma("unroll") for (int _i = 0; _i < 2; ++_i) \
;         __builtin_amdgcn_global_load_lds((const unsigned*)((const char*)(gbase) + (voff)[_i]), (LAS unsigned*)(lds + (bufoff) + ldsw + _i * 8192), 16, 0, 0); } while (0)
; #define PG8_LDA(dst, b, h) do { _Pragma("unroll") for (int m = 0; m < 4; ++m) _Pragma("unroll") for (int k = 0; k < 2; ++k) dst[m][k] = *(const LAS bf16x8*)(lds + PG8_SA(b, h) + aoff + m * 2048 + k * 1024); } while (0)
; #define PG8_LDB(dst, b, h) do { _Pragma("unroll") for (int n = 0; n < 2; ++n) _Pragma("unroll") for (int k = 0; k < 2; ++k) dst[n][k] = *(const LAS bf16x8*)(lds + PG8_SB(b, h) + boff + n * 2048 + k * 1024); } while (0)
; #define PG8_WAIT_V(n) asm volatile("s_waitcnt vmcnt(" #n ")" ::: "memory")
; #define PG8_WAIT_L(n) asm volatile("s_waitcnt lgkmcnt(" #n ")" ::: "memory")
; #define PG8_BAR __builtin_amdgcn_s_barrier()
; #define PG8_SCHED __builtin_amdgcn_sched_barrier(0)
;     ...
;             PG8_LDB(B0, 1, 0); PG8_LDB(B1, 1, 1); PG8_SCHED; PG8_LDA(At, 1, 0); PG8_STAGE(PG8_SA(0, 1), a2 + hstep, voffA);
;             PG8_WAIT_V(8); PG8_WAIT_L(0); PG8_BAR; PG8_MMA(0, 0, At, B0); PG8_MMA(0, 1, At, B1); PG8_BAR; PG8_SCHED;
;             PG8_LDA(At, 1, 1); PG8_STAGE(PG8_SB(1, 0), b3, voffB); PG8_STAGE(PG8_SB(1, 1), b3 + hstep, voffB); PG8_STAGE(PG8_SA(1, 0), a3, voffA);
;             PG8_WAIT_V(8); PG8_WAIT_L(0); PG8_BAR; PG8_MMA(1, 0, At, B0); PG8_MMA(1, 1, At, B1); PG8_BAR; PG8_SCHED;
;         }
	s_add_i32 s67, 0, 0x18000
	s_add_i32 s68, 0, 0x1c000
	v_add_u32_e32 v12, s67, v191
	v_add_u32_e32 v28, s68, v191
	ds_read_b128 v[0:3], v12
	ds_read_b128 v[4:7], v12 offset:1024
	ds_read_b128 v[8:11], v12 offset:2048
	ds_read_b128 v[12:15], v12 offset:3072
	ds_read_b128 v[16:19], v28
	ds_read_b128 v[20:23], v28 offset:1024
	ds_read_b128 v[24:27], v28 offset:2048
	ds_read_b128 v[28:31], v28 offset:3072
	s_add_u32 s30, s38, 0xe0000
	s_addc_u32 s31, s39, 0
	s_mov_b32 m0, s46
	v_lshl_add_u64 v[230:231], s[30:31], 0, v[162:163]
	ds_read_b128 v[198:201], v194 offset:32768
	ds_read_b128 v[202:205], v194 offset:33792
	ds_read_b128 v[206:209], v194 offset:34816
	ds_read_b128 v[210:213], v194 offset:35840
	ds_read_b128 v[214:217], v194 offset:36864
	ds_read_b128 v[218:221], v194 offset:37888
	ds_read_b128 v[222:225], v194 offset:38912
	ds_read_b128 v[226:229], v194 offset:39936
	global_load_lds_dwordx4 v[230:231], off
	v_lshl_add_u64 v[230:231], s[30:31], 0, v[164:165]
	s_mov_b32 m0, s47
	s_nop 0
	global_load_lds_dwordx4 v[230:231], off
	s_waitcnt vmcnt(8)
	s_waitcnt lgkmcnt(0)
	s_barrier
	s_setprio 1
	s_waitcnt lgkmcnt(0)
	v_mfma_scale_f32_16x16x128_f8f6f4 v[156:159], v[0:7], v[198:205], v[156:159], v195, v195 op_sel_hi:[0,0,0]
	v_mfma_scale_f32_16x16x128_f8f6f4 v[152:155], v[8:15], v[198:205], v[152:155], v195, v195 op_sel_hi:[0,0,0]
	v_mfma_scale_f32_16x16x128_f8f6f4 v[140:143], v[0:7], v[206:213], v[140:143], v195, v195 op_sel_hi:[0,0,0]
	v_mfma_scale_f32_16x16x128_f8f6f4 v[136:139], v[8:15], v[206:213], v[136:139], v195, v195 op_sel_hi:[0,0,0]
	v_mfma_scale_f32_16x16x128_f8f6f4 v[124:127], v[0:7], v[214:221], v[124:127], v195, v195 op_sel_hi:[0,0,0]
	v_mfma_scale_f32_16x16x128_f8f6f4 v[120:123], v[8:15], v[214:221], v[120:123], v195, v195 op_sel_hi:[0,0,0]
	v_mfma_scale_f32_16x16x128_f8f6f4 v[108:111], v[0:7], v[222:229], v[108:111], v195, v195 op_sel_hi:[0,0,0]
	v_mfma_scale_f32_16x16x128_f8f6f4 v[104:107], v[8:15], v[222:229], v[104:107], v195, v195 op_sel_hi:[0,0,0]
	s_setprio 0
	s_setprio 1
	v_mfma_scale_f32_16x16x128_f8f6f4 v[148:151], v[16:23], v[198:205], v[148:151], v195, v195 op_sel_hi:[0,0,0]
	v_mfma_scale_f32_16x16x128_f8f6f4 v[144:147], v[24:31], v[198:205], v[144:147], v195, v195 op_sel_hi:[0,0,0]
	v_mfma_scale_f32_16x16x128_f8f6f4 v[132:135], v[16:23], v[206:213], v[132:135], v195, v195 op_sel_hi:[0,0,0]
	v_mfma_scale_f32_16x16x128_f8f6f4 v[128:131], v[24:31], v[206:213], v[128:131], v195, v195 op_sel_hi:[0,0,0]
	v_mfma_scale_f32_16x16x128_f8f6f4 v[116:119], v[16:23], v[214:221], v[116:119], v195, v195 op_sel_hi:[0,0,0]
	v_mfma_scale_f32_16x16x128_f8f6f4 v[112:115], v[24:31], v[214:221], v[112:115], v195, v195 op_sel_hi:[0,0,0]
	v_mfma_scale_f32_16x16x128_f8f6f4 v[100:103], v[16:23], v[222:229], v[100:103], v195, v195 op_sel_hi:[0,0,0]
	v_mfma_scale_f32_16x16x128_f8f6f4 v[96:99], v[24:31], v[222:229], v[96:99], v195, v195 op_sel_hi:[0,0,0]
	s_setprio 0
	s_barrier
	s_add_i32 s30, s67, s42
	v_lshl_add_u64 v[182:183], v[182:183], 0, s[18:19]
	s_mov_b32 m0, s30
	ds_read_b128 v[198:201], v194 offset:49152
	ds_read_b128 v[202:205], v194 offset:50176
	ds_read_b128 v[206:209], v194 offset:51200
	ds_read_b128 v[210:213], v194 offset:52224
	ds_read_b128 v[214:217], v194 offset:53248
	ds_read_b128 v[218:221], v194 offset:54272
	ds_read_b128 v[222:225], v194 offset:55296
	ds_read_b128 v[226:229], v194 offset:56320
	global_load_lds_dwordx4 v[182:183], off
	v_lshl_add_u64 v[182:183], v[184:185], 0, s[18:19]
	s_add_i32 m0, s30, 0x2000
	v_lshl_add_u64 v[180:181], v[180:181], 0, s[20:21]
	s_add_i32 s30, s68, s42
	global_load_lds_dwordx4 v[182:183], off
	v_lshl_add_u64 v[182:183], v[180:181], 0, v[160:161]
	s_mov_b32 m0, s30
	v_lshl_add_u64 v[180:181], v[180:181], 0, v[166:167]
	global_load_lds_dwordx4 v[182:183], off
	s_add_i32 m0, s30, 0x2000
	s_nop 0
	global_load_lds_dwordx4 v[180:181], off
	v_lshl_add_u64 v[180:181], v[186:187], 0, s[18:19]
	s_mov_b32 m0, s48
	s_nop 0
	global_load_lds_dwordx4 v[180:181], off
	v_lshl_add_u64 v[180:181], v[188:189], 0, s[18:19]
	s_mov_b32 m0, s49
	s_nop 0
	global_load_lds_dwordx4 v[180:181], off
	s_waitcnt vmcnt(8)
	s_waitcnt lgkmcnt(0)
	s_barrier
	s_setprio 1
	s_waitcnt lgkmcnt(0)
	v_mfma_scale_f32_16x16x128_f8f6f4 v[92:95], v[0:7], v[198:205], v[92:95], v195, v195 op_sel_hi:[0,0,0]
	v_mfma_scale_f32_16x16x128_f8f6f4 v[88:91], v[8:15], v[198:205], v[88:91], v195, v195 op_sel_hi:[0,0,0]
	v_mfma_scale_f32_16x16x128_f8f6f4 v[76:79], v[0:7], v[206:213], v[76:79], v195, v195 op_sel_hi:[0,0,0]
	v_mfma_scale_f32_16x16x128_f8f6f4 v[72:75], v[8:15], v[206:213], v[72:75], v195, v195 op_sel_hi:[0,0,0]
	v_mfma_scale_f32_16x16x128_f8f6f4 v[60:63], v[0:7], v[214:221], v[60:63], v195, v195 op_sel_hi:[0,0,0]
	v_mfma_scale_f32_16x16x128_f8f6f4 v[56:59], v[8:15], v[214:221], v[56:59], v195, v195 op_sel_hi:[0,0,0]
	v_mfma_scale_f32_16x16x128_f8f6f4 v[44:47], v[0:7], v[222:229], v[44:47], v195, v195 op_sel_hi:[0,0,0]
	v_mfma_scale_f32_16x16x128_f8f6f4 v[40:43], v[8:15], v[222:229], v[40:43], v195, v195 op_sel_hi:[0,0,0]
	s_setprio 0
	s_setprio 1
	v_mfma_scale_f32_16x16x128_f8f6f4 v[84:87], v[16:23], v[198:205], v[84:87], v195, v195 op_sel_hi:[0,0,0]
	v_mfma_scale_f32_16x16x128_f8f6f4 v[80:83], v[24:31], v[198:205], v[80:83], v195, v195 op_sel_hi:[0,0,0]
	v_mfma_scale_f32_16x16x128_f8f6f4 v[68:71], v[16:23], v[206:213], v[68:71], v195, v195 op_sel_hi:[0,0,0]
	v_mfma_scale_f32_16x16x128_f8f6f4 v[64:67], v[24:31], v[206:213], v[64:67], v195, v195 op_sel_hi:[0,0,0]
	v_mfma_scale_f32_16x16x128_f8f6f4 v[52:55], v[16:23], v[214:221], v[52:55], v195, v195 op_sel_hi:[0,0,0]
	v_mfma_scale_f32_16x16x128_f8f6f4 v[48:51], v[24:31], v[214:221], v[48:51], v195, v195 op_sel_hi:[0,0,0]
	v_mfma_scale_f32_16x16x128_f8f6f4 v[36:39], v[16:23], v[222:229], v[36:39], v195, v195 op_sel_hi:[0,0,0]
	v_mfma_scale_f32_16x16x128_f8f6f4 v[32:35], v[24:31], v[222:229], v[32:35], v195, v195 op_sel_hi:[0,0,0]
	s_setprio 0
	s_barrier
	s_add_i32 s66, s66, 2
	v_lshl_add_u64 v[178:179], v[178:179], 0, s[26:27]
	s_cmp_gt_u32 s66, 53
	s_mov_b64 s[30:31], s[36:37]
	s_cbranch_scc0 .LBB0_4813
